# snake MFMA order in big GEMM loops: consecutive MFMAs share accumulator (chain) or one A/B operand register
# speedup vs baseline: 1.0664x; 1.0055x over previous
; #define PG8_STAGE(bufoff, gbase, voff) do { _Pragma("unroll") for (int _i = 0; _i < 2; ++_i) \
;         __builtin_amdgcn_global_load_lds((const unsigned*)((const char*)(gbase) + (voff)[_i]), (PG8_LAS unsigned*)(lds + (bufoff) + ldsw + _i * 8192), 16, 0, 0); } while (0)
; #define PG8_LDA(dst, b, h) do { _Pragma("unroll") for (int m = 0; m < 4; ++m) _Pragma("unroll") for (int k = 0; k < 2; ++k) dst[m][k] = *(const PG8_LAS bf16x8*)(lds + PG8_SA(b, h) + aoff + m * 2048 + k * 1024); } while (0)
; #define PG8_LDB(dst, b, h) do { _Pragma("unroll") for (int n = 0; n < 2; ++n) _Pragma("unroll") for (int k = 0; k < 2; ++k) dst[n][k] = *(const PG8_LAS bf16x8*)(lds + PG8_SB(b, h) + boff + n * 2048 + k * 1024); } while (0)
; #define PG8_MMA(ai, bj, At, Bt) do { __builtin_amdgcn_s_setprio(1); _Pragma("unroll") for (int m = 0; m < 4; ++m) _Pragma("unroll") for (int n = 0; n < 2; ++n) _Pragma("unroll") for (int k = 0; k < 2; ++k) \
;         acc[ai][bj][m][n] = __builtin_amdgcn_mfma_f32_16x16x32_bf16(Bt[n][k], At[m][k], acc[ai][bj][m][n], 0, 0, 0); __builtin_amdgcn_s_setprio(0); } while (0)
; #define PG8_WAIT_V(n) asm volatile("s_waitcnt vmcnt(" #n ")" ::: "memory")
; #define PG8_WAIT_L(n) asm volatile("s_waitcnt lgkmcnt(" #n ")" ::: "memory")
; #define PG8_BAR __builtin_amdgcn_s_barrier()
; #define PG8_SCHED __builtin_amdgcn_sched_barrier(0)
; template <class Epi, class Sched, bool ALIGN_EPI>
; __device__ __forceinline__ void gemm_phase(PG8_LAS unsigned char* lds, const Gemm g, const Sched& S, const Epi& E) {
;     ...
;             PG8_LDB(B0, 0, 0); PG8_LDB(B1, 0, 1); PG8_SCHED; PG8_LDA(At, 0, 0); PG8_STAGE(PG8_SA(1, 1), a1 + hstepA, voffA);
;             PG8_WAIT_V(8); PG8_WAIT_L(0); PG8_BAR; PG8_MMA(0, 0, At, B0); PG8_MMA(0, 1, At, B1); PG8_BAR; PG8_SCHED;
;             PG8_LDA(At, 0, 1); PG8_STAGE(PG8_SB(0, 0), b2, voffB); PG8_STAGE(PG8_SB(0, 1), b2 + hstepB, voffB); PG8_STAGE(PG8_SA(0, 0), a2, voffA);
;             PG8_WAIT_V(8); PG8_WAIT_L(0); PG8_BAR; PG8_MMA(1, 0, At, B0); PG8_MMA(1, 1, At, B1); PG8_BAR; PG8_SCHED;
.LBB0_403:
	ds_read_b128 v[152:155], v166
	ds_read_b128 v[172:175], v166 offset:1024
	ds_read_b128 v[176:179], v166 offset:2048
	ds_read_b128 v[180:183], v166 offset:3072
	ds_read_b128 v[184:187], v167
	ds_read_b128 v[188:191], v167 offset:1024
	ds_read_b128 v[192:195], v167 offset:2048
	ds_read_b128 v[196:199], v167 offset:3072
	s_add_u32 s23, s24, 0xfff80080
	s_addc_u32 s26, s25, -1
	s_cmp_eq_u32 s17, 28
	s_cselect_b32 s29, s19, s26
	s_cselect_b32 s28, s18, s23
	s_cselect_b32 s27, s21, s15
	s_cselect_b32 s26, s20, s5
	v_lshl_add_u64 v[156:157], s[24:25], 0, v[140:141]
	s_add_i32 m0, s34, 0xc000
	ds_read_b128 v[200:203], v168
	ds_read_b128 v[204:207], v168 offset:1024
	ds_read_b128 v[208:211], v168 offset:2048
	ds_read_b128 v[212:215], v168 offset:3072
	ds_read_b128 v[216:219], v168 offset:4096
	ds_read_b128 v[220:223], v168 offset:5120
	ds_read_b128 v[224:227], v168 offset:6144
	ds_read_b128 v[228:231], v168 offset:7168
	global_load_lds_dwordx4 v[156:157], off
	v_lshl_add_u64 v[156:157], s[24:25], 0, v[142:143]
	s_add_i32 m0, s34, 0xe000
	s_nop 0
	global_load_lds_dwordx4 v[156:157], off
	s_waitcnt vmcnt(8)
	s_waitcnt lgkmcnt(0)
	s_barrier
	s_setprio 1
	s_waitcnt lgkmcnt(0)
	v_mfma_f32_16x16x32_bf16 v[126:129], v[152:155], v[200:203], v[126:129]
	v_mfma_f32_16x16x32_bf16 v[126:129], v[172:175], v[204:207], v[126:129]
	v_mfma_f32_16x16x32_bf16 v[122:125], v[180:183], v[204:207], v[122:125]
	v_mfma_f32_16x16x32_bf16 v[122:125], v[176:179], v[200:203], v[122:125]
	v_mfma_f32_16x16x32_bf16 v[106:109], v[176:179], v[208:211], v[106:109]
	v_mfma_f32_16x16x32_bf16 v[106:109], v[180:183], v[212:215], v[106:109]
	v_mfma_f32_16x16x32_bf16 v[110:113], v[172:175], v[212:215], v[110:113]
	v_mfma_f32_16x16x32_bf16 v[110:113], v[152:155], v[208:211], v[110:113]
	v_mfma_f32_16x16x32_bf16 v[94:97], v[152:155], v[216:219], v[94:97]
	v_mfma_f32_16x16x32_bf16 v[94:97], v[172:175], v[220:223], v[94:97]
	v_mfma_f32_16x16x32_bf16 v[90:93], v[180:183], v[220:223], v[90:93]
	v_mfma_f32_16x16x32_bf16 v[90:93], v[176:179], v[216:219], v[90:93]
	v_mfma_f32_16x16x32_bf16 v[74:77], v[176:179], v[224:227], v[74:77]
	v_mfma_f32_16x16x32_bf16 v[74:77], v[180:183], v[228:231], v[74:77]
	v_mfma_f32_16x16x32_bf16 v[78:81], v[172:175], v[228:231], v[78:81]
	v_mfma_f32_16x16x32_bf16 v[78:81], v[152:155], v[224:227], v[78:81]
	s_setprio 0
	s_setprio 1
	v_mfma_f32_16x16x32_bf16 v[118:121], v[184:187], v[200:203], v[118:121]
	v_mfma_f32_16x16x32_bf16 v[118:121], v[188:191], v[204:207], v[118:121]
	v_mfma_f32_16x16x32_bf16 v[114:117], v[196:199], v[204:207], v[114:117]
	v_mfma_f32_16x16x32_bf16 v[114:117], v[192:195], v[200:203], v[114:117]
	v_mfma_f32_16x16x32_bf16 v[98:101], v[192:195], v[208:211], v[98:101]
	v_mfma_f32_16x16x32_bf16 v[98:101], v[196:199], v[212:215], v[98:101]
	v_mfma_f32_16x16x32_bf16 v[102:105], v[188:191], v[212:215], v[102:105]
	v_mfma_f32_16x16x32_bf16 v[102:105], v[184:187], v[208:211], v[102:105]
	v_mfma_f32_16x16x32_bf16 v[86:89], v[184:187], v[216:219], v[86:89]
	v_mfma_f32_16x16x32_bf16 v[86:89], v[188:191], v[220:223], v[86:89]
	v_mfma_f32_16x16x32_bf16 v[82:85], v[196:199], v[220:223], v[82:85]
	v_mfma_f32_16x16x32_bf16 v[82:85], v[192:195], v[216:219], v[82:85]
	v_mfma_f32_16x16x32_bf16 v[66:69], v[192:195], v[224:227], v[66:69]
	v_mfma_f32_16x16x32_bf16 v[66:69], v[196:199], v[228:231], v[66:69]
	v_mfma_f32_16x16x32_bf16 v[70:73], v[188:191], v[228:231], v[70:73]
	v_mfma_f32_16x16x32_bf16 v[70:73], v[184:187], v[224:227], v[70:73]
	s_setprio 0
	s_barrier
	s_add_i32 s23, s45, s3
	v_lshl_add_u64 v[156:157], s[26:27], 0, v[134:135]
	s_mov_b32 m0, s23
	ds_read_b128 v[200:203], v168 offset:16384
	ds_read_b128 v[204:207], v168 offset:17408
	ds_read_b128 v[208:211], v168 offset:18432
	ds_read_b128 v[212:215], v168 offset:19456
	ds_read_b128 v[216:219], v168 offset:20480
	ds_read_b128 v[220:223], v168 offset:21504
	ds_read_b128 v[224:227], v168 offset:22528
	ds_read_b128 v[228:231], v168 offset:23552
	global_load_lds_dwordx4 v[156:157], off
	s_add_i32 m0, s23, 0x2000
	s_add_u32 s48, s26, 0x80000
	v_lshl_add_u64 v[232:233], s[26:27], 0, v[130:131]
	s_addc_u32 s49, s27, 0
	s_add_i32 s23, s46, s3
	global_load_lds_dwordx4 v[232:233], off
	v_lshl_add_u64 v[234:235], s[48:49], 0, v[134:135]
	s_mov_b32 m0, s23
	v_lshl_add_u64 v[236:237], s[28:29], 0, v[132:133]
	global_load_lds_dwordx4 v[234:235], off
	v_lshl_add_u64 v[234:235], s[48:49], 0, v[130:131]
	s_add_i32 m0, s23, 0x2000
	s_nop 0
	global_load_lds_dwordx4 v[234:235], off
	v_lshl_add_u64 v[234:235], s[28:29], 0, v[136:137]
	s_mov_b32 m0, s34
	s_nop 0
	global_load_lds_dwordx4 v[234:235], off
	s_mov_b32 m0, s35
	s_nop 0
	global_load_lds_dwordx4 v[236:237], off
	s_waitcnt vmcnt(8)
	s_waitcnt lgkmcnt(0)
	s_barrier
; #define PG8_STAGE(bufoff, gbase, voff) do { _Pragma("unroll") for (int _i = 0; _i < 2; ++_i) \
;         __builtin_amdgcn_global_load_lds((const unsigned*)((const char*)(gbase) + (voff)[_i]), (PG8_LAS unsigned*)(lds + (bufoff) + ldsw + _i * 8192), 16, 0, 0); } while (0)
; #define PG8_LDA(dst, b, h) do { _Pragma("unroll") for (int m = 0; m < 4; ++m) _Pragma("unroll") for (int k = 0; k < 2; ++k) dst[m][k] = *(const PG8_LAS bf16x8*)(lds + PG8_SA(b, h) + aoff + m * 2048 + k * 1024); } while (0)
; #define PG8_LDB(dst, b, h) do { _Pragma("unroll") for (int n = 0; n < 2; ++n) _Pragma("unroll") for (int k = 0; k < 2; ++k) dst[n][k] = *(const PG8_LAS bf16x8*)(lds + PG8_SB(b, h) + boff + n * 2048 + k * 1024); } while (0)
; #define PG8_MMA(ai, bj, At, Bt) do { __builtin_amdgcn_s_setprio(1); _Pragma("unroll") for (int m = 0; m < 4; ++m) _Pragma("unroll") for (int n = 0; n < 2; ++n) _Pragma("unroll") for (int k = 0; k < 2; ++k) \
;         acc[ai][bj][m][n] = __builtin_amdgcn_mfma_f32_16x16x32_bf16(Bt[n][k], At[m][k], acc[ai][bj][m][n], 0, 0, 0); __builtin_amdgcn_s_setprio(0); } while (0)
; #define PG8_WAIT_V(n) asm volatile("s_waitcnt vmcnt(" #n ")" ::: "memory")
; #define PG8_WAIT_L(n) asm volatile("s_waitcnt lgkmcnt(" #n ")" ::: "memory")
; #define PG8_BAR __builtin_amdgcn_s_barrier()
; #define PG8_SCHED __builtin_amdgcn_sched_barrier(0)
; template <class Epi, class Sched, bool ALIGN_EPI>
; __device__ __forceinline__ void gemm_phase(PG8_LAS unsigned char* lds, const Gemm g, const Sched& S, const Epi& E) {
;     ...
;             PG8_WAIT_V(8); PG8_WAIT_L(0); PG8_BAR; PG8_MMA(1, 0, At, B0); PG8_MMA(1, 1, At, B1); PG8_BAR; PG8_SCHED;
;             PG8_LDB(B0, 1, 0); PG8_LDB(B1, 1, 1); PG8_SCHED; PG8_LDA(At, 1, 0); PG8_STAGE(PG8_SA(0, 1), a2 + hstepA, voffA);
;             PG8_WAIT_V(8); PG8_WAIT_L(0); PG8_BAR; PG8_MMA(0, 0, At, B0); PG8_MMA(0, 1, At, B1); PG8_BAR; PG8_SCHED;
	s_setprio 1
	s_waitcnt lgkmcnt(0)
	v_mfma_f32_16x16x32_bf16 v[62:65], v[152:155], v[200:203], v[62:65]
	v_mfma_f32_16x16x32_bf16 v[62:65], v[172:175], v[204:207], v[62:65]
	v_mfma_f32_16x16x32_bf16 v[58:61], v[180:183], v[204:207], v[58:61]
	v_mfma_f32_16x16x32_bf16 v[58:61], v[176:179], v[200:203], v[58:61]
	v_mfma_f32_16x16x32_bf16 v[42:45], v[176:179], v[208:211], v[42:45]
	v_mfma_f32_16x16x32_bf16 v[42:45], v[180:183], v[212:215], v[42:45]
	v_mfma_f32_16x16x32_bf16 v[46:49], v[172:175], v[212:215], v[46:49]
	v_mfma_f32_16x16x32_bf16 v[46:49], v[152:155], v[208:211], v[46:49]
	v_mfma_f32_16x16x32_bf16 v[30:33], v[152:155], v[216:219], v[30:33]
	v_mfma_f32_16x16x32_bf16 v[30:33], v[172:175], v[220:223], v[30:33]
	v_mfma_f32_16x16x32_bf16 v[26:29], v[180:183], v[220:223], v[26:29]
	v_mfma_f32_16x16x32_bf16 v[26:29], v[176:179], v[216:219], v[26:29]
	v_mfma_f32_16x16x32_bf16 v[10:13], v[176:179], v[224:227], v[10:13]
	v_mfma_f32_16x16x32_bf16 v[10:13], v[180:183], v[228:231], v[10:13]
	v_mfma_f32_16x16x32_bf16 v[14:17], v[172:175], v[228:231], v[14:17]
	v_mfma_f32_16x16x32_bf16 v[14:17], v[152:155], v[224:227], v[14:17]
	s_setprio 0
	s_setprio 1
	v_mfma_f32_16x16x32_bf16 v[54:57], v[184:187], v[200:203], v[54:57]
	v_mfma_f32_16x16x32_bf16 v[54:57], v[188:191], v[204:207], v[54:57]
	v_mfma_f32_16x16x32_bf16 v[50:53], v[196:199], v[204:207], v[50:53]
	v_mfma_f32_16x16x32_bf16 v[50:53], v[192:195], v[200:203], v[50:53]
	v_mfma_f32_16x16x32_bf16 v[34:37], v[192:195], v[208:211], v[34:37]
	v_mfma_f32_16x16x32_bf16 v[34:37], v[196:199], v[212:215], v[34:37]
	v_mfma_f32_16x16x32_bf16 v[38:41], v[188:191], v[212:215], v[38:41]
	v_mfma_f32_16x16x32_bf16 v[38:41], v[184:187], v[208:211], v[38:41]
	v_mfma_f32_16x16x32_bf16 v[22:25], v[184:187], v[216:219], v[22:25]
	v_mfma_f32_16x16x32_bf16 v[22:25], v[188:191], v[220:223], v[22:25]
	v_mfma_f32_16x16x32_bf16 v[18:21], v[196:199], v[220:223], v[18:21]
	v_mfma_f32_16x16x32_bf16 v[18:21], v[192:195], v[216:219], v[18:21]
	v_mfma_f32_16x16x32_bf16 v[2:5], v[192:195], v[224:227], v[2:5]
	v_mfma_f32_16x16x32_bf16 v[2:5], v[196:199], v[228:231], v[2:5]
	v_mfma_f32_16x16x32_bf16 v[6:9], v[188:191], v[228:231], v[6:9]
	v_mfma_f32_16x16x32_bf16 v[6:9], v[184:187], v[224:227], v[6:9]
	s_setprio 0
	s_barrier
	s_add_i32 s23, 0, 0x18000
	v_add_u32_e32 v149, s23, v159
	s_add_i32 s48, 0, 0x1c000
	ds_read_b128 v[152:155], v149
	ds_read_b128 v[172:175], v149 offset:1024
	ds_read_b128 v[176:179], v149 offset:2048
	ds_read_b128 v[180:183], v149 offset:3072
	v_add_u32_e32 v149, s48, v159
	ds_read_b128 v[184:187], v149
	ds_read_b128 v[188:191], v149 offset:1024
	ds_read_b128 v[192:195], v149 offset:2048
	ds_read_b128 v[196:199], v149 offset:3072
	s_add_u32 s28, s28, 0x80000
	s_addc_u32 s29, s29, 0
	s_mov_b32 m0, s36
	v_lshl_add_u64 v[238:239], s[28:29], 0, v[136:137]
	ds_read_b128 v[200:203], v168 offset:32768
	ds_read_b128 v[204:207], v168 offset:33792
	ds_read_b128 v[208:211], v168 offset:34816
	ds_read_b128 v[212:215], v168 offset:35840
	ds_read_b128 v[216:219], v168 offset:36864
	ds_read_b128 v[220:223], v168 offset:37888
	ds_read_b128 v[224:227], v168 offset:38912
	ds_read_b128 v[228:231], v168 offset:39936
	global_load_lds_dwordx4 v[238:239], off
	v_lshl_add_u64 v[238:239], s[28:29], 0, v[132:133]
	s_mov_b32 m0, s37
	s_nop 0
	global_load_lds_dwordx4 v[238:239], off
	s_waitcnt vmcnt(8)
	s_waitcnt lgkmcnt(0)
	s_barrier
	s_setprio 1
	s_waitcnt lgkmcnt(0)
	v_mfma_f32_16x16x32_bf16 v[126:129], v[152:155], v[200:203], v[126:129]
	v_mfma_f32_16x16x32_bf16 v[126:129], v[172:175], v[204:207], v[126:129]
	v_mfma_f32_16x16x32_bf16 v[122:125], v[180:183], v[204:207], v[122:125]
	v_mfma_f32_16x16x32_bf16 v[122:125], v[176:179], v[200:203], v[122:125]
	v_mfma_f32_16x16x32_bf16 v[106:109], v[176:179], v[208:211], v[106:109]
	v_mfma_f32_16x16x32_bf16 v[106:109], v[180:183], v[212:215], v[106:109]
	v_mfma_f32_16x16x32_bf16 v[110:113], v[172:175], v[212:215], v[110:113]
	v_mfma_f32_16x16x32_bf16 v[110:113], v[152:155], v[208:211], v[110:113]
	v_mfma_f32_16x16x32_bf16 v[94:97], v[152:155], v[216:219], v[94:97]
	v_mfma_f32_16x16x32_bf16 v[94:97], v[172:175], v[220:223], v[94:97]
	v_mfma_f32_16x16x32_bf16 v[90:93], v[180:183], v[220:223], v[90:93]
	v_mfma_f32_16x16x32_bf16 v[90:93], v[176:179], v[216:219], v[90:93]
	v_mfma_f32_16x16x32_bf16 v[74:77], v[176:179], v[224:227], v[74:77]
	v_mfma_f32_16x16x32_bf16 v[74:77], v[180:183], v[228:231], v[74:77]
	v_mfma_f32_16x16x32_bf16 v[78:81], v[172:175], v[228:231], v[78:81]
	v_mfma_f32_16x16x32_bf16 v[78:81], v[152:155], v[224:227], v[78:81]
	s_setprio 0
	s_setprio 1
	v_mfma_f32_16x16x32_bf16 v[118:121], v[184:187], v[200:203], v[118:121]
	v_mfma_f32_16x16x32_bf16 v[118:121], v[188:191], v[204:207], v[118:121]
	v_mfma_f32_16x16x32_bf16 v[114:117], v[196:199], v[204:207], v[114:117]
	v_mfma_f32_16x16x32_bf16 v[114:117], v[192:195], v[200:203], v[114:117]
	v_mfma_f32_16x16x32_bf16 v[98:101], v[192:195], v[208:211], v[98:101]
	v_mfma_f32_16x16x32_bf16 v[98:101], v[196:199], v[212:215], v[98:101]
	v_mfma_f32_16x16x32_bf16 v[102:105], v[188:191], v[212:215], v[102:105]
	v_mfma_f32_16x16x32_bf16 v[102:105], v[184:187], v[208:211], v[102:105]
	v_mfma_f32_16x16x32_bf16 v[86:89], v[184:187], v[216:219], v[86:89]
	v_mfma_f32_16x16x32_bf16 v[86:89], v[188:191], v[220:223], v[86:89]
	v_mfma_f32_16x16x32_bf16 v[82:85], v[196:199], v[220:223], v[82:85]
	v_mfma_f32_16x16x32_bf16 v[82:85], v[192:195], v[216:219], v[82:85]
	v_mfma_f32_16x16x32_bf16 v[66:69], v[192:195], v[224:227], v[66:69]
	v_mfma_f32_16x16x32_bf16 v[66:69], v[196:199], v[228:231], v[66:69]
	v_mfma_f32_16x16x32_bf16 v[70:73], v[188:191], v[228:231], v[70:73]
	v_mfma_f32_16x16x32_bf16 v[70:73], v[184:187], v[224:227], v[70:73]
	s_setprio 0
	s_barrier
; #define PG8_STAGE(bufoff, gbase, voff) do { _Pragma("unroll") for (int _i = 0; _i < 2; ++_i) \
;         __builtin_amdgcn_global_load_lds((const unsigned*)((const char*)(gbase) + (voff)[_i]), (PG8_LAS unsigned*)(lds + (bufoff) + ldsw + _i * 8192), 16, 0, 0); } while (0)
; #define PG8_LDA(dst, b, h) do { _Pragma("unroll") for (int m = 0; m < 4; ++m) _Pragma("unroll") for (int k = 0; k < 2; ++k) dst[m][k] = *(const PG8_LAS bf16x8*)(lds + PG8_SA(b, h) + aoff + m * 2048 + k * 1024); } while (0)
; #define PG8_MMA(ai, bj, At, Bt) do { __builtin_amdgcn_s_setprio(1); _Pragma("unroll") for (int m = 0; m < 4; ++m) _Pragma("unroll") for (int n = 0; n < 2; ++n) _Pragma("unroll") for (int k = 0; k < 2; ++k) \
;         acc[ai][bj][m][n] = __builtin_amdgcn_mfma_f32_16x16x32_bf16(Bt[n][k], At[m][k], acc[ai][bj][m][n], 0, 0, 0); __builtin_amdgcn_s_setprio(0); } while (0)
; #define PG8_WAIT_V(n) asm volatile("s_waitcnt vmcnt(" #n ")" ::: "memory")
; #define PG8_WAIT_L(n) asm volatile("s_waitcnt lgkmcnt(" #n ")" ::: "memory")
; #define PG8_BAR __builtin_amdgcn_s_barrier()
; #define PG8_SCHED __builtin_amdgcn_sched_barrier(0)
; template <class Epi, class Sched, bool ALIGN_EPI>
; __device__ __forceinline__ void gemm_phase(PG8_LAS unsigned char* lds, const Gemm g, const Sched& S, const Epi& E) {
;     ...
;             PG8_LDA(At, 1, 1); PG8_STAGE(PG8_SB(1, 0), b3, voffB); PG8_STAGE(PG8_SB(1, 1), b3 + hstepB, voffB); PG8_STAGE(PG8_SA(1, 0), a3, voffA);
;             PG8_WAIT_V(8); PG8_WAIT_L(0); PG8_BAR; PG8_MMA(1, 0, At, B0); PG8_MMA(1, 1, At, B1); PG8_BAR; PG8_SCHED;
;         }
;         if constexpr (ALIGN_EPI) { if (wr == 0) PG8_BAR; }
	s_add_i32 s23, s23, s3
	v_lshl_add_u64 v[156:157], v[156:157], 0, s[8:9]
	s_mov_b32 m0, s23
	ds_read_b128 v[200:203], v168 offset:49152
	ds_read_b128 v[204:207], v168 offset:50176
	ds_read_b128 v[208:211], v168 offset:51200
	ds_read_b128 v[212:215], v168 offset:52224
	ds_read_b128 v[216:219], v168 offset:53248
	ds_read_b128 v[220:223], v168 offset:54272
	ds_read_b128 v[224:227], v168 offset:55296
	ds_read_b128 v[228:231], v168 offset:56320
	global_load_lds_dwordx4 v[156:157], off
	s_add_i32 m0, s23, 0x2000
	s_add_u32 s26, s26, 0x80080
	v_lshl_add_u64 v[156:157], v[232:233], 0, s[8:9]
	s_addc_u32 s27, s27, 0
	s_add_i32 s23, s48, s3
	global_load_lds_dwordx4 v[156:157], off
	v_lshl_add_u64 v[156:157], s[26:27], 0, v[134:135]
	s_mov_b32 m0, s23
	s_nop 0
	global_load_lds_dwordx4 v[156:157], off
	v_lshl_add_u64 v[156:157], s[26:27], 0, v[130:131]
	s_add_i32 m0, s23, 0x2000
	s_nop 0
	global_load_lds_dwordx4 v[156:157], off
	v_lshl_add_u64 v[156:157], v[234:235], 0, s[8:9]
	s_mov_b32 m0, s42
	s_nop 0
	global_load_lds_dwordx4 v[156:157], off
	v_lshl_add_u64 v[156:157], v[236:237], 0, s[8:9]
	s_mov_b32 m0, s43
	s_nop 0
	global_load_lds_dwordx4 v[156:157], off
	s_waitcnt vmcnt(8)
	s_waitcnt lgkmcnt(0)
	s_barrier
	s_setprio 1
	s_waitcnt lgkmcnt(0)
	v_mfma_f32_16x16x32_bf16 v[62:65], v[152:155], v[200:203], v[62:65]
	v_mfma_f32_16x16x32_bf16 v[62:65], v[172:175], v[204:207], v[62:65]
	v_mfma_f32_16x16x32_bf16 v[58:61], v[180:183], v[204:207], v[58:61]
	v_mfma_f32_16x16x32_bf16 v[58:61], v[176:179], v[200:203], v[58:61]
	v_mfma_f32_16x16x32_bf16 v[42:45], v[176:179], v[208:211], v[42:45]
	v_mfma_f32_16x16x32_bf16 v[42:45], v[180:183], v[212:215], v[42:45]
	v_mfma_f32_16x16x32_bf16 v[46:49], v[172:175], v[212:215], v[46:49]
	v_mfma_f32_16x16x32_bf16 v[46:49], v[152:155], v[208:211], v[46:49]
	v_mfma_f32_16x16x32_bf16 v[30:33], v[152:155], v[216:219], v[30:33]
	v_mfma_f32_16x16x32_bf16 v[30:33], v[172:175], v[220:223], v[30:33]
	v_mfma_f32_16x16x32_bf16 v[26:29], v[180:183], v[220:223], v[26:29]
	v_mfma_f32_16x16x32_bf16 v[26:29], v[176:179], v[216:219], v[26:29]
	v_mfma_f32_16x16x32_bf16 v[10:13], v[176:179], v[224:227], v[10:13]
	v_mfma_f32_16x16x32_bf16 v[10:13], v[180:183], v[228:231], v[10:13]
	v_mfma_f32_16x16x32_bf16 v[14:17], v[172:175], v[228:231], v[14:17]
	v_mfma_f32_16x16x32_bf16 v[14:17], v[152:155], v[224:227], v[14:17]
	s_setprio 0
	s_setprio 1
	v_mfma_f32_16x16x32_bf16 v[54:57], v[184:187], v[200:203], v[54:57]
	v_mfma_f32_16x16x32_bf16 v[54:57], v[188:191], v[204:207], v[54:57]
	v_mfma_f32_16x16x32_bf16 v[50:53], v[196:199], v[204:207], v[50:53]
	v_mfma_f32_16x16x32_bf16 v[50:53], v[192:195], v[200:203], v[50:53]
	v_mfma_f32_16x16x32_bf16 v[34:37], v[192:195], v[208:211], v[34:37]
	v_mfma_f32_16x16x32_bf16 v[34:37], v[196:199], v[212:215], v[34:37]
	v_mfma_f32_16x16x32_bf16 v[38:41], v[188:191], v[212:215], v[38:41]
	v_mfma_f32_16x16x32_bf16 v[38:41], v[184:187], v[208:211], v[38:41]
	v_mfma_f32_16x16x32_bf16 v[22:25], v[184:187], v[216:219], v[22:25]
	v_mfma_f32_16x16x32_bf16 v[22:25], v[188:191], v[220:223], v[22:25]
	v_mfma_f32_16x16x32_bf16 v[18:21], v[196:199], v[220:223], v[18:21]
	v_mfma_f32_16x16x32_bf16 v[18:21], v[192:195], v[216:219], v[18:21]
	v_mfma_f32_16x16x32_bf16 v[2:5], v[192:195], v[224:227], v[2:5]
	v_mfma_f32_16x16x32_bf16 v[2:5], v[196:199], v[228:231], v[2:5]
	v_mfma_f32_16x16x32_bf16 v[6:9], v[188:191], v[228:231], v[6:9]
	v_mfma_f32_16x16x32_bf16 v[6:9], v[184:187], v[224:227], v[6:9]
	s_setprio 0
	s_barrier
	s_add_i32 s17, s17, 2
	s_add_u32 s24, s24, 0x100
	s_addc_u32 s25, s25, 0
	s_add_u32 s5, s5, 0x100
	s_addc_u32 s15, s15, 0
	s_cmp_gt_u32 s17, 29
	s_cbranch_scc0 .LBB0_403
	s_and_b64 vcc, exec, s[10:11]
	s_cbranch_vccz .LBB0_406
	s_barrier

; #define PG8_STAGE(bufoff, gbase, voff) do { _Pragma("unroll") for (int _i = 0; _i < 2; ++_i) \
;         __builtin_amdgcn_global_load_lds((const unsigned*)((const char*)(gbase) + (voff)[_i]), (PG8_LAS unsigned*)(lds + (bufoff) + ldsw + _i * 8192), 16, 0, 0); } while (0)
; #define PG8_LDA(dst, b, h) do { _Pragma("unroll") for (int m = 0; m < 4; ++m) _Pragma("unroll") for (int k = 0; k < 2; ++k) dst[m][k] = *(const PG8_LAS bf16x8*)(lds + PG8_SA(b, h) + aoff + m * 2048 + k * 1024); } while (0)
; #define PG8_LDB(dst, b, h) do { _Pragma("unroll") for (int n = 0; n < 2; ++n) _Pragma("unroll") for (int k = 0; k < 2; ++k) dst[n][k] = *(const PG8_LAS bf16x8*)(lds + PG8_SB(b, h) + boff + n * 2048 + k * 1024); } while (0)
; #define PG8_MMA(ai, bj, At, Bt) do { __builtin_amdgcn_s_setprio(1); _Pragma("unroll") for (int m = 0; m < 4; ++m) _Pragma("unroll") for (int n = 0; n < 2; ++n) _Pragma("unroll") for (int k = 0; k < 2; ++k) \
;         acc[ai][bj][m][n] = __builtin_amdgcn_mfma_f32_16x16x32_bf16(Bt[n][k], At[m][k], acc[ai][bj][m][n], 0, 0, 0); __builtin_amdgcn_s_setprio(0); } while (0)
; #define PG8_WAIT_V(n) asm volatile("s_waitcnt vmcnt(" #n ")" ::: "memory")
; #define PG8_WAIT_L(n) asm volatile("s_waitcnt lgkmcnt(" #n ")" ::: "memory")
; #define PG8_BAR __builtin_amdgcn_s_barrier()
; #define PG8_SCHED __builtin_amdgcn_sched_barrier(0)
; template <class Epi, class Sched, bool ALIGN_EPI>
; __device__ __forceinline__ void gemm_phase(PG8_LAS unsigned char* lds, const Gemm g, const Sched& S, const Epi& E) {
;     ...
;             PG8_LDB(B0, 0, 0); PG8_LDB(B1, 0, 1); PG8_SCHED; PG8_LDA(At, 0, 0); PG8_STAGE(PG8_SA(1, 1), a1 + hstepA, voffA);
;             PG8_WAIT_V(8); PG8_WAIT_L(0); PG8_BAR; PG8_MMA(0, 0, At, B0); PG8_MMA(0, 1, At, B1); PG8_BAR; PG8_SCHED;
;             PG8_LDA(At, 0, 1); PG8_STAGE(PG8_SB(0, 0), b2, voffB); PG8_STAGE(PG8_SB(0, 1), b2 + hstepB, voffB); PG8_STAGE(PG8_SA(0, 0), a2, voffA);
;             PG8_WAIT_V(8); PG8_WAIT_L(0); PG8_BAR; PG8_MMA(1, 0, At, B0); PG8_MMA(1, 1, At, B1); PG8_BAR; PG8_SCHED;
.LBB0_431:
	ds_read_b128 v[150:153], v147
	ds_read_b128 v[154:157], v147 offset:1024
	ds_read_b128 v[158:161], v147 offset:2048
	ds_read_b128 v[162:165], v147 offset:3072
	ds_read_b128 v[166:169], v148
	ds_read_b128 v[170:173], v148 offset:1024
	ds_read_b128 v[174:177], v148 offset:2048
	ds_read_b128 v[178:181], v148 offset:3072
	s_add_u32 s34, s30, 0xfff80080
	s_addc_u32 s35, s31, -1
	s_cmp_eq_u32 s54, 28
	s_cselect_b32 s37, s25, s35
	s_cselect_b32 s36, s24, s34
	s_cselect_b32 s35, s27, s23
	s_cselect_b32 s34, s26, s21
	v_lshl_add_u64 v[142:143], s[30:31], 0, v[138:139]
	s_add_i32 m0, s29, 0xc000
	ds_read_b128 v[182:185], v149
	ds_read_b128 v[186:189], v149 offset:1024
	ds_read_b128 v[190:193], v149 offset:2048
	ds_read_b128 v[194:197], v149 offset:3072
	ds_read_b128 v[198:201], v149 offset:4096
	ds_read_b128 v[202:205], v149 offset:5120
	ds_read_b128 v[206:209], v149 offset:6144
	ds_read_b128 v[210:213], v149 offset:7168
	global_load_lds_dwordx4 v[142:143], off
	v_lshl_add_u64 v[142:143], s[30:31], 0, v[140:141]
	s_add_i32 m0, s29, 0xe000
	s_nop 0
	global_load_lds_dwordx4 v[142:143], off
	s_waitcnt vmcnt(8)
	s_waitcnt lgkmcnt(0)
	s_barrier
	s_setprio 1
	s_waitcnt lgkmcnt(0)
	v_mfma_f32_16x16x32_bf16 v[126:129], v[150:153], v[182:185], v[126:129]
	v_mfma_f32_16x16x32_bf16 v[126:129], v[154:157], v[186:189], v[126:129]
	v_mfma_f32_16x16x32_bf16 v[122:125], v[162:165], v[186:189], v[122:125]
	v_mfma_f32_16x16x32_bf16 v[122:125], v[158:161], v[182:185], v[122:125]
	v_mfma_f32_16x16x32_bf16 v[110:113], v[158:161], v[190:193], v[110:113]
	v_mfma_f32_16x16x32_bf16 v[110:113], v[162:165], v[194:197], v[110:113]
	v_mfma_f32_16x16x32_bf16 v[118:121], v[154:157], v[194:197], v[118:121]
	v_mfma_f32_16x16x32_bf16 v[118:121], v[150:153], v[190:193], v[118:121]
	v_mfma_f32_16x16x32_bf16 v[102:105], v[150:153], v[198:201], v[102:105]
	v_mfma_f32_16x16x32_bf16 v[102:105], v[154:157], v[202:205], v[102:105]
	v_mfma_f32_16x16x32_bf16 v[94:97], v[162:165], v[202:205], v[94:97]
	v_mfma_f32_16x16x32_bf16 v[94:97], v[158:161], v[198:201], v[94:97]
	v_mfma_f32_16x16x32_bf16 v[78:81], v[158:161], v[206:209], v[78:81]
	v_mfma_f32_16x16x32_bf16 v[78:81], v[162:165], v[210:213], v[78:81]
	v_mfma_f32_16x16x32_bf16 v[86:89], v[154:157], v[210:213], v[86:89]
	v_mfma_f32_16x16x32_bf16 v[86:89], v[150:153], v[206:209], v[86:89]
	s_setprio 0
	s_setprio 1
	v_mfma_f32_16x16x32_bf16 v[114:117], v[166:169], v[182:185], v[114:117]
	v_mfma_f32_16x16x32_bf16 v[114:117], v[170:173], v[186:189], v[114:117]
	v_mfma_f32_16x16x32_bf16 v[106:109], v[178:181], v[186:189], v[106:109]
	v_mfma_f32_16x16x32_bf16 v[106:109], v[174:177], v[182:185], v[106:109]
	v_mfma_f32_16x16x32_bf16 v[90:93], v[174:177], v[190:193], v[90:93]
	v_mfma_f32_16x16x32_bf16 v[90:93], v[178:181], v[194:197], v[90:93]
	v_mfma_f32_16x16x32_bf16 v[98:101], v[170:173], v[194:197], v[98:101]
	v_mfma_f32_16x16x32_bf16 v[98:101], v[166:169], v[190:193], v[98:101]
	v_mfma_f32_16x16x32_bf16 v[82:85], v[166:169], v[198:201], v[82:85]
	v_mfma_f32_16x16x32_bf16 v[82:85], v[170:173], v[202:205], v[82:85]
	v_mfma_f32_16x16x32_bf16 v[74:77], v[178:181], v[202:205], v[74:77]
	v_mfma_f32_16x16x32_bf16 v[74:77], v[174:177], v[198:201], v[74:77]
	v_mfma_f32_16x16x32_bf16 v[66:69], v[174:177], v[206:209], v[66:69]
	v_mfma_f32_16x16x32_bf16 v[66:69], v[178:181], v[210:213], v[66:69]
	v_mfma_f32_16x16x32_bf16 v[70:73], v[170:173], v[210:213], v[70:73]
	v_mfma_f32_16x16x32_bf16 v[70:73], v[166:169], v[206:209], v[70:73]
	s_setprio 0
	s_barrier
	s_add_i32 s55, s47, s39
	v_lshl_add_u64 v[142:143], s[34:35], 0, v[132:133]
	s_mov_b32 m0, s55
	ds_read_b128 v[182:185], v149 offset:16384
	ds_read_b128 v[186:189], v149 offset:17408
	ds_read_b128 v[190:193], v149 offset:18432
	ds_read_b128 v[194:197], v149 offset:19456
	ds_read_b128 v[198:201], v149 offset:20480
	ds_read_b128 v[202:205], v149 offset:21504
	ds_read_b128 v[206:209], v149 offset:22528
	ds_read_b128 v[210:213], v149 offset:23552
	global_load_lds_dwordx4 v[142:143], off
	s_add_i32 m0, s55, 0x2000
	s_add_u32 s56, s34, 0x80000
	v_lshl_add_u64 v[214:215], s[34:35], 0, v[136:137]
	s_addc_u32 s57, s35, 0
	s_add_i32 s55, s48, s39
	global_load_lds_dwordx4 v[214:215], off
	v_lshl_add_u64 v[216:217], s[56:57], 0, v[132:133]
	s_mov_b32 m0, s55
	v_lshl_add_u64 v[218:219], s[36:37], 0, v[134:135]
	global_load_lds_dwordx4 v[216:217], off
	v_lshl_add_u64 v[216:217], s[56:57], 0, v[136:137]
	s_add_i32 m0, s55, 0x2000
	s_nop 0
	global_load_lds_dwordx4 v[216:217], off
	v_lshl_add_u64 v[216:217], s[36:37], 0, v[130:131]
	s_mov_b32 m0, s29
	s_nop 0
	global_load_lds_dwordx4 v[216:217], off
	s_mov_b32 m0, s40
	s_nop 0
	global_load_lds_dwordx4 v[218:219], off
	s_waitcnt vmcnt(8)
	s_waitcnt lgkmcnt(0)
	s_barrier
; #define PG8_STAGE(bufoff, gbase, voff) do { _Pragma("unroll") for (int _i = 0; _i < 2; ++_i) \
;         __builtin_amdgcn_global_load_lds((const unsigned*)((const char*)(gbase) + (voff)[_i]), (PG8_LAS unsigned*)(lds + (bufoff) + ldsw + _i * 8192), 16, 0, 0); } while (0)
; #define PG8_LDA(dst, b, h) do { _Pragma("unroll") for (int m = 0; m < 4; ++m) _Pragma("unroll") for (int k = 0; k < 2; ++k) dst[m][k] = *(const PG8_LAS bf16x8*)(lds + PG8_SA(b, h) + aoff + m * 2048 + k * 1024); } while (0)
; #define PG8_LDB(dst, b, h) do { _Pragma("unroll") for (int n = 0; n < 2; ++n) _Pragma("unroll") for (int k = 0; k < 2; ++k) dst[n][k] = *(const PG8_LAS bf16x8*)(lds + PG8_SB(b, h) + boff + n * 2048 + k * 1024); } while (0)
; #define PG8_MMA(ai, bj, At, Bt) do { __builtin_amdgcn_s_setprio(1); _Pragma("unroll") for (int m = 0; m < 4; ++m) _Pragma("unroll") for (int n = 0; n < 2; ++n) _Pragma("unroll") for (int k = 0; k < 2; ++k) \
;         acc[ai][bj][m][n] = __builtin_amdgcn_mfma_f32_16x16x32_bf16(Bt[n][k], At[m][k], acc[ai][bj][m][n], 0, 0, 0); __builtin_amdgcn_s_setprio(0); } while (0)
; #define PG8_WAIT_V(n) asm volatile("s_waitcnt vmcnt(" #n ")" ::: "memory")
; #define PG8_WAIT_L(n) asm volatile("s_waitcnt lgkmcnt(" #n ")" ::: "memory")
; #define PG8_BAR __builtin_amdgcn_s_barrier()
; #define PG8_SCHED __builtin_amdgcn_sched_barrier(0)
; template <class Epi, class Sched, bool ALIGN_EPI>
; __device__ __forceinline__ void gemm_phase(PG8_LAS unsigned char* lds, const Gemm g, const Sched& S, const Epi& E) {
;     ...
;             PG8_WAIT_V(8); PG8_WAIT_L(0); PG8_BAR; PG8_MMA(1, 0, At, B0); PG8_MMA(1, 1, At, B1); PG8_BAR; PG8_SCHED;
;             PG8_LDB(B0, 1, 0); PG8_LDB(B1, 1, 1); PG8_SCHED; PG8_LDA(At, 1, 0); PG8_STAGE(PG8_SA(0, 1), a2 + hstepA, voffA);
;             PG8_WAIT_V(8); PG8_WAIT_L(0); PG8_BAR; PG8_MMA(0, 0, At, B0); PG8_MMA(0, 1, At, B1); PG8_BAR; PG8_SCHED;
	s_setprio 1
	s_waitcnt lgkmcnt(0)
	v_mfma_f32_16x16x32_bf16 v[62:65], v[150:153], v[182:185], v[62:65]
	v_mfma_f32_16x16x32_bf16 v[62:65], v[154:157], v[186:189], v[62:65]
	v_mfma_f32_16x16x32_bf16 v[58:61], v[162:165], v[186:189], v[58:61]
	v_mfma_f32_16x16x32_bf16 v[58:61], v[158:161], v[182:185], v[58:61]
	v_mfma_f32_16x16x32_bf16 v[46:49], v[158:161], v[190:193], v[46:49]
	v_mfma_f32_16x16x32_bf16 v[46:49], v[162:165], v[194:197], v[46:49]
	v_mfma_f32_16x16x32_bf16 v[54:57], v[154:157], v[194:197], v[54:57]
	v_mfma_f32_16x16x32_bf16 v[54:57], v[150:153], v[190:193], v[54:57]
	v_mfma_f32_16x16x32_bf16 v[38:41], v[150:153], v[198:201], v[38:41]
	v_mfma_f32_16x16x32_bf16 v[38:41], v[154:157], v[202:205], v[38:41]
	v_mfma_f32_16x16x32_bf16 v[30:33], v[162:165], v[202:205], v[30:33]
	v_mfma_f32_16x16x32_bf16 v[30:33], v[158:161], v[198:201], v[30:33]
	v_mfma_f32_16x16x32_bf16 v[14:17], v[158:161], v[206:209], v[14:17]
	v_mfma_f32_16x16x32_bf16 v[14:17], v[162:165], v[210:213], v[14:17]
	v_mfma_f32_16x16x32_bf16 v[22:25], v[154:157], v[210:213], v[22:25]
	v_mfma_f32_16x16x32_bf16 v[22:25], v[150:153], v[206:209], v[22:25]
	s_setprio 0
	s_setprio 1
	v_mfma_f32_16x16x32_bf16 v[50:53], v[166:169], v[182:185], v[50:53]
	v_mfma_f32_16x16x32_bf16 v[50:53], v[170:173], v[186:189], v[50:53]
	v_mfma_f32_16x16x32_bf16 v[42:45], v[178:181], v[186:189], v[42:45]
	v_mfma_f32_16x16x32_bf16 v[42:45], v[174:177], v[182:185], v[42:45]
	v_mfma_f32_16x16x32_bf16 v[26:29], v[174:177], v[190:193], v[26:29]
	v_mfma_f32_16x16x32_bf16 v[26:29], v[178:181], v[194:197], v[26:29]
	v_mfma_f32_16x16x32_bf16 v[34:37], v[170:173], v[194:197], v[34:37]
	v_mfma_f32_16x16x32_bf16 v[34:37], v[166:169], v[190:193], v[34:37]
	v_mfma_f32_16x16x32_bf16 v[18:21], v[166:169], v[198:201], v[18:21]
	v_mfma_f32_16x16x32_bf16 v[18:21], v[170:173], v[202:205], v[18:21]
	v_mfma_f32_16x16x32_bf16 v[10:13], v[178:181], v[202:205], v[10:13]
	v_mfma_f32_16x16x32_bf16 v[10:13], v[174:177], v[198:201], v[10:13]
	v_mfma_f32_16x16x32_bf16 v[2:5], v[174:177], v[206:209], v[2:5]
	v_mfma_f32_16x16x32_bf16 v[2:5], v[178:181], v[210:213], v[2:5]
	v_mfma_f32_16x16x32_bf16 v[6:9], v[170:173], v[210:213], v[6:9]
	v_mfma_f32_16x16x32_bf16 v[6:9], v[166:169], v[206:209], v[6:9]
	s_setprio 0
	s_barrier
	s_add_i32 s55, 0, 0x18000
	s_add_i32 s56, 0, 0x1c000
	v_add_u32_e32 v162, s55, v145
	v_add_u32_e32 v178, s56, v145
	ds_read_b128 v[150:153], v162
	ds_read_b128 v[154:157], v162 offset:1024
	ds_read_b128 v[158:161], v162 offset:2048
	ds_read_b128 v[162:165], v162 offset:3072
	ds_read_b128 v[166:169], v178
	ds_read_b128 v[170:173], v178 offset:1024
	ds_read_b128 v[174:177], v178 offset:2048
	ds_read_b128 v[178:181], v178 offset:3072
	s_add_u32 s36, s36, 0x80000
	s_addc_u32 s37, s37, 0
	s_mov_b32 m0, s41
	v_lshl_add_u64 v[220:221], s[36:37], 0, v[130:131]
	ds_read_b128 v[182:185], v149 offset:32768
	ds_read_b128 v[186:189], v149 offset:33792
	ds_read_b128 v[190:193], v149 offset:34816
	ds_read_b128 v[194:197], v149 offset:35840
	ds_read_b128 v[198:201], v149 offset:36864
	ds_read_b128 v[202:205], v149 offset:37888
	ds_read_b128 v[206:209], v149 offset:38912
	ds_read_b128 v[210:213], v149 offset:39936
	global_load_lds_dwordx4 v[220:221], off
	v_lshl_add_u64 v[220:221], s[36:37], 0, v[134:135]
	s_mov_b32 m0, s42
	s_nop 0
	global_load_lds_dwordx4 v[220:221], off
	s_waitcnt vmcnt(8)
	s_waitcnt lgkmcnt(0)
	s_barrier
	s_setprio 1
	s_waitcnt lgkmcnt(0)
	v_mfma_f32_16x16x32_bf16 v[126:129], v[150:153], v[182:185], v[126:129]
	v_mfma_f32_16x16x32_bf16 v[126:129], v[154:157], v[186:189], v[126:129]
	v_mfma_f32_16x16x32_bf16 v[122:125], v[162:165], v[186:189], v[122:125]
	v_mfma_f32_16x16x32_bf16 v[122:125], v[158:161], v[182:185], v[122:125]
	v_mfma_f32_16x16x32_bf16 v[110:113], v[158:161], v[190:193], v[110:113]
	v_mfma_f32_16x16x32_bf16 v[110:113], v[162:165], v[194:197], v[110:113]
	v_mfma_f32_16x16x32_bf16 v[118:121], v[154:157], v[194:197], v[118:121]
	v_mfma_f32_16x16x32_bf16 v[118:121], v[150:153], v[190:193], v[118:121]
	v_mfma_f32_16x16x32_bf16 v[102:105], v[150:153], v[198:201], v[102:105]
	v_mfma_f32_16x16x32_bf16 v[102:105], v[154:157], v[202:205], v[102:105]
	v_mfma_f32_16x16x32_bf16 v[94:97], v[162:165], v[202:205], v[94:97]
	v_mfma_f32_16x16x32_bf16 v[94:97], v[158:161], v[198:201], v[94:97]
	v_mfma_f32_16x16x32_bf16 v[78:81], v[158:161], v[206:209], v[78:81]
	v_mfma_f32_16x16x32_bf16 v[78:81], v[162:165], v[210:213], v[78:81]
	v_mfma_f32_16x16x32_bf16 v[86:89], v[154:157], v[210:213], v[86:89]
	v_mfma_f32_16x16x32_bf16 v[86:89], v[150:153], v[206:209], v[86:89]
	s_setprio 0
	s_setprio 1
	v_mfma_f32_16x16x32_bf16 v[114:117], v[166:169], v[182:185], v[114:117]
	v_mfma_f32_16x16x32_bf16 v[114:117], v[170:173], v[186:189], v[114:117]
	v_mfma_f32_16x16x32_bf16 v[106:109], v[178:181], v[186:189], v[106:109]
	v_mfma_f32_16x16x32_bf16 v[106:109], v[174:177], v[182:185], v[106:109]
	v_mfma_f32_16x16x32_bf16 v[90:93], v[174:177], v[190:193], v[90:93]
	v_mfma_f32_16x16x32_bf16 v[90:93], v[178:181], v[194:197], v[90:93]
	v_mfma_f32_16x16x32_bf16 v[98:101], v[170:173], v[194:197], v[98:101]
	v_mfma_f32_16x16x32_bf16 v[98:101], v[166:169], v[190:193], v[98:101]
	v_mfma_f32_16x16x32_bf16 v[82:85], v[166:169], v[198:201], v[82:85]
	v_mfma_f32_16x16x32_bf16 v[82:85], v[170:173], v[202:205], v[82:85]
	v_mfma_f32_16x16x32_bf16 v[74:77], v[178:181], v[202:205], v[74:77]
	v_mfma_f32_16x16x32_bf16 v[74:77], v[174:177], v[198:201], v[74:77]
	v_mfma_f32_16x16x32_bf16 v[66:69], v[174:177], v[206:209], v[66:69]
	v_mfma_f32_16x16x32_bf16 v[66:69], v[178:181], v[210:213], v[66:69]
	v_mfma_f32_16x16x32_bf16 v[70:73], v[170:173], v[210:213], v[70:73]
	v_mfma_f32_16x16x32_bf16 v[70:73], v[166:169], v[206:209], v[70:73]
	s_setprio 0
	s_barrier
; #define PG8_STAGE(bufoff, gbase, voff) do { _Pragma("unroll") for (int _i = 0; _i < 2; ++_i) \
;         __builtin_amdgcn_global_load_lds((const unsigned*)((const char*)(gbase) + (voff)[_i]), (PG8_LAS unsigned*)(lds + (bufoff) + ldsw + _i * 8192), 16, 0, 0); } while (0)
; #define PG8_LDA(dst, b, h) do { _Pragma("unroll") for (int m = 0; m < 4; ++m) _Pragma("unroll") for (int k = 0; k < 2; ++k) dst[m][k] = *(const PG8_LAS bf16x8*)(lds + PG8_SA(b, h) + aoff + m * 2048 + k * 1024); } while (0)
; #define PG8_MMA(ai, bj, At, Bt) do { __builtin_amdgcn_s_setprio(1); _Pragma("unroll") for (int m = 0; m < 4; ++m) _Pragma("unroll") for (int n = 0; n < 2; ++n) _Pragma("unroll") for (int k = 0; k < 2; ++k) \
;         acc[ai][bj][m][n] = __builtin_amdgcn_mfma_f32_16x16x32_bf16(Bt[n][k], At[m][k], acc[ai][bj][m][n], 0, 0, 0); __builtin_amdgcn_s_setprio(0); } while (0)
; #define PG8_WAIT_V(n) asm volatile("s_waitcnt vmcnt(" #n ")" ::: "memory")
; #define PG8_WAIT_L(n) asm volatile("s_waitcnt lgkmcnt(" #n ")" ::: "memory")
; #define PG8_BAR __builtin_amdgcn_s_barrier()
; #define PG8_SCHED __builtin_amdgcn_sched_barrier(0)
; template <class Epi, class Sched, bool ALIGN_EPI>
; __device__ __forceinline__ void gemm_phase(PG8_LAS unsigned char* lds, const Gemm g, const Sched& S, const Epi& E) {
;     ...
;             PG8_LDA(At, 1, 1); PG8_STAGE(PG8_SB(1, 0), b3, voffB); PG8_STAGE(PG8_SB(1, 1), b3 + hstepB, voffB); PG8_STAGE(PG8_SA(1, 0), a3, voffA);
;             PG8_WAIT_V(8); PG8_WAIT_L(0); PG8_BAR; PG8_MMA(1, 0, At, B0); PG8_MMA(1, 1, At, B1); PG8_BAR; PG8_SCHED;
;         }
;         if constexpr (ALIGN_EPI) { if (wr == 0) PG8_BAR; }
	s_add_i32 s36, s55, s39
	v_lshl_add_u64 v[142:143], v[142:143], 0, s[8:9]
	s_mov_b32 m0, s36
	ds_read_b128 v[182:185], v149 offset:49152
	ds_read_b128 v[186:189], v149 offset:50176
	ds_read_b128 v[190:193], v149 offset:51200
	ds_read_b128 v[194:197], v149 offset:52224
	ds_read_b128 v[198:201], v149 offset:53248
	ds_read_b128 v[202:205], v149 offset:54272
	ds_read_b128 v[206:209], v149 offset:55296
	ds_read_b128 v[210:213], v149 offset:56320
	global_load_lds_dwordx4 v[142:143], off
	s_add_i32 m0, s36, 0x2000
	s_add_u32 s34, s34, 0x80080
	v_lshl_add_u64 v[142:143], v[214:215], 0, s[8:9]
	s_addc_u32 s35, s35, 0
	s_add_i32 s36, s56, s39
	global_load_lds_dwordx4 v[142:143], off
	v_lshl_add_u64 v[142:143], s[34:35], 0, v[132:133]
	s_mov_b32 m0, s36
	s_nop 0
	global_load_lds_dwordx4 v[142:143], off
	v_lshl_add_u64 v[142:143], s[34:35], 0, v[136:137]
	s_add_i32 m0, s36, 0x2000
	s_nop 0
	global_load_lds_dwordx4 v[142:143], off
	v_lshl_add_u64 v[142:143], v[216:217], 0, s[8:9]
	s_mov_b32 m0, s44
	s_nop 0
	global_load_lds_dwordx4 v[142:143], off
	v_lshl_add_u64 v[142:143], v[218:219], 0, s[8:9]
	s_mov_b32 m0, s45
	s_nop 0
	global_load_lds_dwordx4 v[142:143], off
	s_waitcnt vmcnt(8)
	s_waitcnt lgkmcnt(0)
	s_barrier
	s_setprio 1
	s_waitcnt lgkmcnt(0)
	v_mfma_f32_16x16x32_bf16 v[62:65], v[150:153], v[182:185], v[62:65]
	v_mfma_f32_16x16x32_bf16 v[62:65], v[154:157], v[186:189], v[62:65]
	v_mfma_f32_16x16x32_bf16 v[58:61], v[162:165], v[186:189], v[58:61]
	v_mfma_f32_16x16x32_bf16 v[58:61], v[158:161], v[182:185], v[58:61]
	v_mfma_f32_16x16x32_bf16 v[46:49], v[158:161], v[190:193], v[46:49]
	v_mfma_f32_16x16x32_bf16 v[46:49], v[162:165], v[194:197], v[46:49]
	v_mfma_f32_16x16x32_bf16 v[54:57], v[154:157], v[194:197], v[54:57]
	v_mfma_f32_16x16x32_bf16 v[54:57], v[150:153], v[190:193], v[54:57]
	v_mfma_f32_16x16x32_bf16 v[38:41], v[150:153], v[198:201], v[38:41]
	v_mfma_f32_16x16x32_bf16 v[38:41], v[154:157], v[202:205], v[38:41]
	v_mfma_f32_16x16x32_bf16 v[30:33], v[162:165], v[202:205], v[30:33]
	v_mfma_f32_16x16x32_bf16 v[30:33], v[158:161], v[198:201], v[30:33]
	v_mfma_f32_16x16x32_bf16 v[14:17], v[158:161], v[206:209], v[14:17]
	v_mfma_f32_16x16x32_bf16 v[14:17], v[162:165], v[210:213], v[14:17]
	v_mfma_f32_16x16x32_bf16 v[22:25], v[154:157], v[210:213], v[22:25]
	v_mfma_f32_16x16x32_bf16 v[22:25], v[150:153], v[206:209], v[22:25]
	s_setprio 0
	s_setprio 1
	v_mfma_f32_16x16x32_bf16 v[50:53], v[166:169], v[182:185], v[50:53]
	v_mfma_f32_16x16x32_bf16 v[50:53], v[170:173], v[186:189], v[50:53]
	v_mfma_f32_16x16x32_bf16 v[42:45], v[178:181], v[186:189], v[42:45]
	v_mfma_f32_16x16x32_bf16 v[42:45], v[174:177], v[182:185], v[42:45]
	v_mfma_f32_16x16x32_bf16 v[26:29], v[174:177], v[190:193], v[26:29]
	v_mfma_f32_16x16x32_bf16 v[26:29], v[178:181], v[194:197], v[26:29]
	v_mfma_f32_16x16x32_bf16 v[34:37], v[170:173], v[194:197], v[34:37]
	v_mfma_f32_16x16x32_bf16 v[34:37], v[166:169], v[190:193], v[34:37]
	v_mfma_f32_16x16x32_bf16 v[18:21], v[166:169], v[198:201], v[18:21]
	v_mfma_f32_16x16x32_bf16 v[18:21], v[170:173], v[202:205], v[18:21]
	v_mfma_f32_16x16x32_bf16 v[10:13], v[178:181], v[202:205], v[10:13]
	v_mfma_f32_16x16x32_bf16 v[10:13], v[174:177], v[198:201], v[10:13]
	v_mfma_f32_16x16x32_bf16 v[2:5], v[174:177], v[206:209], v[2:5]
	v_mfma_f32_16x16x32_bf16 v[2:5], v[178:181], v[210:213], v[2:5]
	v_mfma_f32_16x16x32_bf16 v[6:9], v[170:173], v[210:213], v[6:9]
	v_mfma_f32_16x16x32_bf16 v[6:9], v[166:169], v[206:209], v[6:9]
	s_setprio 0
	s_barrier
	s_add_i32 s54, s54, 2
	s_add_u32 s30, s30, 0x100
	s_addc_u32 s31, s31, 0
	s_add_u32 s21, s21, 0x100
	s_addc_u32 s23, s23, 0
	s_cmp_gt_u32 s54, 29
	s_cbranch_scc0 .LBB0_431
	s_and_b64 vcc, exec, s[10:11]
	s_cbranch_vccz .LBB0_434
	s_barrier

; #define PG8_STAGE(bufoff, gbase, voff) do { _Pragma("unroll") for (int _i = 0; _i < 2; ++_i) \
;         __builtin_amdgcn_global_load_lds((const unsigned*)((const char*)(gbase) + (voff)[_i]), (PG8_LAS unsigned*)(lds + (bufoff) + ldsw + _i * 8192), 16, 0, 0); } while (0)
; #define PG8_LDA(dst, b, h) do { _Pragma("unroll") for (int m = 0; m < 4; ++m) _Pragma("unroll") for (int k = 0; k < 2; ++k) dst[m][k] = *(const PG8_LAS bf16x8*)(lds + PG8_SA(b, h) + aoff + m * 2048 + k * 1024); } while (0)
; #define PG8_LDB(dst, b, h) do { _Pragma("unroll") for (int n = 0; n < 2; ++n) _Pragma("unroll") for (int k = 0; k < 2; ++k) dst[n][k] = *(const PG8_LAS bf16x8*)(lds + PG8_SB(b, h) + boff + n * 2048 + k * 1024); } while (0)
; #define PG8_MMA(ai, bj, At, Bt) do { __builtin_amdgcn_s_setprio(1); _Pragma("unroll") for (int m = 0; m < 4; ++m) _Pragma("unroll") for (int n = 0; n < 2; ++n) _Pragma("unroll") for (int k = 0; k < 2; ++k) \
;         acc[ai][bj][m][n] = __builtin_amdgcn_mfma_f32_16x16x32_bf16(Bt[n][k], At[m][k], acc[ai][bj][m][n], 0, 0, 0); __builtin_amdgcn_s_setprio(0); } while (0)
; #define PG8_WAIT_V(n) asm volatile("s_waitcnt vmcnt(" #n ")" ::: "memory")
; #define PG8_WAIT_L(n) asm volatile("s_waitcnt lgkmcnt(" #n ")" ::: "memory")
; template <class Epi, class Sched, bool ALIGN_EPI>
; __device__ __forceinline__ void gemm_phase(PG8_LAS unsigned char* lds, const Gemm g, const Sched& S, const Epi& E) {
;     ...
;         for (int t = 0; t < nt; t += 2) {
;             if constexpr (Epi::MIDK) { if (t == (nt >> 1)) E.midk(acc, cur, wr, fr); }
;             const bool last = (t == nt - 2);
;             const char* a1 = cA + (size_t)(t + 1) * kstepA;
;             const char* a2 = last ? nA : cA + (size_t)(t + 2) * kstepA; const char* b2 = last ? nB : cB + (size_t)(t + 2) * kstep;
;             const char* a3 = a2 + kstepA; const char* b3 = b2 + kstep;
;             PG8_LDB(B0, 0, 0); PG8_LDB(B1, 0, 1); PG8_SCHED; PG8_LDA(At, 0, 0); PG8_STAGE(PG8_SA(1, 1), a1 + hstepA, voffA);
;             PG8_WAIT_V(8); PG8_WAIT_L(0); PG8_BAR; PG8_MMA(0, 0, At, B0); PG8_MMA(0, 1, At, B1); PG8_BAR; PG8_SCHED;
;             PG8_LDA(At, 0, 1); PG8_STAGE(PG8_SB(0, 0), b2, voffB); PG8_STAGE(PG8_SB(0, 1), b2 + hstepB, voffB); PG8_STAGE(PG8_SA(0, 0), a2, voffA);
;             PG8_WAIT_V(8); PG8_WAIT_L(0); PG8_BAR; PG8_MMA(1, 0, At, B0); PG8_MMA(1, 1, At, B1); PG8_BAR; PG8_SCHED;
.LBB0_628:
	s_ashr_i32 s54, s48, 2
	s_and_b64 s[56:57], s[24:25], exec
	s_cselect_b32 s56, s54, s55
	s_cselect_b32 s55, 0, 0x100
	s_add_u32 s20, s22, s20
	s_addc_u32 s21, s23, s21
	s_ashr_i32 s57, s56, 31
	s_lshl_b64 s[22:23], s[56:57], 17
	ds_read_b128 v[2:5], v79
	ds_read_b128 v[6:9], v79 offset:1024
	ds_read_b128 v[10:13], v79 offset:2048
	ds_read_b128 v[14:17], v79 offset:3072
	s_add_u32 s56, s31, s22
	s_addc_u32 s57, s34, s23
	s_and_b64 s[22:23], s[24:25], exec
	s_cselect_b32 s22, s56, s28
	s_cselect_b32 s23, s57, s29
	s_add_u32 s22, s22, s55
	s_addc_u32 s23, s23, 0
	s_add_u32 s56, s26, 0x18080
	s_addc_u32 s57, s27, 0
	s_mov_b32 m0, s47
	v_lshl_add_u64 v[50:51], s[56:57], 0, v[72:73]
	ds_read_b128 v[18:21], v80
	ds_read_b128 v[22:25], v80 offset:1024
	ds_read_b128 v[26:29], v80 offset:2048
	ds_read_b128 v[30:33], v80 offset:3072
	ds_read_b128 v[34:37], v80 offset:4096
	ds_read_b128 v[38:41], v80 offset:5120
	ds_read_b128 v[42:45], v80 offset:6144
	ds_read_b128 v[46:49], v80 offset:7168
	global_load_lds_dwordx4 v[50:51], off
	v_lshl_add_u64 v[50:51], s[56:57], 0, v[68:69]
	s_mov_b32 m0, s49
	s_nop 0
	global_load_lds_dwordx4 v[50:51], off
	s_waitcnt vmcnt(8)
	s_waitcnt lgkmcnt(0)
	s_barrier
	s_setprio 1
	s_waitcnt lgkmcnt(0)
	v_mfma_f32_16x16x32_bf16 v[50:53], v[2:5], v[18:21], 0
	v_mfma_f32_16x16x32_bf16 v[18:21], v[10:13], v[18:21], 0
	v_mfma_f32_16x16x32_bf16 v[50:53], v[6:9], v[22:25], v[50:53]
	v_mfma_f32_16x16x32_bf16 v[18:21], v[14:17], v[22:25], v[18:21]
	v_mfma_f32_16x16x32_bf16 v[22:25], v[2:5], v[26:29], 0
	v_mfma_f32_16x16x32_bf16 v[26:29], v[10:13], v[26:29], 0
	v_mfma_f32_16x16x32_bf16 v[22:25], v[6:9], v[30:33], v[22:25]
	v_mfma_f32_16x16x32_bf16 v[26:29], v[14:17], v[30:33], v[26:29]
	v_mfma_f32_16x16x32_bf16 v[30:33], v[2:5], v[34:37], 0
	v_mfma_f32_16x16x32_bf16 v[34:37], v[10:13], v[34:37], 0
	v_mfma_f32_16x16x32_bf16 v[30:33], v[6:9], v[38:41], v[30:33]
	v_mfma_f32_16x16x32_bf16 v[34:37], v[14:17], v[38:41], v[34:37]
	v_mfma_f32_16x16x32_bf16 v[38:41], v[2:5], v[42:45], 0
	v_mfma_f32_16x16x32_bf16 v[42:45], v[10:13], v[42:45], 0
	v_mfma_f32_16x16x32_bf16 v[38:41], v[6:9], v[46:49], v[38:41]
	v_mfma_f32_16x16x32_bf16 v[42:45], v[14:17], v[46:49], v[42:45]
	s_setprio 0
	s_setprio 1
	s_setprio 0
	s_barrier
	v_lshl_add_u64 v[130:131], s[28:29], 0, v[70:71]
	s_mov_b32 m0, s50
	v_lshl_add_u64 v[98:99], v[130:131], 0, s[16:17]
	v_lshl_add_u64 v[132:133], s[28:29], 0, v[66:67]
	s_add_u32 s56, s28, 0x10100
	ds_read_b128 v[46:49], v80 offset:16384
	ds_read_b128 v[54:57], v80 offset:17408
	ds_read_b128 v[58:61], v80 offset:18432
	ds_read_b128 v[62:65], v80 offset:19456
	ds_read_b128 v[82:85], v80 offset:20480
	ds_read_b128 v[86:89], v80 offset:21504
	ds_read_b128 v[90:93], v80 offset:22528
	ds_read_b128 v[94:97], v80 offset:23552
	global_load_lds_dwordx4 v[98:99], off
	v_lshl_add_u64 v[98:99], v[132:133], 0, s[16:17]
	s_mov_b32 m0, s51
	s_addc_u32 s57, s29, 0
	global_load_lds_dwordx4 v[98:99], off
	v_lshl_add_u64 v[98:99], s[56:57], 0, v[70:71]
	s_mov_b32 m0, s36
	v_lshl_add_u64 v[134:135], s[26:27], 0, v[72:73]
	global_load_lds_dwordx4 v[98:99], off
	v_lshl_add_u64 v[98:99], s[56:57], 0, v[66:67]
	s_mov_b32 m0, s37
	v_lshl_add_u64 v[136:137], s[26:27], 0, v[68:69]
	global_load_lds_dwordx4 v[98:99], off
	v_lshl_add_u64 v[98:99], v[134:135], 0, s[16:17]
	s_mov_b32 m0, s35
	s_nop 0
	global_load_lds_dwordx4 v[98:99], off
	v_lshl_add_u64 v[98:99], v[136:137], 0, s[16:17]
	s_mov_b32 m0, s39
	s_nop 0
	global_load_lds_dwordx4 v[98:99], off
	s_waitcnt vmcnt(8)
	s_waitcnt lgkmcnt(0)
	s_barrier
	s_setprio 1
	s_waitcnt lgkmcnt(0)
	v_mfma_f32_16x16x32_bf16 v[98:101], v[2:5], v[46:49], 0
	v_mfma_f32_16x16x32_bf16 v[46:49], v[10:13], v[46:49], 0
	v_mfma_f32_16x16x32_bf16 v[98:101], v[6:9], v[54:57], v[98:101]
	v_mfma_f32_16x16x32_bf16 v[46:49], v[14:17], v[54:57], v[46:49]
	v_mfma_f32_16x16x32_bf16 v[54:57], v[2:5], v[58:61], 0
	v_mfma_f32_16x16x32_bf16 v[58:61], v[10:13], v[58:61], 0
	v_mfma_f32_16x16x32_bf16 v[54:57], v[6:9], v[62:65], v[54:57]
	v_mfma_f32_16x16x32_bf16 v[58:61], v[14:17], v[62:65], v[58:61]
	v_mfma_f32_16x16x32_bf16 v[62:65], v[2:5], v[82:85], 0
	v_mfma_f32_16x16x32_bf16 v[2:5], v[2:5], v[90:93], 0
	v_mfma_f32_16x16x32_bf16 v[62:65], v[6:9], v[86:89], v[62:65]
	v_mfma_f32_16x16x32_bf16 v[2:5], v[6:9], v[94:97], v[2:5]
	v_mfma_f32_16x16x32_bf16 v[6:9], v[10:13], v[90:93], 0
	v_mfma_f32_16x16x32_bf16 v[82:85], v[10:13], v[82:85], 0
	v_mfma_f32_16x16x32_bf16 v[6:9], v[14:17], v[94:97], v[6:9]
	v_mfma_f32_16x16x32_bf16 v[82:85], v[14:17], v[86:89], v[82:85]
	s_setprio 0
	s_setprio 1
	s_setprio 0
	s_barrier
	ds_read_b128 v[10:13], v81
	ds_read_b128 v[14:17], v81 offset:1024
	ds_read_b128 v[86:89], v81 offset:2048
	ds_read_b128 v[90:93], v81 offset:3072
	s_add_u32 s56, s26, 0x18100
	s_addc_u32 s57, s27, 0
	s_mov_b32 m0, s40
	v_lshl_add_u64 v[138:139], s[56:57], 0, v[72:73]
	ds_read_b128 v[94:97], v80 offset:32768
	ds_read_b128 v[102:105], v80 offset:33792
	ds_read_b128 v[106:109], v80 offset:34816
	ds_read_b128 v[110:113], v80 offset:35840
	ds_read_b128 v[114:117], v80 offset:36864
	ds_read_b128 v[118:121], v80 offset:37888
	ds_read_b128 v[122:125], v80 offset:38912
	ds_read_b128 v[126:129], v80 offset:39936
	global_load_lds_dwordx4 v[138:139], off
	v_lshl_add_u64 v[138:139], s[56:57], 0, v[68:69]
	s_mov_b32 m0, s41
	s_nop 0
	global_load_lds_dwordx4 v[138:139], off
	s_waitcnt vmcnt(8)
	s_waitcnt lgkmcnt(0)
	s_barrier
; #define PG8_STAGE(bufoff, gbase, voff) do { _Pragma("unroll") for (int _i = 0; _i < 2; ++_i) \
;         __builtin_amdgcn_global_load_lds((const unsigned*)((const char*)(gbase) + (voff)[_i]), (PG8_LAS unsigned*)(lds + (bufoff) + ldsw + _i * 8192), 16, 0, 0); } while (0)
; #define PG8_LDA(dst, b, h) do { _Pragma("unroll") for (int m = 0; m < 4; ++m) _Pragma("unroll") for (int k = 0; k < 2; ++k) dst[m][k] = *(const PG8_LAS bf16x8*)(lds + PG8_SA(b, h) + aoff + m * 2048 + k * 1024); } while (0)
; #define PG8_LDB(dst, b, h) do { _Pragma("unroll") for (int n = 0; n < 2; ++n) _Pragma("unroll") for (int k = 0; k < 2; ++k) dst[n][k] = *(const PG8_LAS bf16x8*)(lds + PG8_SB(b, h) + boff + n * 2048 + k * 1024); } while (0)
; #define PG8_MMA(ai, bj, At, Bt) do { __builtin_amdgcn_s_setprio(1); _Pragma("unroll") for (int m = 0; m < 4; ++m) _Pragma("unroll") for (int n = 0; n < 2; ++n) _Pragma("unroll") for (int k = 0; k < 2; ++k) \
;         acc[ai][bj][m][n] = __builtin_amdgcn_mfma_f32_16x16x32_bf16(Bt[n][k], At[m][k], acc[ai][bj][m][n], 0, 0, 0); __builtin_amdgcn_s_setprio(0); } while (0)
; #define PG8_WAIT_V(n) asm volatile("s_waitcnt vmcnt(" #n ")" ::: "memory")
; #define PG8_WAIT_L(n) asm volatile("s_waitcnt lgkmcnt(" #n ")" ::: "memory")
; #define PG8_BAR __builtin_amdgcn_s_barrier()
; #define PG8_SCHED __builtin_amdgcn_sched_barrier(0)
; template <class Epi, class Sched, bool ALIGN_EPI>
; __device__ __forceinline__ void gemm_phase(PG8_LAS unsigned char* lds, const Gemm g, const Sched& S, const Epi& E) {
;     ...
;             PG8_WAIT_V(8); PG8_WAIT_L(0); PG8_BAR; PG8_MMA(1, 0, At, B0); PG8_MMA(1, 1, At, B1); PG8_BAR; PG8_SCHED;
;             PG8_LDB(B0, 1, 0); PG8_LDB(B1, 1, 1); PG8_SCHED; PG8_LDA(At, 1, 0); PG8_STAGE(PG8_SA(0, 1), a2 + hstepA, voffA);
;             PG8_WAIT_V(8); PG8_WAIT_L(0); PG8_BAR; PG8_MMA(0, 0, At, B0); PG8_MMA(0, 1, At, B1); PG8_BAR; PG8_SCHED;
;             PG8_LDA(At, 1, 1); PG8_STAGE(PG8_SB(1, 0), b3, voffB); PG8_STAGE(PG8_SB(1, 1), b3 + hstepB, voffB); PG8_STAGE(PG8_SA(1, 0), a3, voffA);
;             PG8_WAIT_V(8); PG8_WAIT_L(0); PG8_BAR; PG8_MMA(1, 0, At, B0); PG8_MMA(1, 1, At, B1); PG8_BAR; PG8_SCHED;
	s_setprio 1
	s_waitcnt lgkmcnt(0)
	v_mfma_f32_16x16x32_bf16 v[50:53], v[10:13], v[94:97], v[50:53]
	v_mfma_f32_16x16x32_bf16 v[50:53], v[14:17], v[102:105], v[50:53]
	v_mfma_f32_16x16x32_bf16 v[18:21], v[90:93], v[102:105], v[18:21]
	v_mfma_f32_16x16x32_bf16 v[18:21], v[86:89], v[94:97], v[18:21]
	v_mfma_f32_16x16x32_bf16 v[26:29], v[86:89], v[106:109], v[26:29]
	v_mfma_f32_16x16x32_bf16 v[26:29], v[90:93], v[110:113], v[26:29]
	v_mfma_f32_16x16x32_bf16 v[22:25], v[14:17], v[110:113], v[22:25]
	v_mfma_f32_16x16x32_bf16 v[22:25], v[10:13], v[106:109], v[22:25]
	v_mfma_f32_16x16x32_bf16 v[30:33], v[10:13], v[114:117], v[30:33]
	v_mfma_f32_16x16x32_bf16 v[30:33], v[14:17], v[118:121], v[30:33]
	v_mfma_f32_16x16x32_bf16 v[34:37], v[90:93], v[118:121], v[34:37]
	v_mfma_f32_16x16x32_bf16 v[34:37], v[86:89], v[114:117], v[34:37]
	v_mfma_f32_16x16x32_bf16 v[42:45], v[86:89], v[122:125], v[42:45]
	v_mfma_f32_16x16x32_bf16 v[42:45], v[90:93], v[126:129], v[42:45]
	v_mfma_f32_16x16x32_bf16 v[38:41], v[14:17], v[126:129], v[38:41]
	v_mfma_f32_16x16x32_bf16 v[38:41], v[10:13], v[122:125], v[38:41]
	s_setprio 0
	s_setprio 1
	s_setprio 0
	s_barrier
	s_mov_b32 m0, s52
	v_lshl_add_u64 v[130:131], v[130:131], 0, s[18:19]
	s_add_u32 s28, s28, 0x10180
	ds_read_b128 v[94:97], v80 offset:49152
	ds_read_b128 v[102:105], v80 offset:50176
	ds_read_b128 v[106:109], v80 offset:51200
	ds_read_b128 v[110:113], v80 offset:52224
	ds_read_b128 v[114:117], v80 offset:53248
	ds_read_b128 v[118:121], v80 offset:54272
	ds_read_b128 v[122:125], v80 offset:55296
	ds_read_b128 v[126:129], v80 offset:56320
	global_load_lds_dwordx4 v[130:131], off
	v_lshl_add_u64 v[130:131], v[132:133], 0, s[18:19]
	s_mov_b32 m0, s53
	s_addc_u32 s29, s29, 0
	global_load_lds_dwordx4 v[130:131], off
	v_lshl_add_u64 v[130:131], s[28:29], 0, v[70:71]
	s_mov_b32 m0, s44
	s_nop 0
	global_load_lds_dwordx4 v[130:131], off
	v_lshl_add_u64 v[130:131], s[28:29], 0, v[66:67]
	s_mov_b32 m0, s45
	s_nop 0
	global_load_lds_dwordx4 v[130:131], off
	v_lshl_add_u64 v[130:131], v[134:135], 0, s[18:19]
	s_mov_b32 m0, s42
	s_nop 0
	global_load_lds_dwordx4 v[130:131], off
	v_lshl_add_u64 v[130:131], v[136:137], 0, s[18:19]
	s_mov_b32 m0, s43
	s_nop 0
	global_load_lds_dwordx4 v[130:131], off
	s_waitcnt vmcnt(8)
	s_waitcnt lgkmcnt(0)
	s_barrier
	s_setprio 1
	s_waitcnt lgkmcnt(0)
	v_mfma_f32_16x16x32_bf16 v[46:49], v[86:89], v[94:97], v[46:49]
	v_mfma_f32_16x16x32_bf16 v[46:49], v[90:93], v[102:105], v[46:49]
	v_mfma_f32_16x16x32_bf16 v[54:57], v[14:17], v[110:113], v[54:57]
	v_mfma_f32_16x16x32_bf16 v[54:57], v[10:13], v[106:109], v[54:57]
	v_mfma_f32_16x16x32_bf16 v[62:65], v[10:13], v[114:117], v[62:65]
	v_mfma_f32_16x16x32_bf16 v[62:65], v[14:17], v[118:121], v[62:65]
	v_mfma_f32_16x16x32_bf16 v[58:61], v[90:93], v[110:113], v[58:61]
	v_mfma_f32_16x16x32_bf16 v[58:61], v[86:89], v[106:109], v[58:61]
	v_mfma_f32_16x16x32_bf16 v[2:5], v[10:13], v[122:125], v[2:5]
	v_mfma_f32_16x16x32_bf16 v[2:5], v[14:17], v[126:129], v[2:5]
	v_mfma_f32_16x16x32_bf16 v[6:9], v[90:93], v[126:129], v[6:9]
	v_mfma_f32_16x16x32_bf16 v[6:9], v[86:89], v[122:125], v[6:9]
	v_mfma_f32_16x16x32_bf16 v[82:85], v[86:89], v[114:117], v[82:85]
	v_mfma_f32_16x16x32_bf16 v[82:85], v[90:93], v[118:121], v[82:85]
	v_mfma_f32_16x16x32_bf16 v[98:101], v[14:17], v[102:105], v[98:101]
	v_mfma_f32_16x16x32_bf16 v[98:101], v[10:13], v[94:97], v[98:101]
	s_setprio 0
	s_setprio 1
	s_setprio 0
	s_barrier
	ds_read_b128 v[10:13], v79
	ds_read_b128 v[14:17], v79 offset:1024
	ds_read_b128 v[86:89], v79 offset:2048
	ds_read_b128 v[90:93], v79 offset:3072
	s_add_u32 s26, s26, 0x18180
	s_addc_u32 s27, s27, 0
	s_mov_b32 m0, s47
	v_lshl_add_u64 v[130:131], s[26:27], 0, v[72:73]
	ds_read_b128 v[94:97], v80
	ds_read_b128 v[102:105], v80 offset:1024
	ds_read_b128 v[106:109], v80 offset:2048
	ds_read_b128 v[110:113], v80 offset:3072
	ds_read_b128 v[114:117], v80 offset:4096
	ds_read_b128 v[118:121], v80 offset:5120
	ds_read_b128 v[122:125], v80 offset:6144
	ds_read_b128 v[126:129], v80 offset:7168
	global_load_lds_dwordx4 v[130:131], off
	v_lshl_add_u64 v[130:131], s[26:27], 0, v[68:69]
	s_mov_b32 m0, s49
	s_nop 0
	global_load_lds_dwordx4 v[130:131], off
	s_waitcnt vmcnt(8)
	s_waitcnt lgkmcnt(0)
	s_barrier
	s_setprio 1
	s_waitcnt lgkmcnt(0)
	v_mfma_f32_16x16x32_bf16 v[26:29], v[86:89], v[106:109], v[26:29]
	v_mfma_f32_16x16x32_bf16 v[50:53], v[10:13], v[94:97], v[50:53]
	v_mfma_f32_16x16x32_bf16 v[18:21], v[86:89], v[94:97], v[18:21]
	v_mfma_f32_16x16x32_bf16 v[94:97], v[90:93], v[110:113], v[26:29]
	v_mfma_f32_16x16x32_bf16 v[26:29], v[10:13], v[114:117], v[30:33]
	v_mfma_f32_16x16x32_bf16 v[50:53], v[14:17], v[102:105], v[50:53]
	v_mfma_f32_16x16x32_bf16 v[18:21], v[90:93], v[102:105], v[18:21]
	v_mfma_f32_16x16x32_bf16 v[102:105], v[14:17], v[118:121], v[26:29]
	v_mfma_f32_16x16x32_bf16 v[26:29], v[86:89], v[114:117], v[34:37]
	v_mfma_f32_16x16x32_bf16 v[34:37], v[90:93], v[118:121], v[26:29]
	v_mfma_f32_16x16x32_bf16 v[26:29], v[10:13], v[122:125], v[38:41]
	v_mfma_f32_16x16x32_bf16 v[22:25], v[10:13], v[106:109], v[22:25]
	v_mfma_f32_16x16x32_bf16 v[38:41], v[14:17], v[126:129], v[26:29]
	v_mfma_f32_16x16x32_bf16 v[26:29], v[86:89], v[122:125], v[42:45]
	v_mfma_f32_16x16x32_bf16 v[22:25], v[14:17], v[110:113], v[22:25]
	v_mfma_f32_16x16x32_bf16 v[42:45], v[90:93], v[126:129], v[26:29]
	s_setprio 0
	s_setprio 1
	s_setprio 0
	s_barrier
; #define PG8_STAGE(bufoff, gbase, voff) do { _Pragma("unroll") for (int _i = 0; _i < 2; ++_i) \
;         __builtin_amdgcn_global_load_lds((const unsigned*)((const char*)(gbase) + (voff)[_i]), (PG8_LAS unsigned*)(lds + (bufoff) + ldsw + _i * 8192), 16, 0, 0); } while (0)
; #define PG8_LDA(dst, b, h) do { _Pragma("unroll") for (int m = 0; m < 4; ++m) _Pragma("unroll") for (int k = 0; k < 2; ++k) dst[m][k] = *(const PG8_LAS bf16x8*)(lds + PG8_SA(b, h) + aoff + m * 2048 + k * 1024); } while (0)
; #define PG8_MMA(ai, bj, At, Bt) do { __builtin_amdgcn_s_setprio(1); _Pragma("unroll") for (int m = 0; m < 4; ++m) _Pragma("unroll") for (int n = 0; n < 2; ++n) _Pragma("unroll") for (int k = 0; k < 2; ++k) \
;         acc[ai][bj][m][n] = __builtin_amdgcn_mfma_f32_16x16x32_bf16(Bt[n][k], At[m][k], acc[ai][bj][m][n], 0, 0, 0); __builtin_amdgcn_s_setprio(0); } while (0)
; #define PG8_WAIT_V(n) asm volatile("s_waitcnt vmcnt(" #n ")" ::: "memory")
; #define PG8_WAIT_L(n) asm volatile("s_waitcnt lgkmcnt(" #n ")" ::: "memory")
; #define PG8_BAR __builtin_amdgcn_s_barrier()
; #define PG8_SCHED __builtin_amdgcn_sched_barrier(0)
; template <class Epi, class Sched, bool ALIGN_EPI>
; __device__ __forceinline__ void gemm_phase(PG8_LAS unsigned char* lds, const Gemm g, const Sched& S, const Epi& E) {
;     ...
;             PG8_WAIT_V(8); PG8_WAIT_L(0); PG8_BAR; PG8_MMA(0, 0, At, B0); PG8_MMA(0, 1, At, B1); PG8_BAR; PG8_SCHED;
;             PG8_LDA(At, 1, 1); PG8_STAGE(PG8_SB(1, 0), b3, voffB); PG8_STAGE(PG8_SB(1, 1), b3 + hstepB, voffB); PG8_STAGE(PG8_SA(1, 0), a3, voffA);
;             PG8_WAIT_V(8); PG8_WAIT_L(0); PG8_BAR; PG8_MMA(1, 0, At, B0); PG8_MMA(1, 1, At, B1); PG8_BAR; PG8_SCHED;
;         }
;         if constexpr (ALIGN_EPI) { if (wr == 0) PG8_BAR; }
	s_mov_b32 m0, s50
	v_lshl_add_u64 v[142:143], s[22:23], 0, v[70:71]
	s_add_u32 s26, s22, 0x10000
	ds_read_b128 v[26:29], v80 offset:16384
	ds_read_b128 v[30:33], v80 offset:17408
	ds_read_b128 v[106:109], v80 offset:18432
	ds_read_b128 v[110:113], v80 offset:19456
	ds_read_b128 v[114:117], v80 offset:20480
	ds_read_b128 v[118:121], v80 offset:21504
	ds_read_b128 v[122:125], v80 offset:22528
	ds_read_b128 v[126:129], v80 offset:23552
	global_load_lds_dwordx4 v[142:143], off
	v_lshl_add_u64 v[144:145], s[22:23], 0, v[66:67]
	s_mov_b32 m0, s51
	s_addc_u32 s27, s23, 0
	global_load_lds_dwordx4 v[144:145], off
	v_lshl_add_u64 v[130:131], s[26:27], 0, v[70:71]
	s_mov_b32 m0, s36
	v_lshl_add_u64 v[146:147], s[20:21], 0, v[72:73]
	global_load_lds_dwordx4 v[130:131], off
	v_lshl_add_u64 v[130:131], s[26:27], 0, v[66:67]
	s_mov_b32 m0, s37
	v_lshl_add_u64 v[148:149], s[20:21], 0, v[68:69]
	global_load_lds_dwordx4 v[130:131], off
	s_mov_b32 m0, s35
	s_nop 0
	global_load_lds_dwordx4 v[146:147], off
	s_mov_b32 m0, s39
	s_nop 0
	global_load_lds_dwordx4 v[148:149], off
	s_waitcnt vmcnt(8)
	s_waitcnt lgkmcnt(0)
	s_barrier
	s_setprio 1
	s_waitcnt lgkmcnt(0)
	v_mfma_f32_16x16x32_bf16 v[98:101], v[10:13], v[26:29], v[98:101]
	v_mfma_f32_16x16x32_bf16 v[26:29], v[86:89], v[26:29], v[46:49]
	v_mfma_f32_16x16x32_bf16 v[46:49], v[90:93], v[30:33], v[26:29]
	v_mfma_f32_16x16x32_bf16 v[26:29], v[10:13], v[106:109], v[54:57]
	v_mfma_f32_16x16x32_bf16 v[54:57], v[14:17], v[110:113], v[26:29]
	v_mfma_f32_16x16x32_bf16 v[26:29], v[86:89], v[106:109], v[58:61]
	v_mfma_f32_16x16x32_bf16 v[106:109], v[90:93], v[110:113], v[26:29]
	v_mfma_f32_16x16x32_bf16 v[26:29], v[10:13], v[114:117], v[62:65]
	v_mfma_f32_16x16x32_bf16 v[2:5], v[10:13], v[122:125], v[2:5]
	v_mfma_f32_16x16x32_bf16 v[110:113], v[14:17], v[118:121], v[26:29]
	v_mfma_f32_16x16x32_bf16 v[26:29], v[86:89], v[114:117], v[82:85]
	v_mfma_f32_16x16x32_bf16 v[114:117], v[14:17], v[126:129], v[2:5]
	v_mfma_f32_16x16x32_bf16 v[2:5], v[86:89], v[122:125], v[6:9]
	v_mfma_f32_16x16x32_bf16 v[98:101], v[14:17], v[30:33], v[98:101]
	v_mfma_f32_16x16x32_bf16 v[82:85], v[90:93], v[118:121], v[26:29]
	v_mfma_f32_16x16x32_bf16 v[86:89], v[90:93], v[126:129], v[2:5]
	s_setprio 0
	s_setprio 1
	s_setprio 0
	s_barrier
	ds_read_b128 v[90:93], v81
	ds_read_b128 v[118:121], v81 offset:1024
	ds_read_b128 v[122:125], v81 offset:2048
	ds_read_b128 v[126:129], v81 offset:3072
	s_add_u32 s26, s20, 0x18000
	s_addc_u32 s27, s21, 0
	s_mov_b32 m0, s40
	v_lshl_add_u64 v[26:27], s[26:27], 0, v[72:73]
	ds_read_b128 v[2:5], v80 offset:32768
	ds_read_b128 v[6:9], v80 offset:33792
	ds_read_b128 v[10:13], v80 offset:34816
	ds_read_b128 v[14:17], v80 offset:35840
	ds_read_b128 v[58:61], v80 offset:36864
	ds_read_b128 v[62:65], v80 offset:37888
	ds_read_b128 v[130:133], v80 offset:38912
	ds_read_b128 v[134:137], v80 offset:39936
	global_load_lds_dwordx4 v[26:27], off
	v_lshl_add_u64 v[26:27], s[26:27], 0, v[68:69]
	s_mov_b32 m0, s41
	s_nop 0
	global_load_lds_dwordx4 v[26:27], off
	s_waitcnt vmcnt(8)
	s_waitcnt lgkmcnt(0)
	s_barrier
	s_setprio 1
	s_waitcnt lgkmcnt(0)
	v_mfma_f32_16x16x32_bf16 v[26:29], v[90:93], v[2:5], v[50:53]
	v_mfma_f32_16x16x32_bf16 v[2:5], v[122:125], v[2:5], v[18:21]
	v_mfma_f32_16x16x32_bf16 v[30:33], v[126:129], v[6:9], v[2:5]
	v_mfma_f32_16x16x32_bf16 v[2:5], v[90:93], v[10:13], v[22:25]
	v_mfma_f32_16x16x32_bf16 v[18:21], v[118:121], v[14:17], v[2:5]
	v_mfma_f32_16x16x32_bf16 v[2:5], v[122:125], v[10:13], v[94:97]
	v_mfma_f32_16x16x32_bf16 v[22:25], v[126:129], v[14:17], v[2:5]
	v_mfma_f32_16x16x32_bf16 v[2:5], v[90:93], v[58:61], v[102:105]
	v_mfma_f32_16x16x32_bf16 v[10:13], v[118:121], v[62:65], v[2:5]
	v_mfma_f32_16x16x32_bf16 v[2:5], v[122:125], v[58:61], v[34:37]
	v_mfma_f32_16x16x32_bf16 v[26:29], v[118:121], v[6:9], v[26:29]
	v_mfma_f32_16x16x32_bf16 v[14:17], v[126:129], v[62:65], v[2:5]
	v_mfma_f32_16x16x32_bf16 v[2:5], v[90:93], v[130:133], v[38:41]
	v_mfma_f32_16x16x32_bf16 v[6:9], v[122:125], v[130:133], v[42:45]
	v_mfma_f32_16x16x32_bf16 v[2:5], v[118:121], v[134:137], v[2:5]
	v_mfma_f32_16x16x32_bf16 v[6:9], v[126:129], v[134:137], v[6:9]
	s_setprio 0
	s_setprio 1
	s_setprio 0
	s_barrier
	s_mov_b32 m0, s52
	v_lshl_add_u64 v[50:51], v[142:143], 0, s[12:13]
	s_add_u32 s26, s22, 0x10080
	ds_read_b128 v[34:37], v80 offset:49152
	ds_read_b128 v[38:41], v80 offset:50176
	ds_read_b128 v[42:45], v80 offset:51200
	ds_read_b128 v[94:97], v80 offset:52224
	ds_read_b128 v[102:105], v80 offset:53248
	ds_read_b128 v[130:133], v80 offset:54272
	ds_read_b128 v[134:137], v80 offset:55296
	ds_read_b128 v[138:141], v80 offset:56320
	global_load_lds_dwordx4 v[50:51], off
	v_lshl_add_u64 v[50:51], v[144:145], 0, s[12:13]
	s_mov_b32 m0, s53
	s_addc_u32 s27, s23, 0
	global_load_lds_dwordx4 v[50:51], off
	v_lshl_add_u64 v[50:51], s[26:27], 0, v[70:71]
	s_mov_b32 m0, s44
	s_nop 0
	global_load_lds_dwordx4 v[50:51], off
	v_lshl_add_u64 v[50:51], s[26:27], 0, v[66:67]
	s_mov_b32 m0, s45
	s_nop 0
	global_load_lds_dwordx4 v[50:51], off
	v_lshl_add_u64 v[50:51], v[146:147], 0, s[12:13]
	s_mov_b32 m0, s42
	s_nop 0
	global_load_lds_dwordx4 v[50:51], off
	v_lshl_add_u64 v[50:51], v[148:149], 0, s[12:13]
	s_mov_b32 m0, s43
	s_nop 0
	global_load_lds_dwordx4 v[50:51], off
	s_waitcnt vmcnt(8)
	s_waitcnt lgkmcnt(0)
	s_barrier
	s_setprio 1
	s_waitcnt lgkmcnt(0)
	v_mfma_f32_16x16x32_bf16 v[50:53], v[90:93], v[34:37], v[98:101]
	v_mfma_f32_16x16x32_bf16 v[34:37], v[122:125], v[34:37], v[46:49]
	v_mfma_f32_16x16x32_bf16 v[62:65], v[126:129], v[38:41], v[34:37]
	v_mfma_f32_16x16x32_bf16 v[34:37], v[90:93], v[42:45], v[54:57]
	v_mfma_f32_16x16x32_bf16 v[58:61], v[118:121], v[38:41], v[50:53]
	v_mfma_f32_16x16x32_bf16 v[50:53], v[118:121], v[94:97], v[34:37]
	v_mfma_f32_16x16x32_bf16 v[34:37], v[122:125], v[42:45], v[106:109]
	v_mfma_f32_16x16x32_bf16 v[54:57], v[126:129], v[94:97], v[34:37]
	v_mfma_f32_16x16x32_bf16 v[34:37], v[90:93], v[102:105], v[110:113]
	v_mfma_f32_16x16x32_bf16 v[42:45], v[118:121], v[130:133], v[34:37]
	v_mfma_f32_16x16x32_bf16 v[34:37], v[122:125], v[102:105], v[82:85]
	v_mfma_f32_16x16x32_bf16 v[46:49], v[126:129], v[130:133], v[34:37]
	v_mfma_f32_16x16x32_bf16 v[34:37], v[90:93], v[134:137], v[114:117]
	v_mfma_f32_16x16x32_bf16 v[38:41], v[122:125], v[134:137], v[86:89]
	v_mfma_f32_16x16x32_bf16 v[34:37], v[118:121], v[138:141], v[34:37]
	v_mfma_f32_16x16x32_bf16 v[38:41], v[126:129], v[138:141], v[38:41]
	s_setprio 0
	s_setprio 1
	s_setprio 0
	s_barrier
	s_and_b64 vcc, exec, s[0:1]
	s_cbranch_vccnz .LBB0_630
	s_barrier

; #define PG8_STAGE(bufoff, gbase, voff) do { _Pragma("unroll") for (int _i = 0; _i < 2; ++_i) \
;         __builtin_amdgcn_global_load_lds((const unsigned*)((const char*)(gbase) + (voff)[_i]), (PG8_LAS unsigned*)(lds + (bufoff) + ldsw + _i * 8192), 16, 0, 0); } while (0)
; #define PG8_LDA(dst, b, h) do { _Pragma("unroll") for (int m = 0; m < 4; ++m) _Pragma("unroll") for (int k = 0; k < 2; ++k) dst[m][k] = *(const PG8_LAS bf16x8*)(lds + PG8_SA(b, h) + aoff + m * 2048 + k * 1024); } while (0)
; #define PG8_LDB(dst, b, h) do { _Pragma("unroll") for (int n = 0; n < 2; ++n) _Pragma("unroll") for (int k = 0; k < 2; ++k) dst[n][k] = *(const PG8_LAS bf16x8*)(lds + PG8_SB(b, h) + boff + n * 2048 + k * 1024); } while (0)
; #define PG8_MMA(ai, bj, At, Bt) do { __builtin_amdgcn_s_setprio(1); _Pragma("unroll") for (int m = 0; m < 4; ++m) _Pragma("unroll") for (int n = 0; n < 2; ++n) _Pragma("unroll") for (int k = 0; k < 2; ++k) \
;         acc[ai][bj][m][n] = __builtin_amdgcn_mfma_f32_16x16x32_bf16(Bt[n][k], At[m][k], acc[ai][bj][m][n], 0, 0, 0); __builtin_amdgcn_s_setprio(0); } while (0)
; #define PG8_WAIT_V(n) asm volatile("s_waitcnt vmcnt(" #n ")" ::: "memory")
; #define PG8_WAIT_L(n) asm volatile("s_waitcnt lgkmcnt(" #n ")" ::: "memory")
; #define PG8_BAR __builtin_amdgcn_s_barrier()
; #define PG8_SCHED __builtin_amdgcn_sched_barrier(0)
; template <class Epi, class Sched, bool ALIGN_EPI>
; __device__ __forceinline__ void gemm_phase(PG8_LAS unsigned char* lds, const Gemm g, const Sched& S, const Epi& E) {
;     ...
;             PG8_LDB(B0, 0, 0); PG8_LDB(B1, 0, 1); PG8_SCHED; PG8_LDA(At, 0, 0); PG8_STAGE(PG8_SA(1, 1), a1 + hstepA, voffA);
;             PG8_WAIT_V(8); PG8_WAIT_L(0); PG8_BAR; PG8_MMA(0, 0, At, B0); PG8_MMA(0, 1, At, B1); PG8_BAR; PG8_SCHED;
;             PG8_LDA(At, 0, 1); PG8_STAGE(PG8_SB(0, 0), b2, voffB); PG8_STAGE(PG8_SB(0, 1), b2 + hstepB, voffB); PG8_STAGE(PG8_SA(0, 0), a2, voffA);
;             PG8_WAIT_V(8); PG8_WAIT_L(0); PG8_BAR; PG8_MMA(1, 0, At, B0); PG8_MMA(1, 1, At, B1); PG8_BAR; PG8_SCHED;
.LBB0_648:
	ds_read_b128 v[12:15], v146
	ds_read_b128 v[16:19], v146 offset:1024
	ds_read_b128 v[20:23], v146 offset:2048
	ds_read_b128 v[24:27], v146 offset:3072
	ds_read_b128 v[28:31], v147
	ds_read_b128 v[32:35], v147 offset:1024
	ds_read_b128 v[36:39], v147 offset:2048
	ds_read_b128 v[40:43], v147 offset:3072
	s_add_u32 s24, s36, s24
	s_addc_u32 s25, s37, s25
	s_and_b64 s[4:5], s[26:27], exec
	s_cselect_b32 s4, 0, 0x200
	s_add_u32 s26, s34, s4
	s_addc_u32 s27, s35, 0
	s_add_u32 s4, s28, 0x18080
	s_addc_u32 s5, s29, 0
	s_mov_b32 m0, s51
	v_lshl_add_u64 v[68:69], s[4:5], 0, v[138:139]
	ds_read_b128 v[4:7], v3
	ds_read_b128 v[8:11], v3 offset:1024
	ds_read_b128 v[44:47], v3 offset:2048
	ds_read_b128 v[48:51], v3 offset:3072
	ds_read_b128 v[52:55], v3 offset:4096
	ds_read_b128 v[56:59], v3 offset:5120
	ds_read_b128 v[60:63], v3 offset:6144
	ds_read_b128 v[64:67], v3 offset:7168
	global_load_lds_dwordx4 v[68:69], off
	v_lshl_add_u64 v[68:69], s[4:5], 0, v[134:135]
	s_mov_b32 m0, s52
	s_nop 0
	global_load_lds_dwordx4 v[68:69], off
	s_waitcnt vmcnt(8)
	s_waitcnt lgkmcnt(0)
	s_barrier
	s_setprio 1
	s_waitcnt lgkmcnt(0)
	v_mfma_f32_16x16x32_bf16 v[68:71], v[12:15], v[4:7], 0
	v_mfma_f32_16x16x32_bf16 v[72:75], v[20:23], v[4:7], 0
	v_mfma_f32_16x16x32_bf16 v[76:79], v[12:15], v[44:47], 0
	v_mfma_f32_16x16x32_bf16 v[80:83], v[20:23], v[44:47], 0
	v_mfma_f32_16x16x32_bf16 v[84:87], v[12:15], v[52:55], 0
	v_mfma_f32_16x16x32_bf16 v[88:91], v[20:23], v[52:55], 0
	v_mfma_f32_16x16x32_bf16 v[92:95], v[12:15], v[60:63], 0
	v_mfma_f32_16x16x32_bf16 v[96:99], v[20:23], v[60:63], 0
	v_mfma_f32_16x16x32_bf16 v[68:71], v[16:19], v[8:11], v[68:71]
	v_mfma_f32_16x16x32_bf16 v[72:75], v[24:27], v[8:11], v[72:75]
	v_mfma_f32_16x16x32_bf16 v[76:79], v[16:19], v[48:51], v[76:79]
	v_mfma_f32_16x16x32_bf16 v[80:83], v[24:27], v[48:51], v[80:83]
	v_mfma_f32_16x16x32_bf16 v[84:87], v[16:19], v[56:59], v[84:87]
	v_mfma_f32_16x16x32_bf16 v[88:91], v[24:27], v[56:59], v[88:91]
	v_mfma_f32_16x16x32_bf16 v[92:95], v[16:19], v[64:67], v[92:95]
	v_mfma_f32_16x16x32_bf16 v[96:99], v[24:27], v[64:67], v[96:99]
	s_setprio 0
	s_setprio 1
	v_mfma_f32_16x16x32_bf16 v[100:103], v[28:31], v[4:7], 0
	v_mfma_f32_16x16x32_bf16 v[4:7], v[36:39], v[4:7], 0
	v_mfma_f32_16x16x32_bf16 v[104:107], v[40:43], v[8:11], v[4:7]
	v_mfma_f32_16x16x32_bf16 v[4:7], v[28:31], v[44:47], 0
	v_mfma_f32_16x16x32_bf16 v[108:111], v[32:35], v[48:51], v[4:7]
	v_mfma_f32_16x16x32_bf16 v[4:7], v[36:39], v[44:47], 0
	v_mfma_f32_16x16x32_bf16 v[44:47], v[40:43], v[48:51], v[4:7]
	v_mfma_f32_16x16x32_bf16 v[4:7], v[28:31], v[52:55], 0
	v_mfma_f32_16x16x32_bf16 v[48:51], v[32:35], v[56:59], v[4:7]
	v_mfma_f32_16x16x32_bf16 v[4:7], v[36:39], v[52:55], 0
	v_mfma_f32_16x16x32_bf16 v[52:55], v[40:43], v[56:59], v[4:7]
	v_mfma_f32_16x16x32_bf16 v[4:7], v[28:31], v[60:63], 0
	v_mfma_f32_16x16x32_bf16 v[56:59], v[32:35], v[64:67], v[4:7]
	v_mfma_f32_16x16x32_bf16 v[4:7], v[36:39], v[60:63], 0
	v_mfma_f32_16x16x32_bf16 v[100:103], v[32:35], v[8:11], v[100:103]
	v_mfma_f32_16x16x32_bf16 v[60:63], v[40:43], v[64:67], v[4:7]
	s_setprio 0
	s_barrier
	s_nop 3
	v_lshl_add_u64 v[4:5], s[30:31], 0, v[136:137]
	s_mov_b32 m0, s53
	v_lshl_add_u64 v[6:7], v[4:5], 0, s[16:17]
	ds_read_b128 v[64:67], v3 offset:16384
	ds_read_b128 v[112:115], v3 offset:17408
	ds_read_b128 v[116:119], v3 offset:18432
	ds_read_b128 v[120:123], v3 offset:19456
	ds_read_b128 v[124:127], v3 offset:20480
	ds_read_b128 v[128:131], v3 offset:21504
	ds_read_b128 v[150:153], v3 offset:22528
	ds_read_b128 v[154:157], v3 offset:23552
	global_load_lds_dwordx4 v[6:7], off
	v_lshl_add_u64 v[6:7], s[30:31], 0, v[132:133]
	s_add_u32 s4, s30, 0x18100
	v_lshl_add_u64 v[8:9], v[6:7], 0, s[16:17]
	s_mov_b32 m0, s57
	s_addc_u32 s5, s31, 0
	global_load_lds_dwordx4 v[8:9], off
	v_lshl_add_u64 v[8:9], s[4:5], 0, v[136:137]
	s_mov_b32 m0, s58
	s_nop 0
	global_load_lds_dwordx4 v[8:9], off
	v_lshl_add_u64 v[8:9], s[4:5], 0, v[132:133]
	s_mov_b32 m0, s59
	s_nop 0
	global_load_lds_dwordx4 v[8:9], off
	v_lshl_add_u64 v[8:9], s[28:29], 0, v[138:139]
	v_lshl_add_u64 v[10:11], v[8:9], 0, s[16:17]
	s_mov_b32 m0, s42
	s_nop 0
	global_load_lds_dwordx4 v[10:11], off
	v_lshl_add_u64 v[10:11], s[28:29], 0, v[134:135]
	v_lshl_add_u64 v[158:159], v[10:11], 0, s[16:17]
	s_mov_b32 m0, s43
	s_nop 0
	global_load_lds_dwordx4 v[158:159], off
	s_waitcnt vmcnt(8)
	s_waitcnt lgkmcnt(0)
	s_barrier
	s_setprio 1
	s_waitcnt lgkmcnt(0)
	v_mfma_f32_16x16x32_bf16 v[158:161], v[12:15], v[64:67], 0
	v_mfma_f32_16x16x32_bf16 v[166:169], v[12:15], v[116:119], 0
	v_mfma_f32_16x16x32_bf16 v[174:177], v[12:15], v[124:127], 0
	v_mfma_f32_16x16x32_bf16 v[12:15], v[12:15], v[150:153], 0
	v_mfma_f32_16x16x32_bf16 v[158:161], v[16:19], v[112:115], v[158:161]
	v_mfma_f32_16x16x32_bf16 v[166:169], v[16:19], v[120:123], v[166:169]
	v_mfma_f32_16x16x32_bf16 v[174:177], v[16:19], v[128:131], v[174:177]
	v_mfma_f32_16x16x32_bf16 v[12:15], v[16:19], v[154:157], v[12:15]
	v_mfma_f32_16x16x32_bf16 v[16:19], v[20:23], v[150:153], 0
	v_mfma_f32_16x16x32_bf16 v[162:165], v[20:23], v[64:67], 0
	v_mfma_f32_16x16x32_bf16 v[170:173], v[20:23], v[116:119], 0
	v_mfma_f32_16x16x32_bf16 v[178:181], v[20:23], v[124:127], 0
	v_mfma_f32_16x16x32_bf16 v[16:19], v[24:27], v[154:157], v[16:19]
	v_mfma_f32_16x16x32_bf16 v[162:165], v[24:27], v[112:115], v[162:165]
	v_mfma_f32_16x16x32_bf16 v[170:173], v[24:27], v[120:123], v[170:173]
	v_mfma_f32_16x16x32_bf16 v[178:181], v[24:27], v[128:131], v[178:181]
	s_setprio 0
	s_setprio 1
	v_mfma_f32_16x16x32_bf16 v[20:23], v[28:31], v[64:67], 0
	v_mfma_f32_16x16x32_bf16 v[24:27], v[36:39], v[64:67], 0
	v_mfma_f32_16x16x32_bf16 v[20:23], v[32:35], v[112:115], v[20:23]
	v_mfma_f32_16x16x32_bf16 v[24:27], v[40:43], v[112:115], v[24:27]
	v_mfma_f32_16x16x32_bf16 v[64:67], v[28:31], v[116:119], 0
	v_mfma_f32_16x16x32_bf16 v[112:115], v[36:39], v[116:119], 0
	v_mfma_f32_16x16x32_bf16 v[116:119], v[28:31], v[124:127], 0
	v_mfma_f32_16x16x32_bf16 v[28:31], v[28:31], v[150:153], 0
	v_mfma_f32_16x16x32_bf16 v[64:67], v[32:35], v[120:123], v[64:67]
	v_mfma_f32_16x16x32_bf16 v[112:115], v[40:43], v[120:123], v[112:115]
	v_mfma_f32_16x16x32_bf16 v[116:119], v[32:35], v[128:131], v[116:119]
	v_mfma_f32_16x16x32_bf16 v[120:123], v[36:39], v[124:127], 0
	v_mfma_f32_16x16x32_bf16 v[28:31], v[32:35], v[154:157], v[28:31]
	v_mfma_f32_16x16x32_bf16 v[32:35], v[36:39], v[150:153], 0
	v_mfma_f32_16x16x32_bf16 v[120:123], v[40:43], v[128:131], v[120:123]
	v_mfma_f32_16x16x32_bf16 v[32:35], v[40:43], v[154:157], v[32:35]
	s_setprio 0
	s_barrier
; #define PG8_STAGE(bufoff, gbase, voff) do { _Pragma("unroll") for (int _i = 0; _i < 2; ++_i) \
;         __builtin_amdgcn_global_load_lds((const unsigned*)((const char*)(gbase) + (voff)[_i]), (PG8_LAS unsigned*)(lds + (bufoff) + ldsw + _i * 8192), 16, 0, 0); } while (0)
; #define PG8_LDA(dst, b, h) do { _Pragma("unroll") for (int m = 0; m < 4; ++m) _Pragma("unroll") for (int k = 0; k < 2; ++k) dst[m][k] = *(const PG8_LAS bf16x8*)(lds + PG8_SA(b, h) + aoff + m * 2048 + k * 1024); } while (0)
; #define PG8_LDB(dst, b, h) do { _Pragma("unroll") for (int n = 0; n < 2; ++n) _Pragma("unroll") for (int k = 0; k < 2; ++k) dst[n][k] = *(const PG8_LAS bf16x8*)(lds + PG8_SB(b, h) + boff + n * 2048 + k * 1024); } while (0)
; #define PG8_MMA(ai, bj, At, Bt) do { __builtin_amdgcn_s_setprio(1); _Pragma("unroll") for (int m = 0; m < 4; ++m) _Pragma("unroll") for (int n = 0; n < 2; ++n) _Pragma("unroll") for (int k = 0; k < 2; ++k) \
;         acc[ai][bj][m][n] = __builtin_amdgcn_mfma_f32_16x16x32_bf16(Bt[n][k], At[m][k], acc[ai][bj][m][n], 0, 0, 0); __builtin_amdgcn_s_setprio(0); } while (0)
; #define PG8_WAIT_V(n) asm volatile("s_waitcnt vmcnt(" #n ")" ::: "memory")
; #define PG8_WAIT_L(n) asm volatile("s_waitcnt lgkmcnt(" #n ")" ::: "memory")
; #define PG8_BAR __builtin_amdgcn_s_barrier()
; #define PG8_SCHED __builtin_amdgcn_sched_barrier(0)
; template <class Epi, class Sched, bool ALIGN_EPI>
; __device__ __forceinline__ void gemm_phase(PG8_LAS unsigned char* lds, const Gemm g, const Sched& S, const Epi& E) {
;     ...
;             PG8_LDB(B0, 1, 0); PG8_LDB(B1, 1, 1); PG8_SCHED; PG8_LDA(At, 1, 0); PG8_STAGE(PG8_SA(0, 1), a2 + hstepA, voffA);
;             PG8_WAIT_V(8); PG8_WAIT_L(0); PG8_BAR; PG8_MMA(0, 0, At, B0); PG8_MMA(0, 1, At, B1); PG8_BAR; PG8_SCHED;
;             PG8_LDA(At, 1, 1); PG8_STAGE(PG8_SB(1, 0), b3, voffB); PG8_STAGE(PG8_SB(1, 1), b3 + hstepB, voffB); PG8_STAGE(PG8_SA(1, 0), a3, voffA);
	ds_read_b128 v[36:39], v148
	ds_read_b128 v[40:43], v148 offset:1024
	ds_read_b128 v[124:127], v148 offset:2048
	ds_read_b128 v[128:131], v148 offset:3072
	ds_read_b128 v[150:153], v149
	ds_read_b128 v[154:157], v149 offset:1024
	ds_read_b128 v[182:185], v149 offset:2048
	ds_read_b128 v[186:189], v149 offset:3072
	s_add_u32 s4, s28, 0x18100
	s_addc_u32 s5, s29, 0
	s_mov_b32 m0, s44
	v_lshl_add_u64 v[222:223], s[4:5], 0, v[138:139]
	ds_read_b128 v[190:193], v3 offset:32768
	ds_read_b128 v[194:197], v3 offset:33792
	ds_read_b128 v[198:201], v3 offset:34816
	ds_read_b128 v[202:205], v3 offset:35840
	ds_read_b128 v[206:209], v3 offset:36864
	ds_read_b128 v[210:213], v3 offset:37888
	ds_read_b128 v[214:217], v3 offset:38912
	ds_read_b128 v[218:221], v3 offset:39936
	global_load_lds_dwordx4 v[222:223], off
	v_lshl_add_u64 v[222:223], s[4:5], 0, v[134:135]
	s_mov_b32 m0, s45
	s_nop 0
	global_load_lds_dwordx4 v[222:223], off
	s_waitcnt vmcnt(8)
	s_waitcnt lgkmcnt(0)
	s_barrier
	s_setprio 1
	s_waitcnt lgkmcnt(0)
	v_mfma_f32_16x16x32_bf16 v[68:71], v[36:39], v[190:193], v[68:71]
	v_mfma_f32_16x16x32_bf16 v[68:71], v[40:43], v[194:197], v[68:71]
	v_mfma_f32_16x16x32_bf16 v[72:75], v[128:131], v[194:197], v[72:75]
	v_mfma_f32_16x16x32_bf16 v[72:75], v[124:127], v[190:193], v[72:75]
	v_mfma_f32_16x16x32_bf16 v[80:83], v[124:127], v[198:201], v[80:83]
	v_mfma_f32_16x16x32_bf16 v[80:83], v[128:131], v[202:205], v[80:83]
	v_mfma_f32_16x16x32_bf16 v[76:79], v[40:43], v[202:205], v[76:79]
	v_mfma_f32_16x16x32_bf16 v[76:79], v[36:39], v[198:201], v[76:79]
	v_mfma_f32_16x16x32_bf16 v[84:87], v[36:39], v[206:209], v[84:87]
	v_mfma_f32_16x16x32_bf16 v[84:87], v[40:43], v[210:213], v[84:87]
	v_mfma_f32_16x16x32_bf16 v[88:91], v[128:131], v[210:213], v[88:91]
	v_mfma_f32_16x16x32_bf16 v[88:91], v[124:127], v[206:209], v[88:91]
	v_mfma_f32_16x16x32_bf16 v[96:99], v[124:127], v[214:217], v[96:99]
	v_mfma_f32_16x16x32_bf16 v[96:99], v[128:131], v[218:221], v[96:99]
	v_mfma_f32_16x16x32_bf16 v[92:95], v[40:43], v[218:221], v[92:95]
	v_mfma_f32_16x16x32_bf16 v[92:95], v[36:39], v[214:217], v[92:95]
	s_setprio 0
	s_setprio 1
	v_mfma_f32_16x16x32_bf16 v[100:103], v[150:153], v[190:193], v[100:103]
	v_mfma_f32_16x16x32_bf16 v[100:103], v[154:157], v[194:197], v[100:103]
	v_mfma_f32_16x16x32_bf16 v[104:107], v[186:189], v[194:197], v[104:107]
	v_mfma_f32_16x16x32_bf16 v[104:107], v[182:185], v[190:193], v[104:107]
	v_mfma_f32_16x16x32_bf16 v[44:47], v[182:185], v[198:201], v[44:47]
	v_mfma_f32_16x16x32_bf16 v[44:47], v[186:189], v[202:205], v[44:47]
	v_mfma_f32_16x16x32_bf16 v[108:111], v[154:157], v[202:205], v[108:111]
	v_mfma_f32_16x16x32_bf16 v[108:111], v[150:153], v[198:201], v[108:111]
	v_mfma_f32_16x16x32_bf16 v[48:51], v[150:153], v[206:209], v[48:51]
	v_mfma_f32_16x16x32_bf16 v[48:51], v[154:157], v[210:213], v[48:51]
	v_mfma_f32_16x16x32_bf16 v[52:55], v[186:189], v[210:213], v[52:55]
	v_mfma_f32_16x16x32_bf16 v[52:55], v[182:185], v[206:209], v[52:55]
	v_mfma_f32_16x16x32_bf16 v[60:63], v[182:185], v[214:217], v[60:63]
	v_mfma_f32_16x16x32_bf16 v[60:63], v[186:189], v[218:221], v[60:63]
	v_mfma_f32_16x16x32_bf16 v[56:59], v[154:157], v[218:221], v[56:59]
	v_mfma_f32_16x16x32_bf16 v[56:59], v[150:153], v[214:217], v[56:59]
	s_setprio 0
	s_barrier
	s_add_i32 s4, s61, 0x2000
	s_mov_b32 m0, s61
	v_lshl_add_u64 v[222:223], v[4:5], 0, s[18:19]
	s_add_u32 s34, s30, 0x18180
	ds_read_b128 v[190:193], v3 offset:49152
	ds_read_b128 v[194:197], v3 offset:50176
	ds_read_b128 v[198:201], v3 offset:51200
	ds_read_b128 v[202:205], v3 offset:52224
	ds_read_b128 v[206:209], v3 offset:53248
	ds_read_b128 v[210:213], v3 offset:54272
	ds_read_b128 v[214:217], v3 offset:55296
	ds_read_b128 v[218:221], v3 offset:56320
	global_load_lds_dwordx4 v[222:223], off
	v_lshl_add_u64 v[222:223], v[6:7], 0, s[18:19]
	s_mov_b32 m0, s4
	s_addc_u32 s35, s31, 0
	s_add_i32 s5, s60, s41
	global_load_lds_dwordx4 v[222:223], off
	v_lshl_add_u64 v[222:223], s[34:35], 0, v[136:137]
	s_mov_b32 m0, s5
	s_add_i32 s7, s5, 0x2000
	global_load_lds_dwordx4 v[222:223], off
	v_lshl_add_u64 v[222:223], s[34:35], 0, v[132:133]
	s_mov_b32 m0, s7
	s_nop 0
	global_load_lds_dwordx4 v[222:223], off
	v_lshl_add_u64 v[222:223], v[8:9], 0, s[18:19]
	s_mov_b32 m0, s47
	s_nop 0
	global_load_lds_dwordx4 v[222:223], off
	v_lshl_add_u64 v[222:223], v[10:11], 0, s[18:19]
	s_mov_b32 m0, s48
	s_nop 0
	global_load_lds_dwordx4 v[222:223], off
	s_waitcnt vmcnt(8)
	s_waitcnt lgkmcnt(0)
	s_barrier
; #define PG8_STAGE(bufoff, gbase, voff) do { _Pragma("unroll") for (int _i = 0; _i < 2; ++_i) \
;         __builtin_amdgcn_global_load_lds((const unsigned*)((const char*)(gbase) + (voff)[_i]), (PG8_LAS unsigned*)(lds + (bufoff) + ldsw + _i * 8192), 16, 0, 0); } while (0)
; #define PG8_LDA(dst, b, h) do { _Pragma("unroll") for (int m = 0; m < 4; ++m) _Pragma("unroll") for (int k = 0; k < 2; ++k) dst[m][k] = *(const PG8_LAS bf16x8*)(lds + PG8_SA(b, h) + aoff + m * 2048 + k * 1024); } while (0)
; #define PG8_LDB(dst, b, h) do { _Pragma("unroll") for (int n = 0; n < 2; ++n) _Pragma("unroll") for (int k = 0; k < 2; ++k) dst[n][k] = *(const PG8_LAS bf16x8*)(lds + PG8_SB(b, h) + boff + n * 2048 + k * 1024); } while (0)
; #define PG8_MMA(ai, bj, At, Bt) do { __builtin_amdgcn_s_setprio(1); _Pragma("unroll") for (int m = 0; m < 4; ++m) _Pragma("unroll") for (int n = 0; n < 2; ++n) _Pragma("unroll") for (int k = 0; k < 2; ++k) \
;         acc[ai][bj][m][n] = __builtin_amdgcn_mfma_f32_16x16x32_bf16(Bt[n][k], At[m][k], acc[ai][bj][m][n], 0, 0, 0); __builtin_amdgcn_s_setprio(0); } while (0)
; #define PG8_WAIT_V(n) asm volatile("s_waitcnt vmcnt(" #n ")" ::: "memory")
; template <class Epi, class Sched, bool ALIGN_EPI>
; __device__ __forceinline__ void gemm_phase(PG8_LAS unsigned char* lds, const Gemm g, const Sched& S, const Epi& E) {
;     ...
;             PG8_LDB(B0, 0, 0); PG8_LDB(B1, 0, 1); PG8_SCHED; PG8_LDA(At, 0, 0); PG8_STAGE(PG8_SA(1, 1), a1 + hstepA, voffA);
;             PG8_WAIT_V(8); PG8_WAIT_L(0); PG8_BAR; PG8_MMA(0, 0, At, B0); PG8_MMA(0, 1, At, B1); PG8_BAR; PG8_SCHED;
;             PG8_LDA(At, 0, 1); PG8_STAGE(PG8_SB(0, 0), b2, voffB); PG8_STAGE(PG8_SB(0, 1), b2 + hstepB, voffB); PG8_STAGE(PG8_SA(0, 0), a2, voffA);
;             PG8_WAIT_V(8); PG8_WAIT_L(0); PG8_BAR; PG8_MMA(1, 0, At, B0); PG8_MMA(1, 1, At, B1); PG8_BAR; PG8_SCHED;
;             PG8_LDB(B0, 1, 0); PG8_LDB(B1, 1, 1); PG8_SCHED; PG8_LDA(At, 1, 0); PG8_STAGE(PG8_SA(0, 1), a2 + hstepA, voffA);
;             PG8_WAIT_V(8); PG8_WAIT_L(0); PG8_BAR; PG8_MMA(0, 0, At, B0); PG8_MMA(0, 1, At, B1); PG8_BAR; PG8_SCHED;
;             PG8_LDA(At, 1, 1); PG8_STAGE(PG8_SB(1, 0), b3, voffB); PG8_STAGE(PG8_SB(1, 1), b3 + hstepB, voffB); PG8_STAGE(PG8_SA(1, 0), a3, voffA);
;             PG8_WAIT_V(8); PG8_WAIT_L(0); PG8_BAR; PG8_MMA(1, 0, At, B0); PG8_MMA(1, 1, At, B1); PG8_BAR; PG8_SCHED;
	s_setprio 1
	s_waitcnt lgkmcnt(0)
	v_mfma_f32_16x16x32_bf16 v[12:15], v[36:39], v[214:217], v[12:15]
	v_mfma_f32_16x16x32_bf16 v[12:15], v[40:43], v[218:221], v[12:15]
	v_mfma_f32_16x16x32_bf16 v[16:19], v[128:131], v[218:221], v[16:19]
	v_mfma_f32_16x16x32_bf16 v[16:19], v[124:127], v[214:217], v[16:19]
	v_mfma_f32_16x16x32_bf16 v[162:165], v[124:127], v[190:193], v[162:165]
	v_mfma_f32_16x16x32_bf16 v[162:165], v[128:131], v[194:197], v[162:165]
	v_mfma_f32_16x16x32_bf16 v[158:161], v[40:43], v[194:197], v[158:161]
	v_mfma_f32_16x16x32_bf16 v[158:161], v[36:39], v[190:193], v[158:161]
	v_mfma_f32_16x16x32_bf16 v[166:169], v[36:39], v[198:201], v[166:169]
	v_mfma_f32_16x16x32_bf16 v[166:169], v[40:43], v[202:205], v[166:169]
	v_mfma_f32_16x16x32_bf16 v[170:173], v[128:131], v[202:205], v[170:173]
	v_mfma_f32_16x16x32_bf16 v[170:173], v[124:127], v[198:201], v[170:173]
	v_mfma_f32_16x16x32_bf16 v[178:181], v[124:127], v[206:209], v[178:181]
	v_mfma_f32_16x16x32_bf16 v[178:181], v[128:131], v[210:213], v[178:181]
	v_mfma_f32_16x16x32_bf16 v[174:177], v[40:43], v[210:213], v[174:177]
	v_mfma_f32_16x16x32_bf16 v[174:177], v[36:39], v[206:209], v[174:177]
	s_setprio 0
	s_setprio 1
	v_mfma_f32_16x16x32_bf16 v[20:23], v[150:153], v[190:193], v[20:23]
	v_mfma_f32_16x16x32_bf16 v[24:27], v[182:185], v[190:193], v[24:27]
	v_mfma_f32_16x16x32_bf16 v[36:39], v[150:153], v[198:201], v[64:67]
	v_mfma_f32_16x16x32_bf16 v[40:43], v[182:185], v[198:201], v[112:115]
	v_mfma_f32_16x16x32_bf16 v[64:67], v[150:153], v[206:209], v[116:119]
	v_mfma_f32_16x16x32_bf16 v[112:115], v[182:185], v[206:209], v[120:123]
	v_mfma_f32_16x16x32_bf16 v[28:31], v[150:153], v[214:217], v[28:31]
	v_mfma_f32_16x16x32_bf16 v[32:35], v[182:185], v[214:217], v[32:35]
	v_mfma_f32_16x16x32_bf16 v[20:23], v[154:157], v[194:197], v[20:23]
	v_mfma_f32_16x16x32_bf16 v[24:27], v[186:189], v[194:197], v[24:27]
	v_mfma_f32_16x16x32_bf16 v[36:39], v[154:157], v[202:205], v[36:39]
	v_mfma_f32_16x16x32_bf16 v[40:43], v[186:189], v[202:205], v[40:43]
	v_mfma_f32_16x16x32_bf16 v[64:67], v[154:157], v[210:213], v[64:67]
	v_mfma_f32_16x16x32_bf16 v[112:115], v[186:189], v[210:213], v[112:115]
	v_mfma_f32_16x16x32_bf16 v[28:31], v[154:157], v[218:221], v[28:31]
	v_mfma_f32_16x16x32_bf16 v[32:35], v[186:189], v[218:221], v[32:35]
	s_setprio 0
	s_barrier
	ds_read_b128 v[116:119], v146
	ds_read_b128 v[120:123], v146 offset:1024
	ds_read_b128 v[124:127], v146 offset:2048
	ds_read_b128 v[128:131], v146 offset:3072
	ds_read_b128 v[150:153], v147
	ds_read_b128 v[154:157], v147 offset:1024
	ds_read_b128 v[182:185], v147 offset:2048
	ds_read_b128 v[186:189], v147 offset:3072
	s_add_u32 s34, s28, 0x18180
	s_addc_u32 s35, s29, 0
	s_mov_b32 m0, s51
	v_lshl_add_u64 v[222:223], s[34:35], 0, v[138:139]
	ds_read_b128 v[190:193], v3
	ds_read_b128 v[194:197], v3 offset:1024
	ds_read_b128 v[198:201], v3 offset:2048
	ds_read_b128 v[202:205], v3 offset:3072
	ds_read_b128 v[206:209], v3 offset:4096
	ds_read_b128 v[210:213], v3 offset:5120
	ds_read_b128 v[214:217], v3 offset:6144
	ds_read_b128 v[218:221], v3 offset:7168
	global_load_lds_dwordx4 v[222:223], off
	v_lshl_add_u64 v[222:223], s[34:35], 0, v[134:135]
	s_mov_b32 m0, s52
	s_nop 0
	global_load_lds_dwordx4 v[222:223], off
	s_waitcnt vmcnt(8)
	s_waitcnt lgkmcnt(0)
	s_barrier
	s_setprio 1
	s_waitcnt lgkmcnt(0)
	v_mfma_f32_16x16x32_bf16 v[68:71], v[116:119], v[190:193], v[68:71]
	v_mfma_f32_16x16x32_bf16 v[68:71], v[120:123], v[194:197], v[68:71]
	v_mfma_f32_16x16x32_bf16 v[72:75], v[128:131], v[194:197], v[72:75]
	v_mfma_f32_16x16x32_bf16 v[72:75], v[124:127], v[190:193], v[72:75]
	v_mfma_f32_16x16x32_bf16 v[80:83], v[124:127], v[198:201], v[80:83]
	v_mfma_f32_16x16x32_bf16 v[80:83], v[128:131], v[202:205], v[80:83]
	v_mfma_f32_16x16x32_bf16 v[76:79], v[120:123], v[202:205], v[76:79]
	v_mfma_f32_16x16x32_bf16 v[76:79], v[116:119], v[198:201], v[76:79]
	v_mfma_f32_16x16x32_bf16 v[84:87], v[116:119], v[206:209], v[84:87]
	v_mfma_f32_16x16x32_bf16 v[84:87], v[120:123], v[210:213], v[84:87]
	v_mfma_f32_16x16x32_bf16 v[88:91], v[128:131], v[210:213], v[88:91]
	v_mfma_f32_16x16x32_bf16 v[88:91], v[124:127], v[206:209], v[88:91]
	v_mfma_f32_16x16x32_bf16 v[96:99], v[124:127], v[214:217], v[96:99]
	v_mfma_f32_16x16x32_bf16 v[96:99], v[128:131], v[218:221], v[96:99]
	v_mfma_f32_16x16x32_bf16 v[92:95], v[120:123], v[218:221], v[92:95]
	v_mfma_f32_16x16x32_bf16 v[92:95], v[116:119], v[214:217], v[92:95]
	s_setprio 0
	s_setprio 1
	v_mfma_f32_16x16x32_bf16 v[100:103], v[150:153], v[190:193], v[100:103]
	v_mfma_f32_16x16x32_bf16 v[100:103], v[154:157], v[194:197], v[100:103]
	v_mfma_f32_16x16x32_bf16 v[104:107], v[186:189], v[194:197], v[104:107]
	v_mfma_f32_16x16x32_bf16 v[104:107], v[182:185], v[190:193], v[104:107]
	v_mfma_f32_16x16x32_bf16 v[44:47], v[182:185], v[198:201], v[44:47]
	v_mfma_f32_16x16x32_bf16 v[44:47], v[186:189], v[202:205], v[44:47]
	v_mfma_f32_16x16x32_bf16 v[108:111], v[154:157], v[202:205], v[108:111]
	v_mfma_f32_16x16x32_bf16 v[108:111], v[150:153], v[198:201], v[108:111]
	v_mfma_f32_16x16x32_bf16 v[48:51], v[150:153], v[206:209], v[48:51]
	v_mfma_f32_16x16x32_bf16 v[48:51], v[154:157], v[210:213], v[48:51]
	v_mfma_f32_16x16x32_bf16 v[52:55], v[186:189], v[210:213], v[52:55]
	v_mfma_f32_16x16x32_bf16 v[52:55], v[182:185], v[206:209], v[52:55]
	v_mfma_f32_16x16x32_bf16 v[60:63], v[182:185], v[214:217], v[60:63]
	v_mfma_f32_16x16x32_bf16 v[60:63], v[186:189], v[218:221], v[60:63]
	v_mfma_f32_16x16x32_bf16 v[56:59], v[154:157], v[218:221], v[56:59]
	v_mfma_f32_16x16x32_bf16 v[56:59], v[150:153], v[214:217], v[56:59]
	s_setprio 0
	s_barrier
; #define PG8_STAGE(bufoff, gbase, voff) do { _Pragma("unroll") for (int _i = 0; _i < 2; ++_i) \
;         __builtin_amdgcn_global_load_lds((const unsigned*)((const char*)(gbase) + (voff)[_i]), (PG8_LAS unsigned*)(lds + (bufoff) + ldsw + _i * 8192), 16, 0, 0); } while (0)
; #define PG8_LDA(dst, b, h) do { _Pragma("unroll") for (int m = 0; m < 4; ++m) _Pragma("unroll") for (int k = 0; k < 2; ++k) dst[m][k] = *(const PG8_LAS bf16x8*)(lds + PG8_SA(b, h) + aoff + m * 2048 + k * 1024); } while (0)
; #define PG8_LDB(dst, b, h) do { _Pragma("unroll") for (int n = 0; n < 2; ++n) _Pragma("unroll") for (int k = 0; k < 2; ++k) dst[n][k] = *(const PG8_LAS bf16x8*)(lds + PG8_SB(b, h) + boff + n * 2048 + k * 1024); } while (0)
; #define PG8_MMA(ai, bj, At, Bt) do { __builtin_amdgcn_s_setprio(1); _Pragma("unroll") for (int m = 0; m < 4; ++m) _Pragma("unroll") for (int n = 0; n < 2; ++n) _Pragma("unroll") for (int k = 0; k < 2; ++k) \
;         acc[ai][bj][m][n] = __builtin_amdgcn_mfma_f32_16x16x32_bf16(Bt[n][k], At[m][k], acc[ai][bj][m][n], 0, 0, 0); __builtin_amdgcn_s_setprio(0); } while (0)
; #define PG8_WAIT_V(n) asm volatile("s_waitcnt vmcnt(" #n ")" ::: "memory")
; #define PG8_WAIT_L(n) asm volatile("s_waitcnt lgkmcnt(" #n ")" ::: "memory")
; template <class Epi, class Sched, bool ALIGN_EPI>
; __device__ __forceinline__ void gemm_phase(PG8_LAS unsigned char* lds, const Gemm g, const Sched& S, const Epi& E) {
;     ...
;             PG8_LDA(At, 0, 1); PG8_STAGE(PG8_SB(0, 0), b2, voffB); PG8_STAGE(PG8_SB(0, 1), b2 + hstepB, voffB); PG8_STAGE(PG8_SA(0, 0), a2, voffA);
;             PG8_WAIT_V(8); PG8_WAIT_L(0); PG8_BAR; PG8_MMA(1, 0, At, B0); PG8_MMA(1, 1, At, B1); PG8_BAR; PG8_SCHED;
;             PG8_LDB(B0, 1, 0); PG8_LDB(B1, 1, 1); PG8_SCHED; PG8_LDA(At, 1, 0); PG8_STAGE(PG8_SA(0, 1), a2 + hstepA, voffA);
;             PG8_WAIT_V(8); PG8_WAIT_L(0); PG8_BAR; PG8_MMA(0, 0, At, B0); PG8_MMA(0, 1, At, B1); PG8_BAR; PG8_SCHED;
;             PG8_LDA(At, 1, 1); PG8_STAGE(PG8_SB(1, 0), b3, voffB); PG8_STAGE(PG8_SB(1, 1), b3 + hstepB, voffB); PG8_STAGE(PG8_SA(1, 0), a3, voffA);
; __global__ void __launch_bounds__(NWAVES * 64, 2) hymba_fwd(Args a) {
;     ...
;             pg8::Gemm g{A2, (const bf16*)(ws + WS_TC), A2LD, A2LD, A2LD}; pg8::DiagOrder S{G, bx, 256};
;             pg8::EpiY E{Zb};
;             pg8::gemm_phase<pg8::EpiY, pg8::DiagOrder, true>(lds, g, S, E);
	s_mov_b32 m0, s53
	v_lshl_add_u64 v[222:223], v[4:5], 0, s[20:21]
	s_add_u32 s34, s30, 0x18200
	ds_read_b128 v[190:193], v3 offset:16384
	ds_read_b128 v[194:197], v3 offset:17408
	ds_read_b128 v[198:201], v3 offset:18432
	ds_read_b128 v[202:205], v3 offset:19456
	ds_read_b128 v[206:209], v3 offset:20480
	ds_read_b128 v[210:213], v3 offset:21504
	ds_read_b128 v[214:217], v3 offset:22528
	ds_read_b128 v[218:221], v3 offset:23552
	global_load_lds_dwordx4 v[222:223], off
	v_lshl_add_u64 v[222:223], v[6:7], 0, s[20:21]
	s_mov_b32 m0, s57
	s_addc_u32 s35, s31, 0
	global_load_lds_dwordx4 v[222:223], off
	v_lshl_add_u64 v[222:223], s[34:35], 0, v[136:137]
	s_mov_b32 m0, s58
	s_nop 0
	global_load_lds_dwordx4 v[222:223], off
	v_lshl_add_u64 v[222:223], s[34:35], 0, v[132:133]
	s_mov_b32 m0, s59
	s_nop 0
	global_load_lds_dwordx4 v[222:223], off
	v_lshl_add_u64 v[222:223], v[8:9], 0, s[20:21]
	s_mov_b32 m0, s42
	s_nop 0
	global_load_lds_dwordx4 v[222:223], off
	v_lshl_add_u64 v[222:223], v[10:11], 0, s[20:21]
	s_mov_b32 m0, s43
	s_nop 0
	global_load_lds_dwordx4 v[222:223], off
	s_waitcnt vmcnt(8)
	s_waitcnt lgkmcnt(0)
	s_barrier
	s_setprio 1
	s_waitcnt lgkmcnt(0)
	v_mfma_f32_16x16x32_bf16 v[12:15], v[116:119], v[214:217], v[12:15]
	v_mfma_f32_16x16x32_bf16 v[12:15], v[120:123], v[218:221], v[12:15]
	v_mfma_f32_16x16x32_bf16 v[16:19], v[128:131], v[218:221], v[16:19]
	v_mfma_f32_16x16x32_bf16 v[16:19], v[124:127], v[214:217], v[16:19]
	v_mfma_f32_16x16x32_bf16 v[162:165], v[124:127], v[190:193], v[162:165]
	v_mfma_f32_16x16x32_bf16 v[162:165], v[128:131], v[194:197], v[162:165]
	v_mfma_f32_16x16x32_bf16 v[158:161], v[120:123], v[194:197], v[158:161]
	v_mfma_f32_16x16x32_bf16 v[158:161], v[116:119], v[190:193], v[158:161]
	v_mfma_f32_16x16x32_bf16 v[166:169], v[116:119], v[198:201], v[166:169]
	v_mfma_f32_16x16x32_bf16 v[166:169], v[120:123], v[202:205], v[166:169]
	v_mfma_f32_16x16x32_bf16 v[170:173], v[128:131], v[202:205], v[170:173]
	v_mfma_f32_16x16x32_bf16 v[170:173], v[124:127], v[198:201], v[170:173]
	v_mfma_f32_16x16x32_bf16 v[178:181], v[124:127], v[206:209], v[178:181]
	v_mfma_f32_16x16x32_bf16 v[178:181], v[128:131], v[210:213], v[178:181]
	v_mfma_f32_16x16x32_bf16 v[174:177], v[120:123], v[210:213], v[174:177]
	v_mfma_f32_16x16x32_bf16 v[174:177], v[116:119], v[206:209], v[174:177]
	s_setprio 0
	s_setprio 1
	v_mfma_f32_16x16x32_bf16 v[20:23], v[150:153], v[190:193], v[20:23]
	v_mfma_f32_16x16x32_bf16 v[20:23], v[154:157], v[194:197], v[20:23]
	v_mfma_f32_16x16x32_bf16 v[24:27], v[186:189], v[194:197], v[24:27]
	v_mfma_f32_16x16x32_bf16 v[24:27], v[182:185], v[190:193], v[24:27]
	v_mfma_f32_16x16x32_bf16 v[40:43], v[182:185], v[198:201], v[40:43]
	v_mfma_f32_16x16x32_bf16 v[40:43], v[186:189], v[202:205], v[40:43]
	v_mfma_f32_16x16x32_bf16 v[36:39], v[154:157], v[202:205], v[36:39]
	v_mfma_f32_16x16x32_bf16 v[36:39], v[150:153], v[198:201], v[36:39]
	v_mfma_f32_16x16x32_bf16 v[64:67], v[150:153], v[206:209], v[64:67]
	v_mfma_f32_16x16x32_bf16 v[64:67], v[154:157], v[210:213], v[64:67]
	v_mfma_f32_16x16x32_bf16 v[112:115], v[186:189], v[210:213], v[112:115]
	v_mfma_f32_16x16x32_bf16 v[112:115], v[182:185], v[206:209], v[112:115]
	v_mfma_f32_16x16x32_bf16 v[32:35], v[182:185], v[214:217], v[32:35]
	v_mfma_f32_16x16x32_bf16 v[32:35], v[186:189], v[218:221], v[32:35]
	v_mfma_f32_16x16x32_bf16 v[28:31], v[154:157], v[218:221], v[28:31]
	v_mfma_f32_16x16x32_bf16 v[28:31], v[150:153], v[214:217], v[28:31]
	s_setprio 0
	s_barrier
	ds_read_b128 v[116:119], v148
	ds_read_b128 v[120:123], v148 offset:1024
	ds_read_b128 v[124:127], v148 offset:2048
	ds_read_b128 v[128:131], v148 offset:3072
	ds_read_b128 v[150:153], v149
	ds_read_b128 v[154:157], v149 offset:1024
	ds_read_b128 v[182:185], v149 offset:2048
	ds_read_b128 v[186:189], v149 offset:3072
	s_add_u32 s34, s28, 0x18200
	s_addc_u32 s35, s29, 0
	s_mov_b32 m0, s44
	v_lshl_add_u64 v[222:223], s[34:35], 0, v[138:139]
	ds_read_b128 v[190:193], v3 offset:32768
	ds_read_b128 v[194:197], v3 offset:33792
	ds_read_b128 v[198:201], v3 offset:34816
	ds_read_b128 v[202:205], v3 offset:35840
	ds_read_b128 v[206:209], v3 offset:36864
	ds_read_b128 v[210:213], v3 offset:37888
	ds_read_b128 v[214:217], v3 offset:38912
	ds_read_b128 v[218:221], v3 offset:39936
	global_load_lds_dwordx4 v[222:223], off
	v_lshl_add_u64 v[222:223], s[34:35], 0, v[134:135]
	s_mov_b32 m0, s45
	s_nop 0
	global_load_lds_dwordx4 v[222:223], off
	s_waitcnt vmcnt(8)
	s_waitcnt lgkmcnt(0)
	s_barrier
	s_setprio 1
	s_waitcnt lgkmcnt(0)
	v_mfma_f32_16x16x32_bf16 v[68:71], v[116:119], v[190:193], v[68:71]
	v_mfma_f32_16x16x32_bf16 v[68:71], v[120:123], v[194:197], v[68:71]
	v_mfma_f32_16x16x32_bf16 v[72:75], v[128:131], v[194:197], v[72:75]
	v_mfma_f32_16x16x32_bf16 v[72:75], v[124:127], v[190:193], v[72:75]
	v_mfma_f32_16x16x32_bf16 v[80:83], v[124:127], v[198:201], v[80:83]
	v_mfma_f32_16x16x32_bf16 v[80:83], v[128:131], v[202:205], v[80:83]
	v_mfma_f32_16x16x32_bf16 v[76:79], v[120:123], v[202:205], v[76:79]
	v_mfma_f32_16x16x32_bf16 v[76:79], v[116:119], v[198:201], v[76:79]
	v_mfma_f32_16x16x32_bf16 v[84:87], v[116:119], v[206:209], v[84:87]
	v_mfma_f32_16x16x32_bf16 v[84:87], v[120:123], v[210:213], v[84:87]
	v_mfma_f32_16x16x32_bf16 v[88:91], v[128:131], v[210:213], v[88:91]
	v_mfma_f32_16x16x32_bf16 v[88:91], v[124:127], v[206:209], v[88:91]
	v_mfma_f32_16x16x32_bf16 v[96:99], v[124:127], v[214:217], v[96:99]
	v_mfma_f32_16x16x32_bf16 v[96:99], v[128:131], v[218:221], v[96:99]
	v_mfma_f32_16x16x32_bf16 v[92:95], v[120:123], v[218:221], v[92:95]
	v_mfma_f32_16x16x32_bf16 v[92:95], v[116:119], v[214:217], v[92:95]
	s_setprio 0
	s_setprio 1
	v_mfma_f32_16x16x32_bf16 v[100:103], v[150:153], v[190:193], v[100:103]
	v_mfma_f32_16x16x32_bf16 v[100:103], v[154:157], v[194:197], v[100:103]
	v_mfma_f32_16x16x32_bf16 v[104:107], v[186:189], v[194:197], v[104:107]
	v_mfma_f32_16x16x32_bf16 v[104:107], v[182:185], v[190:193], v[104:107]
	v_mfma_f32_16x16x32_bf16 v[44:47], v[182:185], v[198:201], v[44:47]
	v_mfma_f32_16x16x32_bf16 v[44:47], v[186:189], v[202:205], v[44:47]
	v_mfma_f32_16x16x32_bf16 v[108:111], v[154:157], v[202:205], v[108:111]
	v_mfma_f32_16x16x32_bf16 v[108:111], v[150:153], v[198:201], v[108:111]
	v_mfma_f32_16x16x32_bf16 v[48:51], v[150:153], v[206:209], v[48:51]
	v_mfma_f32_16x16x32_bf16 v[48:51], v[154:157], v[210:213], v[48:51]
	v_mfma_f32_16x16x32_bf16 v[52:55], v[186:189], v[210:213], v[52:55]
	v_mfma_f32_16x16x32_bf16 v[52:55], v[182:185], v[206:209], v[52:55]
	v_mfma_f32_16x16x32_bf16 v[60:63], v[182:185], v[214:217], v[60:63]
	v_mfma_f32_16x16x32_bf16 v[60:63], v[186:189], v[218:221], v[60:63]
	v_mfma_f32_16x16x32_bf16 v[56:59], v[154:157], v[218:221], v[56:59]
	v_mfma_f32_16x16x32_bf16 v[56:59], v[150:153], v[214:217], v[56:59]
	s_setprio 0
	s_barrier
; #define PG8_STAGE(bufoff, gbase, voff) do { _Pragma("unroll") for (int _i = 0; _i < 2; ++_i) \
;         __builtin_amdgcn_global_load_lds((const unsigned*)((const char*)(gbase) + (voff)[_i]), (PG8_LAS unsigned*)(lds + (bufoff) + ldsw + _i * 8192), 16, 0, 0); } while (0)
; #define PG8_LDA(dst, b, h) do { _Pragma("unroll") for (int m = 0; m < 4; ++m) _Pragma("unroll") for (int k = 0; k < 2; ++k) dst[m][k] = *(const PG8_LAS bf16x8*)(lds + PG8_SA(b, h) + aoff + m * 2048 + k * 1024); } while (0)
; #define PG8_LDB(dst, b, h) do { _Pragma("unroll") for (int n = 0; n < 2; ++n) _Pragma("unroll") for (int k = 0; k < 2; ++k) dst[n][k] = *(const PG8_LAS bf16x8*)(lds + PG8_SB(b, h) + boff + n * 2048 + k * 1024); } while (0)
; #define PG8_MMA(ai, bj, At, Bt) do { __builtin_amdgcn_s_setprio(1); _Pragma("unroll") for (int m = 0; m < 4; ++m) _Pragma("unroll") for (int n = 0; n < 2; ++n) _Pragma("unroll") for (int k = 0; k < 2; ++k) \
;         acc[ai][bj][m][n] = __builtin_amdgcn_mfma_f32_16x16x32_bf16(Bt[n][k], At[m][k], acc[ai][bj][m][n], 0, 0, 0); __builtin_amdgcn_s_setprio(0); } while (0)
; #define PG8_WAIT_V(n) asm volatile("s_waitcnt vmcnt(" #n ")" ::: "memory")
; #define PG8_WAIT_L(n) asm volatile("s_waitcnt lgkmcnt(" #n ")" ::: "memory")
; #define PG8_BAR __builtin_amdgcn_s_barrier()
; #define PG8_SCHED __builtin_amdgcn_sched_barrier(0)
; template <class Epi, class Sched, bool ALIGN_EPI>
; __device__ __forceinline__ void gemm_phase(PG8_LAS unsigned char* lds, const Gemm g, const Sched& S, const Epi& E) {
;     ...
;             PG8_LDB(B0, 0, 0); PG8_LDB(B1, 0, 1); PG8_SCHED; PG8_LDA(At, 0, 0); PG8_STAGE(PG8_SA(1, 1), a1 + hstepA, voffA);
;             PG8_WAIT_V(8); PG8_WAIT_L(0); PG8_BAR; PG8_MMA(0, 0, At, B0); PG8_MMA(0, 1, At, B1); PG8_BAR; PG8_SCHED;
;             PG8_LDA(At, 0, 1); PG8_STAGE(PG8_SB(0, 0), b2, voffB); PG8_STAGE(PG8_SB(0, 1), b2 + hstepB, voffB); PG8_STAGE(PG8_SA(0, 0), a2, voffA);
;             PG8_WAIT_V(8); PG8_WAIT_L(0); PG8_BAR; PG8_MMA(1, 0, At, B0); PG8_MMA(1, 1, At, B1); PG8_BAR; PG8_SCHED;
;     ...
;             PG8_LDA(At, 1, 1); PG8_STAGE(PG8_SB(1, 0), b3, voffB); PG8_STAGE(PG8_SB(1, 1), b3 + hstepB, voffB); PG8_STAGE(PG8_SA(1, 0), a3, voffA);
;             PG8_WAIT_V(8); PG8_WAIT_L(0); PG8_BAR; PG8_MMA(1, 0, At, B0); PG8_MMA(1, 1, At, B1); PG8_BAR; PG8_SCHED;
	s_mov_b32 m0, s61
	v_lshl_add_u64 v[4:5], v[4:5], 0, s[22:23]
	s_add_u32 s30, s30, 0x18280
	ds_read_b128 v[190:193], v3 offset:49152
	ds_read_b128 v[194:197], v3 offset:50176
	ds_read_b128 v[198:201], v3 offset:51200
	ds_read_b128 v[202:205], v3 offset:52224
	ds_read_b128 v[206:209], v3 offset:53248
	ds_read_b128 v[210:213], v3 offset:54272
	ds_read_b128 v[214:217], v3 offset:55296
	ds_read_b128 v[218:221], v3 offset:56320
	global_load_lds_dwordx4 v[4:5], off
	v_lshl_add_u64 v[4:5], v[6:7], 0, s[22:23]
	s_mov_b32 m0, s4
	s_addc_u32 s31, s31, 0
	global_load_lds_dwordx4 v[4:5], off
	v_lshl_add_u64 v[4:5], s[30:31], 0, v[136:137]
	s_mov_b32 m0, s5
	s_nop 0
	global_load_lds_dwordx4 v[4:5], off
	v_lshl_add_u64 v[4:5], s[30:31], 0, v[132:133]
	s_mov_b32 m0, s7
	s_nop 0
	global_load_lds_dwordx4 v[4:5], off
	v_lshl_add_u64 v[4:5], v[8:9], 0, s[22:23]
	s_mov_b32 m0, s47
	s_nop 0
	global_load_lds_dwordx4 v[4:5], off
	v_lshl_add_u64 v[4:5], v[10:11], 0, s[22:23]
	s_mov_b32 m0, s48
	s_nop 0
	global_load_lds_dwordx4 v[4:5], off
	s_waitcnt vmcnt(8)
	s_waitcnt lgkmcnt(0)
	s_barrier
	s_setprio 1
	s_waitcnt lgkmcnt(0)
	v_mfma_f32_16x16x32_bf16 v[4:7], v[116:119], v[190:193], v[158:161]
	v_mfma_f32_16x16x32_bf16 v[8:11], v[124:127], v[190:193], v[162:165]
	v_mfma_f32_16x16x32_bf16 v[12:15], v[116:119], v[214:217], v[12:15]
	v_mfma_f32_16x16x32_bf16 v[16:19], v[124:127], v[214:217], v[16:19]
	v_mfma_f32_16x16x32_bf16 v[4:7], v[120:123], v[194:197], v[4:7]
	v_mfma_f32_16x16x32_bf16 v[8:11], v[128:131], v[194:197], v[8:11]
	v_mfma_f32_16x16x32_bf16 v[158:161], v[116:119], v[198:201], v[166:169]
	v_mfma_f32_16x16x32_bf16 v[162:165], v[124:127], v[198:201], v[170:173]
	v_mfma_f32_16x16x32_bf16 v[166:169], v[116:119], v[206:209], v[174:177]
	v_mfma_f32_16x16x32_bf16 v[170:173], v[124:127], v[206:209], v[178:181]
	v_mfma_f32_16x16x32_bf16 v[12:15], v[120:123], v[218:221], v[12:15]
	v_mfma_f32_16x16x32_bf16 v[16:19], v[128:131], v[218:221], v[16:19]
	v_mfma_f32_16x16x32_bf16 v[158:161], v[120:123], v[202:205], v[158:161]
	v_mfma_f32_16x16x32_bf16 v[162:165], v[128:131], v[202:205], v[162:165]
	v_mfma_f32_16x16x32_bf16 v[166:169], v[120:123], v[210:213], v[166:169]
	v_mfma_f32_16x16x32_bf16 v[170:173], v[128:131], v[210:213], v[170:173]
	s_setprio 0
	s_setprio 1
	v_mfma_f32_16x16x32_bf16 v[20:23], v[150:153], v[190:193], v[20:23]
	v_mfma_f32_16x16x32_bf16 v[20:23], v[154:157], v[194:197], v[20:23]
	v_mfma_f32_16x16x32_bf16 v[24:27], v[186:189], v[194:197], v[24:27]
	v_mfma_f32_16x16x32_bf16 v[24:27], v[182:185], v[190:193], v[24:27]
	v_mfma_f32_16x16x32_bf16 v[40:43], v[182:185], v[198:201], v[40:43]
	v_mfma_f32_16x16x32_bf16 v[40:43], v[186:189], v[202:205], v[40:43]
	v_mfma_f32_16x16x32_bf16 v[36:39], v[154:157], v[202:205], v[36:39]
	v_mfma_f32_16x16x32_bf16 v[36:39], v[150:153], v[198:201], v[36:39]
	v_mfma_f32_16x16x32_bf16 v[64:67], v[150:153], v[206:209], v[64:67]
	v_mfma_f32_16x16x32_bf16 v[64:67], v[154:157], v[210:213], v[64:67]
	v_mfma_f32_16x16x32_bf16 v[112:115], v[186:189], v[210:213], v[112:115]
	v_mfma_f32_16x16x32_bf16 v[112:115], v[182:185], v[206:209], v[112:115]
	v_mfma_f32_16x16x32_bf16 v[32:35], v[182:185], v[214:217], v[32:35]
	v_mfma_f32_16x16x32_bf16 v[32:35], v[186:189], v[218:221], v[32:35]
	v_mfma_f32_16x16x32_bf16 v[28:31], v[154:157], v[218:221], v[28:31]
	v_mfma_f32_16x16x32_bf16 v[28:31], v[150:153], v[214:217], v[28:31]
	s_setprio 0
	s_barrier
	ds_read_b128 v[116:119], v146
	ds_read_b128 v[120:123], v146 offset:1024
	ds_read_b128 v[124:127], v146 offset:2048
	ds_read_b128 v[128:131], v146 offset:3072
	ds_read_b128 v[150:153], v147
	ds_read_b128 v[154:157], v147 offset:1024
	ds_read_b128 v[174:177], v147 offset:2048
	ds_read_b128 v[178:181], v147 offset:3072
	s_add_u32 s28, s28, 0x18280
	s_addc_u32 s29, s29, 0
	s_mov_b32 m0, s51
	v_lshl_add_u64 v[214:215], s[28:29], 0, v[138:139]
	ds_read_b128 v[182:185], v3
	ds_read_b128 v[186:189], v3 offset:1024
	ds_read_b128 v[190:193], v3 offset:2048
	ds_read_b128 v[194:197], v3 offset:3072
	ds_read_b128 v[198:201], v3 offset:4096
	ds_read_b128 v[202:205], v3 offset:5120
	ds_read_b128 v[206:209], v3 offset:6144
	ds_read_b128 v[210:213], v3 offset:7168
	global_load_lds_dwordx4 v[214:215], off
	v_lshl_add_u64 v[214:215], s[28:29], 0, v[134:135]
	s_mov_b32 m0, s52
	s_nop 0
	global_load_lds_dwordx4 v[214:215], off
	s_waitcnt vmcnt(8)
	s_waitcnt lgkmcnt(0)
	s_barrier
	s_setprio 1
	s_waitcnt lgkmcnt(0)
	v_mfma_f32_16x16x32_bf16 v[68:71], v[116:119], v[182:185], v[68:71]
	v_mfma_f32_16x16x32_bf16 v[72:75], v[124:127], v[182:185], v[72:75]
	v_mfma_f32_16x16x32_bf16 v[76:79], v[116:119], v[190:193], v[76:79]
	v_mfma_f32_16x16x32_bf16 v[80:83], v[124:127], v[190:193], v[80:83]
	v_mfma_f32_16x16x32_bf16 v[84:87], v[116:119], v[198:201], v[84:87]
	v_mfma_f32_16x16x32_bf16 v[88:91], v[124:127], v[198:201], v[88:91]
	v_mfma_f32_16x16x32_bf16 v[92:95], v[116:119], v[206:209], v[92:95]
	v_mfma_f32_16x16x32_bf16 v[68:71], v[120:123], v[186:189], v[68:71]
	v_mfma_f32_16x16x32_bf16 v[72:75], v[128:131], v[186:189], v[72:75]
	v_mfma_f32_16x16x32_bf16 v[76:79], v[120:123], v[194:197], v[76:79]
	v_mfma_f32_16x16x32_bf16 v[80:83], v[128:131], v[194:197], v[80:83]
	v_mfma_f32_16x16x32_bf16 v[84:87], v[120:123], v[202:205], v[84:87]
	v_mfma_f32_16x16x32_bf16 v[88:91], v[128:131], v[202:205], v[88:91]
	v_mfma_f32_16x16x32_bf16 v[214:217], v[120:123], v[210:213], v[92:95]
	v_mfma_f32_16x16x32_bf16 v[92:95], v[124:127], v[206:209], v[96:99]
	v_mfma_f32_16x16x32_bf16 v[218:221], v[128:131], v[210:213], v[92:95]
	s_setprio 0
	s_setprio 1
	v_mfma_f32_16x16x32_bf16 v[92:95], v[150:153], v[182:185], v[100:103]
	v_mfma_f32_16x16x32_bf16 v[100:103], v[154:157], v[186:189], v[92:95]
	v_mfma_f32_16x16x32_bf16 v[92:95], v[174:177], v[182:185], v[104:107]
	v_mfma_f32_16x16x32_bf16 v[44:47], v[174:177], v[190:193], v[44:47]
	v_mfma_f32_16x16x32_bf16 v[48:51], v[150:153], v[198:201], v[48:51]
	v_mfma_f32_16x16x32_bf16 v[52:55], v[174:177], v[198:201], v[52:55]
	v_mfma_f32_16x16x32_bf16 v[56:59], v[150:153], v[206:209], v[56:59]
	v_mfma_f32_16x16x32_bf16 v[60:63], v[174:177], v[206:209], v[60:63]
	v_mfma_f32_16x16x32_bf16 v[104:107], v[178:181], v[186:189], v[92:95]
	v_mfma_f32_16x16x32_bf16 v[92:95], v[150:153], v[190:193], v[108:111]
	v_mfma_f32_16x16x32_bf16 v[44:47], v[178:181], v[194:197], v[44:47]
	v_mfma_f32_16x16x32_bf16 v[48:51], v[154:157], v[202:205], v[48:51]
	v_mfma_f32_16x16x32_bf16 v[52:55], v[178:181], v[202:205], v[52:55]
	v_mfma_f32_16x16x32_bf16 v[56:59], v[154:157], v[210:213], v[56:59]
	v_mfma_f32_16x16x32_bf16 v[60:63], v[178:181], v[210:213], v[60:63]
	v_mfma_f32_16x16x32_bf16 v[182:185], v[154:157], v[194:197], v[92:95]
	s_setprio 0
	s_barrier
; #define PG8_STAGE(bufoff, gbase, voff) do { _Pragma("unroll") for (int _i = 0; _i < 2; ++_i) \
;         __builtin_amdgcn_global_load_lds((const unsigned*)((const char*)(gbase) + (voff)[_i]), (PG8_LAS unsigned*)(lds + (bufoff) + ldsw + _i * 8192), 16, 0, 0); } while (0)
; #define PG8_LDA(dst, b, h) do { _Pragma("unroll") for (int m = 0; m < 4; ++m) _Pragma("unroll") for (int k = 0; k < 2; ++k) dst[m][k] = *(const PG8_LAS bf16x8*)(lds + PG8_SA(b, h) + aoff + m * 2048 + k * 1024); } while (0)
; #define PG8_LDB(dst, b, h) do { _Pragma("unroll") for (int n = 0; n < 2; ++n) _Pragma("unroll") for (int k = 0; k < 2; ++k) dst[n][k] = *(const PG8_LAS bf16x8*)(lds + PG8_SB(b, h) + boff + n * 2048 + k * 1024); } while (0)
; #define PG8_MMA(ai, bj, At, Bt) do { __builtin_amdgcn_s_setprio(1); _Pragma("unroll") for (int m = 0; m < 4; ++m) _Pragma("unroll") for (int n = 0; n < 2; ++n) _Pragma("unroll") for (int k = 0; k < 2; ++k) \
;         acc[ai][bj][m][n] = __builtin_amdgcn_mfma_f32_16x16x32_bf16(Bt[n][k], At[m][k], acc[ai][bj][m][n], 0, 0, 0); __builtin_amdgcn_s_setprio(0); } while (0)
; #define PG8_WAIT_V(n) asm volatile("s_waitcnt vmcnt(" #n ")" ::: "memory")
; #define PG8_WAIT_L(n) asm volatile("s_waitcnt lgkmcnt(" #n ")" ::: "memory")
; #define PG8_BAR __builtin_amdgcn_s_barrier()
; #define PG8_SCHED __builtin_amdgcn_sched_barrier(0)
; template <class Epi, class Sched, bool ALIGN_EPI>
; __device__ __forceinline__ void gemm_phase(PG8_LAS unsigned char* lds, const Gemm g, const Sched& S, const Epi& E) {
;     ...
;             PG8_LDA(At, 0, 1); PG8_STAGE(PG8_SB(0, 0), b2, voffB); PG8_STAGE(PG8_SB(0, 1), b2 + hstepB, voffB); PG8_STAGE(PG8_SA(0, 0), a2, voffA);
;             PG8_WAIT_V(8); PG8_WAIT_L(0); PG8_BAR; PG8_MMA(1, 0, At, B0); PG8_MMA(1, 1, At, B1); PG8_BAR; PG8_SCHED;
;             PG8_LDB(B0, 1, 0); PG8_LDB(B1, 1, 1); PG8_SCHED; PG8_LDA(At, 1, 0); PG8_STAGE(PG8_SA(0, 1), a2 + hstepA, voffA);
;             PG8_WAIT_V(8); PG8_WAIT_L(0); PG8_BAR; PG8_MMA(0, 0, At, B0); PG8_MMA(0, 1, At, B1); PG8_BAR; PG8_SCHED;
	s_mov_b32 m0, s53
	v_lshl_add_u64 v[246:247], s[26:27], 0, v[136:137]
	s_add_u32 s28, s26, 0x18000
	ds_read_b128 v[92:95], v3 offset:16384
	ds_read_b128 v[96:99], v3 offset:17408
	ds_read_b128 v[108:111], v3 offset:18432
	ds_read_b128 v[186:189], v3 offset:19456
	ds_read_b128 v[190:193], v3 offset:20480
	ds_read_b128 v[194:197], v3 offset:21504
	ds_read_b128 v[198:201], v3 offset:22528
	ds_read_b128 v[202:205], v3 offset:23552
	global_load_lds_dwordx4 v[246:247], off
	v_lshl_add_u64 v[248:249], s[26:27], 0, v[132:133]
	s_mov_b32 m0, s57
	s_addc_u32 s29, s27, 0
	global_load_lds_dwordx4 v[248:249], off
	v_lshl_add_u64 v[206:207], s[28:29], 0, v[136:137]
	s_mov_b32 m0, s58
	v_lshl_add_u64 v[250:251], s[24:25], 0, v[138:139]
	global_load_lds_dwordx4 v[206:207], off
	v_lshl_add_u64 v[206:207], s[28:29], 0, v[132:133]
	s_mov_b32 m0, s59
	v_lshl_add_u64 v[252:253], s[24:25], 0, v[134:135]
	global_load_lds_dwordx4 v[206:207], off
	s_mov_b32 m0, s42
	s_nop 0
	global_load_lds_dwordx4 v[250:251], off
	s_mov_b32 m0, s43
	s_nop 0
	global_load_lds_dwordx4 v[252:253], off
	s_waitcnt vmcnt(8)
	s_waitcnt lgkmcnt(0)
	s_barrier
	s_setprio 1
	s_waitcnt lgkmcnt(0)
	v_mfma_f32_16x16x32_bf16 v[4:7], v[116:119], v[92:95], v[4:7]
	v_mfma_f32_16x16x32_bf16 v[8:11], v[124:127], v[92:95], v[8:11]
	v_mfma_f32_16x16x32_bf16 v[12:15], v[116:119], v[198:201], v[12:15]
	v_mfma_f32_16x16x32_bf16 v[4:7], v[120:123], v[96:99], v[4:7]
	v_mfma_f32_16x16x32_bf16 v[8:11], v[128:131], v[96:99], v[8:11]
	v_mfma_f32_16x16x32_bf16 v[158:161], v[116:119], v[108:111], v[158:161]
	v_mfma_f32_16x16x32_bf16 v[162:165], v[124:127], v[108:111], v[162:165]
	v_mfma_f32_16x16x32_bf16 v[166:169], v[116:119], v[190:193], v[166:169]
	v_mfma_f32_16x16x32_bf16 v[170:173], v[124:127], v[190:193], v[170:173]
	v_mfma_f32_16x16x32_bf16 v[12:15], v[120:123], v[202:205], v[12:15]
	v_mfma_f32_16x16x32_bf16 v[16:19], v[124:127], v[198:201], v[16:19]
	v_mfma_f32_16x16x32_bf16 v[158:161], v[120:123], v[186:189], v[158:161]
	v_mfma_f32_16x16x32_bf16 v[162:165], v[128:131], v[186:189], v[162:165]
	v_mfma_f32_16x16x32_bf16 v[166:169], v[120:123], v[194:197], v[166:169]
	v_mfma_f32_16x16x32_bf16 v[170:173], v[128:131], v[194:197], v[170:173]
	v_mfma_f32_16x16x32_bf16 v[206:209], v[128:131], v[202:205], v[16:19]
	s_setprio 0
	s_setprio 1
	v_mfma_f32_16x16x32_bf16 v[16:19], v[150:153], v[92:95], v[20:23]
	v_mfma_f32_16x16x32_bf16 v[20:23], v[154:157], v[96:99], v[16:19]
	v_mfma_f32_16x16x32_bf16 v[16:19], v[174:177], v[92:95], v[24:27]
	v_mfma_f32_16x16x32_bf16 v[24:27], v[178:181], v[96:99], v[16:19]
	v_mfma_f32_16x16x32_bf16 v[16:19], v[150:153], v[108:111], v[36:39]
	v_mfma_f32_16x16x32_bf16 v[36:39], v[154:157], v[186:189], v[16:19]
	v_mfma_f32_16x16x32_bf16 v[16:19], v[174:177], v[108:111], v[40:43]
	v_mfma_f32_16x16x32_bf16 v[186:189], v[178:181], v[186:189], v[16:19]
	v_mfma_f32_16x16x32_bf16 v[16:19], v[150:153], v[190:193], v[64:67]
	v_mfma_f32_16x16x32_bf16 v[210:213], v[154:157], v[194:197], v[16:19]
	v_mfma_f32_16x16x32_bf16 v[16:19], v[174:177], v[190:193], v[112:115]
	v_mfma_f32_16x16x32_bf16 v[190:193], v[178:181], v[194:197], v[16:19]
	v_mfma_f32_16x16x32_bf16 v[16:19], v[150:153], v[198:201], v[28:31]
	v_mfma_f32_16x16x32_bf16 v[150:153], v[154:157], v[202:205], v[16:19]
	v_mfma_f32_16x16x32_bf16 v[16:19], v[174:177], v[198:201], v[32:35]
	v_mfma_f32_16x16x32_bf16 v[154:157], v[178:181], v[202:205], v[16:19]
	s_setprio 0
	s_barrier
	s_nop 4
	ds_read_b128 v[16:19], v148
	ds_read_b128 v[40:43], v148 offset:1024
	ds_read_b128 v[174:177], v148 offset:2048
	ds_read_b128 v[178:181], v148 offset:3072
	ds_read_b128 v[194:197], v149
	ds_read_b128 v[198:201], v149 offset:1024
	ds_read_b128 v[202:205], v149 offset:2048
	ds_read_b128 v[222:225], v149 offset:3072
	s_add_u32 s28, s24, 0x18000
	s_addc_u32 s29, s25, 0
	s_mov_b32 m0, s44
	v_lshl_add_u64 v[92:93], s[28:29], 0, v[138:139]
	ds_read_b128 v[28:31], v3 offset:32768
	ds_read_b128 v[32:35], v3 offset:33792
	ds_read_b128 v[64:67], v3 offset:34816
	ds_read_b128 v[226:229], v3 offset:35840
	ds_read_b128 v[230:233], v3 offset:36864
	ds_read_b128 v[234:237], v3 offset:37888
	ds_read_b128 v[238:241], v3 offset:38912
	ds_read_b128 v[242:245], v3 offset:39936
	global_load_lds_dwordx4 v[92:93], off
	v_lshl_add_u64 v[92:93], s[28:29], 0, v[134:135]
	s_mov_b32 m0, s45
	s_nop 0
	global_load_lds_dwordx4 v[92:93], off
	s_waitcnt vmcnt(8)
	s_waitcnt lgkmcnt(0)
	s_barrier
; #define PG8_STAGE(bufoff, gbase, voff) do { _Pragma("unroll") for (int _i = 0; _i < 2; ++_i) \
;         __builtin_amdgcn_global_load_lds((const unsigned*)((const char*)(gbase) + (voff)[_i]), (PG8_LAS unsigned*)(lds + (bufoff) + ldsw + _i * 8192), 16, 0, 0); } while (0)
; #define PG8_LDA(dst, b, h) do { _Pragma("unroll") for (int m = 0; m < 4; ++m) _Pragma("unroll") for (int k = 0; k < 2; ++k) dst[m][k] = *(const PG8_LAS bf16x8*)(lds + PG8_SA(b, h) + aoff + m * 2048 + k * 1024); } while (0)
; #define PG8_LDB(dst, b, h) do { _Pragma("unroll") for (int n = 0; n < 2; ++n) _Pragma("unroll") for (int k = 0; k < 2; ++k) dst[n][k] = *(const PG8_LAS bf16x8*)(lds + PG8_SB(b, h) + boff + n * 2048 + k * 1024); } while (0)
; #define PG8_MMA(ai, bj, At, Bt) do { __builtin_amdgcn_s_setprio(1); _Pragma("unroll") for (int m = 0; m < 4; ++m) _Pragma("unroll") for (int n = 0; n < 2; ++n) _Pragma("unroll") for (int k = 0; k < 2; ++k) \
;         acc[ai][bj][m][n] = __builtin_amdgcn_mfma_f32_16x16x32_bf16(Bt[n][k], At[m][k], acc[ai][bj][m][n], 0, 0, 0); __builtin_amdgcn_s_setprio(0); } while (0)
; #define PG8_WAIT_V(n) asm volatile("s_waitcnt vmcnt(" #n ")" ::: "memory")
; #define PG8_WAIT_L(n) asm volatile("s_waitcnt lgkmcnt(" #n ")" ::: "memory")
; #define PG8_BAR __builtin_amdgcn_s_barrier()
; #define PG8_SCHED __builtin_amdgcn_sched_barrier(0)
; template <class Epi, class Sched, bool ALIGN_EPI>
; __device__ __forceinline__ void gemm_phase(PG8_LAS unsigned char* lds, const Gemm g, const Sched& S, const Epi& E) {
;     ...
;             PG8_WAIT_V(8); PG8_WAIT_L(0); PG8_BAR; PG8_MMA(1, 0, At, B0); PG8_MMA(1, 1, At, B1); PG8_BAR; PG8_SCHED;
;             PG8_LDB(B0, 1, 0); PG8_LDB(B1, 1, 1); PG8_SCHED; PG8_LDA(At, 1, 0); PG8_STAGE(PG8_SA(0, 1), a2 + hstepA, voffA);
;             PG8_WAIT_V(8); PG8_WAIT_L(0); PG8_BAR; PG8_MMA(0, 0, At, B0); PG8_MMA(0, 1, At, B1); PG8_BAR; PG8_SCHED;
;             PG8_LDA(At, 1, 1); PG8_STAGE(PG8_SB(1, 0), b3, voffB); PG8_STAGE(PG8_SB(1, 1), b3 + hstepB, voffB); PG8_STAGE(PG8_SA(1, 0), a3, voffA);
;             PG8_WAIT_V(8); PG8_WAIT_L(0); PG8_BAR; PG8_MMA(1, 0, At, B0); PG8_MMA(1, 1, At, B1); PG8_BAR; PG8_SCHED;
;         }
;         if constexpr (ALIGN_EPI) { if (wr == 0) PG8_BAR; }
	s_setprio 1
	s_waitcnt lgkmcnt(0)
	v_mfma_f32_16x16x32_bf16 v[68:71], v[16:19], v[28:31], v[68:71]
	v_mfma_f32_16x16x32_bf16 v[128:131], v[40:43], v[32:35], v[68:71]
	v_mfma_f32_16x16x32_bf16 v[68:71], v[174:177], v[28:31], v[72:75]
	v_mfma_f32_16x16x32_bf16 v[124:127], v[178:181], v[32:35], v[68:71]
	v_mfma_f32_16x16x32_bf16 v[68:71], v[16:19], v[64:67], v[76:79]
	v_mfma_f32_16x16x32_bf16 v[112:115], v[40:43], v[226:229], v[68:71]
	v_mfma_f32_16x16x32_bf16 v[68:71], v[174:177], v[64:67], v[80:83]
	v_mfma_f32_16x16x32_bf16 v[108:111], v[178:181], v[226:229], v[68:71]
	v_mfma_f32_16x16x32_bf16 v[68:71], v[16:19], v[230:233], v[84:87]
	v_mfma_f32_16x16x32_bf16 v[96:99], v[40:43], v[234:237], v[68:71]
	v_mfma_f32_16x16x32_bf16 v[68:71], v[174:177], v[230:233], v[88:91]
	v_mfma_f32_16x16x32_bf16 v[92:95], v[178:181], v[234:237], v[68:71]
	v_mfma_f32_16x16x32_bf16 v[68:71], v[16:19], v[238:241], v[214:217]
	v_mfma_f32_16x16x32_bf16 v[80:83], v[40:43], v[242:245], v[68:71]
	v_mfma_f32_16x16x32_bf16 v[68:71], v[174:177], v[238:241], v[218:221]
	v_mfma_f32_16x16x32_bf16 v[76:79], v[178:181], v[242:245], v[68:71]
	s_setprio 0
	s_setprio 1
	v_mfma_f32_16x16x32_bf16 v[68:71], v[194:197], v[28:31], v[100:103]
	v_mfma_f32_16x16x32_bf16 v[28:31], v[202:205], v[28:31], v[104:107]
	v_mfma_f32_16x16x32_bf16 v[116:119], v[222:225], v[32:35], v[28:31]
	v_mfma_f32_16x16x32_bf16 v[28:31], v[194:197], v[64:67], v[182:185]
	v_mfma_f32_16x16x32_bf16 v[104:107], v[198:201], v[226:229], v[28:31]
	v_mfma_f32_16x16x32_bf16 v[28:31], v[202:205], v[64:67], v[44:47]
	v_mfma_f32_16x16x32_bf16 v[100:103], v[222:225], v[226:229], v[28:31]
	v_mfma_f32_16x16x32_bf16 v[28:31], v[194:197], v[230:233], v[48:51]
	v_mfma_f32_16x16x32_bf16 v[88:91], v[198:201], v[234:237], v[28:31]
	v_mfma_f32_16x16x32_bf16 v[28:31], v[202:205], v[230:233], v[52:55]
	v_mfma_f32_16x16x32_bf16 v[84:87], v[222:225], v[234:237], v[28:31]
	v_mfma_f32_16x16x32_bf16 v[28:31], v[194:197], v[238:241], v[56:59]
	v_mfma_f32_16x16x32_bf16 v[72:75], v[198:201], v[242:245], v[28:31]
	v_mfma_f32_16x16x32_bf16 v[28:31], v[202:205], v[238:241], v[60:63]
	v_mfma_f32_16x16x32_bf16 v[120:123], v[198:201], v[32:35], v[68:71]
	v_mfma_f32_16x16x32_bf16 v[68:71], v[222:225], v[242:245], v[28:31]
	s_setprio 0
	s_barrier
	s_mov_b32 m0, s61
	s_nop 2
	v_lshl_add_u64 v[28:29], v[246:247], 0, s[10:11]
	s_add_u32 s28, s26, 0x18080
	ds_read_b128 v[52:55], v3 offset:49152
	ds_read_b128 v[182:185], v3 offset:50176
	ds_read_b128 v[214:217], v3 offset:51200
	ds_read_b128 v[218:221], v3 offset:52224
	ds_read_b128 v[226:229], v3 offset:53248
	ds_read_b128 v[230:233], v3 offset:54272
	ds_read_b128 v[234:237], v3 offset:55296
	ds_read_b128 v[238:241], v3 offset:56320
	global_load_lds_dwordx4 v[28:29], off
	v_lshl_add_u64 v[28:29], v[248:249], 0, s[10:11]
	s_mov_b32 m0, s4
	s_addc_u32 s29, s27, 0
	global_load_lds_dwordx4 v[28:29], off
	v_lshl_add_u64 v[28:29], s[28:29], 0, v[136:137]
	s_mov_b32 m0, s5
	s_nop 0
	global_load_lds_dwordx4 v[28:29], off
	v_lshl_add_u64 v[28:29], s[28:29], 0, v[132:133]
	s_mov_b32 m0, s7
	s_nop 0
	global_load_lds_dwordx4 v[28:29], off
	v_lshl_add_u64 v[28:29], v[250:251], 0, s[10:11]
	s_mov_b32 m0, s47
	s_nop 0
	global_load_lds_dwordx4 v[28:29], off
	v_lshl_add_u64 v[28:29], v[252:253], 0, s[10:11]
	s_mov_b32 m0, s48
	s_nop 0
	global_load_lds_dwordx4 v[28:29], off
	s_waitcnt vmcnt(8)
	s_waitcnt lgkmcnt(0)
	s_barrier
	s_setprio 1
	s_waitcnt lgkmcnt(0)
	v_mfma_f32_16x16x32_bf16 v[4:7], v[16:19], v[52:55], v[4:7]
	v_mfma_f32_16x16x32_bf16 v[64:67], v[40:43], v[182:185], v[4:7]
	v_mfma_f32_16x16x32_bf16 v[4:7], v[174:177], v[52:55], v[8:11]
	v_mfma_f32_16x16x32_bf16 v[60:63], v[178:181], v[182:185], v[4:7]
	v_mfma_f32_16x16x32_bf16 v[4:7], v[16:19], v[214:217], v[158:161]
	v_mfma_f32_16x16x32_bf16 v[48:51], v[40:43], v[218:221], v[4:7]
	v_mfma_f32_16x16x32_bf16 v[4:7], v[174:177], v[214:217], v[162:165]
	v_mfma_f32_16x16x32_bf16 v[44:47], v[178:181], v[218:221], v[4:7]
	v_mfma_f32_16x16x32_bf16 v[4:7], v[16:19], v[226:229], v[166:169]
	v_mfma_f32_16x16x32_bf16 v[32:35], v[40:43], v[230:233], v[4:7]
	v_mfma_f32_16x16x32_bf16 v[4:7], v[174:177], v[226:229], v[170:173]
	v_mfma_f32_16x16x32_bf16 v[28:31], v[178:181], v[230:233], v[4:7]
	v_mfma_f32_16x16x32_bf16 v[4:7], v[16:19], v[234:237], v[12:15]
	v_mfma_f32_16x16x32_bf16 v[16:19], v[40:43], v[238:241], v[4:7]
	v_mfma_f32_16x16x32_bf16 v[4:7], v[174:177], v[234:237], v[206:209]
	v_mfma_f32_16x16x32_bf16 v[12:15], v[178:181], v[238:241], v[4:7]
	s_setprio 0
	s_setprio 1
	v_mfma_f32_16x16x32_bf16 v[4:7], v[194:197], v[52:55], v[20:23]
	v_mfma_f32_16x16x32_bf16 v[56:59], v[198:201], v[182:185], v[4:7]
	v_mfma_f32_16x16x32_bf16 v[4:7], v[202:205], v[52:55], v[24:27]
	v_mfma_f32_16x16x32_bf16 v[52:55], v[222:225], v[182:185], v[4:7]
	v_mfma_f32_16x16x32_bf16 v[4:7], v[194:197], v[214:217], v[36:39]
	v_mfma_f32_16x16x32_bf16 v[40:43], v[198:201], v[218:221], v[4:7]
	v_mfma_f32_16x16x32_bf16 v[4:7], v[202:205], v[214:217], v[186:189]
	v_mfma_f32_16x16x32_bf16 v[36:39], v[222:225], v[218:221], v[4:7]
	v_mfma_f32_16x16x32_bf16 v[4:7], v[194:197], v[226:229], v[210:213]
	v_mfma_f32_16x16x32_bf16 v[24:27], v[198:201], v[230:233], v[4:7]
	v_mfma_f32_16x16x32_bf16 v[4:7], v[202:205], v[226:229], v[190:193]
	v_mfma_f32_16x16x32_bf16 v[20:23], v[222:225], v[230:233], v[4:7]
	v_mfma_f32_16x16x32_bf16 v[4:7], v[194:197], v[234:237], v[150:153]
	v_mfma_f32_16x16x32_bf16 v[8:11], v[198:201], v[238:241], v[4:7]
	v_mfma_f32_16x16x32_bf16 v[4:7], v[202:205], v[234:237], v[154:157]
	v_mfma_f32_16x16x32_bf16 v[4:7], v[222:225], v[238:241], v[4:7]
	s_setprio 0
	s_barrier
	s_andn2_b64 vcc, exec, s[12:13]
	s_cbranch_vccnz .LBB0_650
	s_barrier

; #define PG8_STAGE(bufoff, gbase, voff) do { _Pragma("unroll") for (int _i = 0; _i < 2; ++_i) \
;         __builtin_amdgcn_global_load_lds((const unsigned*)((const char*)(gbase) + (voff)[_i]), (PG8_LAS unsigned*)(lds + (bufoff) + ldsw + _i * 8192), 16, 0, 0); } while (0)
; #define PG8_LDA(dst, b, h) do { _Pragma("unroll") for (int m = 0; m < 4; ++m) _Pragma("unroll") for (int k = 0; k < 2; ++k) dst[m][k] = *(const PG8_LAS bf16x8*)(lds + PG8_SA(b, h) + aoff + m * 2048 + k * 1024); } while (0)
; #define PG8_LDB(dst, b, h) do { _Pragma("unroll") for (int n = 0; n < 2; ++n) _Pragma("unroll") for (int k = 0; k < 2; ++k) dst[n][k] = *(const PG8_LAS bf16x8*)(lds + PG8_SB(b, h) + boff + n * 2048 + k * 1024); } while (0)
; #define PG8_MMA(ai, bj, At, Bt) do { __builtin_amdgcn_s_setprio(1); _Pragma("unroll") for (int m = 0; m < 4; ++m) _Pragma("unroll") for (int n = 0; n < 2; ++n) _Pragma("unroll") for (int k = 0; k < 2; ++k) \
;         acc[ai][bj][m][n] = __builtin_amdgcn_mfma_f32_16x16x32_bf16(Bt[n][k], At[m][k], acc[ai][bj][m][n], 0, 0, 0); __builtin_amdgcn_s_setprio(0); } while (0)
; #define PG8_WAIT_V(n) asm volatile("s_waitcnt vmcnt(" #n ")" ::: "memory")
; #define PG8_WAIT_L(n) asm volatile("s_waitcnt lgkmcnt(" #n ")" ::: "memory")
; #define PG8_BAR __builtin_amdgcn_s_barrier()
; #define PG8_SCHED __builtin_amdgcn_sched_barrier(0)
; template <class Epi, class Sched, bool ALIGN_EPI>
; __device__ __forceinline__ void gemm_phase(PG8_LAS unsigned char* lds, const Gemm g, const Sched& S, const Epi& E) {
;     ...
;             PG8_LDB(B0, 0, 0); PG8_LDB(B1, 0, 1); PG8_SCHED; PG8_LDA(At, 0, 0); PG8_STAGE(PG8_SA(1, 1), a1 + hstepA, voffA);
;             PG8_WAIT_V(8); PG8_WAIT_L(0); PG8_BAR; PG8_MMA(0, 0, At, B0); PG8_MMA(0, 1, At, B1); PG8_BAR; PG8_SCHED;
;             PG8_LDA(At, 0, 1); PG8_STAGE(PG8_SB(0, 0), b2, voffB); PG8_STAGE(PG8_SB(0, 1), b2 + hstepB, voffB); PG8_STAGE(PG8_SA(0, 0), a2, voffA);
;             PG8_WAIT_V(8); PG8_WAIT_L(0); PG8_BAR; PG8_MMA(1, 0, At, B0); PG8_MMA(1, 1, At, B1); PG8_BAR; PG8_SCHED;
; __global__ void __launch_bounds__(NWAVES * 64, 2) hymba_fwd(Args a) {
;     ...
;         pg8::Gemm g{Zb, Wglu_t, D_SSM, D_SSM, D_SSM, M * 16}; pg8::StaticOrder S; S.init(M, D_SSM, G, bx);
;         pg8::EpiGlu E{Zb, a.b_glu, A3 + D_ATTN, DM, stat_s};
;         pg8::gemm_phase<pg8::EpiGlu, pg8::StaticOrder, true>(lds, g, S, E);
.LBB0_778:
	ds_read_b128 v[114:117], v178
	ds_read_b128 v[118:121], v178 offset:1024
	ds_read_b128 v[156:159], v178 offset:2048
	ds_read_b128 v[160:163], v178 offset:3072
	ds_read_b128 v[164:167], v179
	ds_read_b128 v[168:171], v179 offset:1024
	ds_read_b128 v[182:185], v179 offset:2048
	ds_read_b128 v[186:189], v179 offset:3072
	s_add_u32 s36, s34, 0x400000
	s_addc_u32 s37, s35, 0
	s_cmp_eq_u32 s21, 12
	s_cselect_b32 s42, s24, s36
	s_cselect_b32 s43, s25, s37
	s_cselect_b32 s40, s26, s4
	s_cselect_b32 s41, s27, s5
	s_add_u32 s38, s42, 0x200000
	s_addc_u32 s39, s43, 0
	v_lshl_add_u64 v[222:223], s[34:35], 0, v[148:149]
	s_add_i32 m0, s31, 0xc000
	ds_read_b128 v[190:193], v180
	ds_read_b128 v[194:197], v180 offset:1024
	ds_read_b128 v[198:201], v180 offset:2048
	ds_read_b128 v[202:205], v180 offset:3072
	ds_read_b128 v[206:209], v180 offset:4096
	ds_read_b128 v[210:213], v180 offset:5120
	ds_read_b128 v[214:217], v180 offset:6144
	ds_read_b128 v[218:221], v180 offset:7168
	global_load_lds_dwordx4 v[222:223], off
	v_lshl_add_u64 v[222:223], s[34:35], 0, v[150:151]
	s_add_i32 m0, s31, 0xe000
	s_nop 0
	global_load_lds_dwordx4 v[222:223], off
	s_waitcnt vmcnt(8)
	s_waitcnt lgkmcnt(0)
	s_barrier
	s_setprio 1
	s_waitcnt lgkmcnt(0)
	v_mfma_f32_16x16x32_bf16 v[134:137], v[114:117], v[190:193], v[134:137]
	v_mfma_f32_16x16x32_bf16 v[134:137], v[118:121], v[194:197], v[134:137]
	v_mfma_f32_16x16x32_bf16 v[130:133], v[160:163], v[194:197], v[130:133]
	v_mfma_f32_16x16x32_bf16 v[130:133], v[156:159], v[190:193], v[130:133]
	v_mfma_f32_16x16x32_bf16 v[122:125], v[156:159], v[198:201], v[122:125]
	v_mfma_f32_16x16x32_bf16 v[122:125], v[160:163], v[202:205], v[122:125]
	v_mfma_f32_16x16x32_bf16 v[126:129], v[118:121], v[202:205], v[126:129]
	v_mfma_f32_16x16x32_bf16 v[126:129], v[114:117], v[198:201], v[126:129]
	v_mfma_f32_16x16x32_bf16 v[110:113], v[114:117], v[206:209], v[110:113]
	v_mfma_f32_16x16x32_bf16 v[110:113], v[118:121], v[210:213], v[110:113]
	v_mfma_f32_16x16x32_bf16 v[106:109], v[160:163], v[210:213], v[106:109]
	v_mfma_f32_16x16x32_bf16 v[106:109], v[156:159], v[206:209], v[106:109]
	v_mfma_f32_16x16x32_bf16 v[98:101], v[156:159], v[214:217], v[98:101]
	v_mfma_f32_16x16x32_bf16 v[98:101], v[160:163], v[218:221], v[98:101]
	v_mfma_f32_16x16x32_bf16 v[102:105], v[118:121], v[218:221], v[102:105]
	v_mfma_f32_16x16x32_bf16 v[102:105], v[114:117], v[214:217], v[102:105]
	s_setprio 0
	s_setprio 1
	v_mfma_f32_16x16x32_bf16 v[62:65], v[164:167], v[190:193], v[62:65]
	v_mfma_f32_16x16x32_bf16 v[62:65], v[168:171], v[194:197], v[62:65]
	v_mfma_f32_16x16x32_bf16 v[58:61], v[186:189], v[194:197], v[58:61]
	v_mfma_f32_16x16x32_bf16 v[58:61], v[182:185], v[190:193], v[58:61]
	v_mfma_f32_16x16x32_bf16 v[50:53], v[182:185], v[198:201], v[50:53]
	v_mfma_f32_16x16x32_bf16 v[50:53], v[186:189], v[202:205], v[50:53]
	v_mfma_f32_16x16x32_bf16 v[54:57], v[168:171], v[202:205], v[54:57]
	v_mfma_f32_16x16x32_bf16 v[54:57], v[164:167], v[198:201], v[54:57]
	v_mfma_f32_16x16x32_bf16 v[46:49], v[164:167], v[206:209], v[46:49]
	v_mfma_f32_16x16x32_bf16 v[46:49], v[168:171], v[210:213], v[46:49]
	v_mfma_f32_16x16x32_bf16 v[42:45], v[186:189], v[210:213], v[42:45]
	v_mfma_f32_16x16x32_bf16 v[42:45], v[182:185], v[206:209], v[42:45]
	v_mfma_f32_16x16x32_bf16 v[34:37], v[182:185], v[214:217], v[34:37]
	v_mfma_f32_16x16x32_bf16 v[34:37], v[186:189], v[218:221], v[34:37]
	v_mfma_f32_16x16x32_bf16 v[38:41], v[168:171], v[218:221], v[38:41]
	v_mfma_f32_16x16x32_bf16 v[38:41], v[164:167], v[214:217], v[38:41]
	s_setprio 0
	s_barrier
	s_add_i32 s2, s52, s3
	v_lshl_add_u64 v[222:223], s[40:41], 0, v[140:141]
	s_mov_b32 m0, s2
	ds_read_b128 v[190:193], v180 offset:16384
	ds_read_b128 v[194:197], v180 offset:17408
	ds_read_b128 v[198:201], v180 offset:18432
	ds_read_b128 v[202:205], v180 offset:19456
	ds_read_b128 v[206:209], v180 offset:20480
	ds_read_b128 v[210:213], v180 offset:21504
	ds_read_b128 v[214:217], v180 offset:22528
	ds_read_b128 v[218:221], v180 offset:23552
	global_load_lds_dwordx4 v[222:223], off
	s_add_i32 m0, s2, 0x2000
	s_add_u32 s34, s40, 0x40000
	v_lshl_add_u64 v[224:225], s[40:41], 0, v[144:145]
	s_addc_u32 s35, s41, 0
	s_add_i32 s2, s53, s3
	global_load_lds_dwordx4 v[224:225], off
	v_lshl_add_u64 v[226:227], s[34:35], 0, v[140:141]
	s_mov_b32 m0, s2
	s_nop 0
	global_load_lds_dwordx4 v[226:227], off
	v_lshl_add_u64 v[226:227], s[34:35], 0, v[144:145]
	s_add_i32 m0, s2, 0x2000
	s_nop 0
	global_load_lds_dwordx4 v[226:227], off
	v_lshl_add_u64 v[226:227], s[42:43], 0, v[138:139]
	s_mov_b32 m0, s31
	s_nop 0
	global_load_lds_dwordx4 v[226:227], off
	v_lshl_add_u64 v[226:227], s[42:43], 0, v[142:143]
	s_mov_b32 m0, s44
	s_nop 0
	global_load_lds_dwordx4 v[226:227], off
	s_waitcnt vmcnt(8)
	s_waitcnt lgkmcnt(0)
	s_barrier
; #define PG8_STAGE(bufoff, gbase, voff) do { _Pragma("unroll") for (int _i = 0; _i < 2; ++_i) \
;         __builtin_amdgcn_global_load_lds((const unsigned*)((const char*)(gbase) + (voff)[_i]), (PG8_LAS unsigned*)(lds + (bufoff) + ldsw + _i * 8192), 16, 0, 0); } while (0)
; #define PG8_LDA(dst, b, h) do { _Pragma("unroll") for (int m = 0; m < 4; ++m) _Pragma("unroll") for (int k = 0; k < 2; ++k) dst[m][k] = *(const PG8_LAS bf16x8*)(lds + PG8_SA(b, h) + aoff + m * 2048 + k * 1024); } while (0)
; #define PG8_LDB(dst, b, h) do { _Pragma("unroll") for (int n = 0; n < 2; ++n) _Pragma("unroll") for (int k = 0; k < 2; ++k) dst[n][k] = *(const PG8_LAS bf16x8*)(lds + PG8_SB(b, h) + boff + n * 2048 + k * 1024); } while (0)
; #define PG8_MMA(ai, bj, At, Bt) do { __builtin_amdgcn_s_setprio(1); _Pragma("unroll") for (int m = 0; m < 4; ++m) _Pragma("unroll") for (int n = 0; n < 2; ++n) _Pragma("unroll") for (int k = 0; k < 2; ++k) \
;         acc[ai][bj][m][n] = __builtin_amdgcn_mfma_f32_16x16x32_bf16(Bt[n][k], At[m][k], acc[ai][bj][m][n], 0, 0, 0); __builtin_amdgcn_s_setprio(0); } while (0)
; #define PG8_WAIT_V(n) asm volatile("s_waitcnt vmcnt(" #n ")" ::: "memory")
; #define PG8_WAIT_L(n) asm volatile("s_waitcnt lgkmcnt(" #n ")" ::: "memory")
; #define PG8_BAR __builtin_amdgcn_s_barrier()
; #define PG8_SCHED __builtin_amdgcn_sched_barrier(0)
; template <class Epi, class Sched, bool ALIGN_EPI>
; __device__ __forceinline__ void gemm_phase(PG8_LAS unsigned char* lds, const Gemm g, const Sched& S, const Epi& E) {
;     ...
;             PG8_WAIT_V(8); PG8_WAIT_L(0); PG8_BAR; PG8_MMA(1, 0, At, B0); PG8_MMA(1, 1, At, B1); PG8_BAR; PG8_SCHED;
;             PG8_LDB(B0, 1, 0); PG8_LDB(B1, 1, 1); PG8_SCHED; PG8_LDA(At, 1, 0); PG8_STAGE(PG8_SA(0, 1), a2 + hstepA, voffA);
;             PG8_WAIT_V(8); PG8_WAIT_L(0); PG8_BAR; PG8_MMA(0, 0, At, B0); PG8_MMA(0, 1, At, B1); PG8_BAR; PG8_SCHED;
	s_setprio 1
	s_waitcnt lgkmcnt(0)
	v_mfma_f32_16x16x32_bf16 v[94:97], v[114:117], v[190:193], v[94:97]
	v_mfma_f32_16x16x32_bf16 v[94:97], v[118:121], v[194:197], v[94:97]
	v_mfma_f32_16x16x32_bf16 v[90:93], v[160:163], v[194:197], v[90:93]
	v_mfma_f32_16x16x32_bf16 v[90:93], v[156:159], v[190:193], v[90:93]
	v_mfma_f32_16x16x32_bf16 v[82:85], v[156:159], v[198:201], v[82:85]
	v_mfma_f32_16x16x32_bf16 v[82:85], v[160:163], v[202:205], v[82:85]
	v_mfma_f32_16x16x32_bf16 v[86:89], v[118:121], v[202:205], v[86:89]
	v_mfma_f32_16x16x32_bf16 v[86:89], v[114:117], v[198:201], v[86:89]
	v_mfma_f32_16x16x32_bf16 v[78:81], v[114:117], v[206:209], v[78:81]
	v_mfma_f32_16x16x32_bf16 v[78:81], v[118:121], v[210:213], v[78:81]
	v_mfma_f32_16x16x32_bf16 v[74:77], v[160:163], v[210:213], v[74:77]
	v_mfma_f32_16x16x32_bf16 v[74:77], v[156:159], v[206:209], v[74:77]
	v_mfma_f32_16x16x32_bf16 v[66:69], v[156:159], v[214:217], v[66:69]
	v_mfma_f32_16x16x32_bf16 v[66:69], v[160:163], v[218:221], v[66:69]
	v_mfma_f32_16x16x32_bf16 v[70:73], v[118:121], v[218:221], v[70:73]
	v_mfma_f32_16x16x32_bf16 v[70:73], v[114:117], v[214:217], v[70:73]
	s_setprio 0
	s_setprio 1
	v_mfma_f32_16x16x32_bf16 v[30:33], v[164:167], v[190:193], v[30:33]
	v_mfma_f32_16x16x32_bf16 v[30:33], v[168:171], v[194:197], v[30:33]
	v_mfma_f32_16x16x32_bf16 v[26:29], v[186:189], v[194:197], v[26:29]
	v_mfma_f32_16x16x32_bf16 v[26:29], v[182:185], v[190:193], v[26:29]
	v_mfma_f32_16x16x32_bf16 v[18:21], v[182:185], v[198:201], v[18:21]
	v_mfma_f32_16x16x32_bf16 v[18:21], v[186:189], v[202:205], v[18:21]
	v_mfma_f32_16x16x32_bf16 v[22:25], v[168:171], v[202:205], v[22:25]
	v_mfma_f32_16x16x32_bf16 v[22:25], v[164:167], v[198:201], v[22:25]
	v_mfma_f32_16x16x32_bf16 v[14:17], v[164:167], v[206:209], v[14:17]
	v_mfma_f32_16x16x32_bf16 v[14:17], v[168:171], v[210:213], v[14:17]
	v_mfma_f32_16x16x32_bf16 v[10:13], v[186:189], v[210:213], v[10:13]
	v_mfma_f32_16x16x32_bf16 v[10:13], v[182:185], v[206:209], v[10:13]
	v_mfma_f32_16x16x32_bf16 v[2:5], v[182:185], v[214:217], v[2:5]
	v_mfma_f32_16x16x32_bf16 v[2:5], v[186:189], v[218:221], v[2:5]
	v_mfma_f32_16x16x32_bf16 v[6:9], v[168:171], v[218:221], v[6:9]
	v_mfma_f32_16x16x32_bf16 v[6:9], v[164:167], v[214:217], v[6:9]
	s_setprio 0
	s_barrier
	s_add_i32 s2, 0, 0x18000
	s_add_i32 s23, 0, 0x1c000
	v_add_u32_e32 v160, s2, v175
	v_add_u32_e32 v181, s23, v175
	ds_read_b128 v[114:117], v160
	ds_read_b128 v[118:121], v160 offset:1024
	ds_read_b128 v[156:159], v160 offset:2048
	ds_read_b128 v[160:163], v160 offset:3072
	ds_read_b128 v[164:167], v181
	ds_read_b128 v[168:171], v181 offset:1024
	ds_read_b128 v[182:185], v181 offset:2048
	ds_read_b128 v[186:189], v181 offset:3072
	s_add_u32 s34, s42, 0x1000
	s_addc_u32 s35, s43, 0
	s_mov_b32 m0, s45
	v_lshl_add_u64 v[226:227], s[34:35], 0, v[138:139]
	ds_read_b128 v[190:193], v180 offset:32768
	ds_read_b128 v[194:197], v180 offset:33792
	ds_read_b128 v[198:201], v180 offset:34816
	ds_read_b128 v[202:205], v180 offset:35840
	ds_read_b128 v[206:209], v180 offset:36864
	ds_read_b128 v[210:213], v180 offset:37888
	ds_read_b128 v[214:217], v180 offset:38912
	ds_read_b128 v[218:221], v180 offset:39936
	global_load_lds_dwordx4 v[226:227], off
	v_lshl_add_u64 v[226:227], s[34:35], 0, v[142:143]
	s_mov_b32 m0, s46
	s_nop 0
	global_load_lds_dwordx4 v[226:227], off
	s_waitcnt vmcnt(8)
	s_waitcnt lgkmcnt(0)
	s_barrier
	s_setprio 1
	s_waitcnt lgkmcnt(0)
	v_mfma_f32_16x16x32_bf16 v[134:137], v[114:117], v[190:193], v[134:137]
	v_mfma_f32_16x16x32_bf16 v[134:137], v[118:121], v[194:197], v[134:137]
	v_mfma_f32_16x16x32_bf16 v[130:133], v[160:163], v[194:197], v[130:133]
	v_mfma_f32_16x16x32_bf16 v[130:133], v[156:159], v[190:193], v[130:133]
	v_mfma_f32_16x16x32_bf16 v[122:125], v[156:159], v[198:201], v[122:125]
	v_mfma_f32_16x16x32_bf16 v[122:125], v[160:163], v[202:205], v[122:125]
	v_mfma_f32_16x16x32_bf16 v[126:129], v[118:121], v[202:205], v[126:129]
	v_mfma_f32_16x16x32_bf16 v[126:129], v[114:117], v[198:201], v[126:129]
	v_mfma_f32_16x16x32_bf16 v[110:113], v[114:117], v[206:209], v[110:113]
	v_mfma_f32_16x16x32_bf16 v[110:113], v[118:121], v[210:213], v[110:113]
	v_mfma_f32_16x16x32_bf16 v[106:109], v[160:163], v[210:213], v[106:109]
	v_mfma_f32_16x16x32_bf16 v[106:109], v[156:159], v[206:209], v[106:109]
	v_mfma_f32_16x16x32_bf16 v[98:101], v[156:159], v[214:217], v[98:101]
	v_mfma_f32_16x16x32_bf16 v[98:101], v[160:163], v[218:221], v[98:101]
	v_mfma_f32_16x16x32_bf16 v[102:105], v[118:121], v[218:221], v[102:105]
	v_mfma_f32_16x16x32_bf16 v[102:105], v[114:117], v[214:217], v[102:105]
	s_setprio 0
	s_setprio 1
	v_mfma_f32_16x16x32_bf16 v[62:65], v[164:167], v[190:193], v[62:65]
	v_mfma_f32_16x16x32_bf16 v[62:65], v[168:171], v[194:197], v[62:65]
	v_mfma_f32_16x16x32_bf16 v[58:61], v[186:189], v[194:197], v[58:61]
	v_mfma_f32_16x16x32_bf16 v[58:61], v[182:185], v[190:193], v[58:61]
	v_mfma_f32_16x16x32_bf16 v[50:53], v[182:185], v[198:201], v[50:53]
	v_mfma_f32_16x16x32_bf16 v[50:53], v[186:189], v[202:205], v[50:53]
	v_mfma_f32_16x16x32_bf16 v[54:57], v[168:171], v[202:205], v[54:57]
	v_mfma_f32_16x16x32_bf16 v[54:57], v[164:167], v[198:201], v[54:57]
	v_mfma_f32_16x16x32_bf16 v[46:49], v[164:167], v[206:209], v[46:49]
	v_mfma_f32_16x16x32_bf16 v[46:49], v[168:171], v[210:213], v[46:49]
	v_mfma_f32_16x16x32_bf16 v[42:45], v[186:189], v[210:213], v[42:45]
	v_mfma_f32_16x16x32_bf16 v[42:45], v[182:185], v[206:209], v[42:45]
	v_mfma_f32_16x16x32_bf16 v[34:37], v[182:185], v[214:217], v[34:37]
	v_mfma_f32_16x16x32_bf16 v[34:37], v[186:189], v[218:221], v[34:37]
	v_mfma_f32_16x16x32_bf16 v[38:41], v[168:171], v[218:221], v[38:41]
	v_mfma_f32_16x16x32_bf16 v[38:41], v[164:167], v[214:217], v[38:41]
	s_setprio 0
	s_barrier
; #define PG8_STAGE(bufoff, gbase, voff) do { _Pragma("unroll") for (int _i = 0; _i < 2; ++_i) \
;         __builtin_amdgcn_global_load_lds((const unsigned*)((const char*)(gbase) + (voff)[_i]), (PG8_LAS unsigned*)(lds + (bufoff) + ldsw + _i * 8192), 16, 0, 0); } while (0)
; #define PG8_LDA(dst, b, h) do { _Pragma("unroll") for (int m = 0; m < 4; ++m) _Pragma("unroll") for (int k = 0; k < 2; ++k) dst[m][k] = *(const PG8_LAS bf16x8*)(lds + PG8_SA(b, h) + aoff + m * 2048 + k * 1024); } while (0)
; #define PG8_MMA(ai, bj, At, Bt) do { __builtin_amdgcn_s_setprio(1); _Pragma("unroll") for (int m = 0; m < 4; ++m) _Pragma("unroll") for (int n = 0; n < 2; ++n) _Pragma("unroll") for (int k = 0; k < 2; ++k) \
;         acc[ai][bj][m][n] = __builtin_amdgcn_mfma_f32_16x16x32_bf16(Bt[n][k], At[m][k], acc[ai][bj][m][n], 0, 0, 0); __builtin_amdgcn_s_setprio(0); } while (0)
; #define PG8_WAIT_V(n) asm volatile("s_waitcnt vmcnt(" #n ")" ::: "memory")
; #define PG8_WAIT_L(n) asm volatile("s_waitcnt lgkmcnt(" #n ")" ::: "memory")
; #define PG8_BAR __builtin_amdgcn_s_barrier()
; #define PG8_SCHED __builtin_amdgcn_sched_barrier(0)
; template <class Epi, class Sched, bool ALIGN_EPI>
; __device__ __forceinline__ void gemm_phase(PG8_LAS unsigned char* lds, const Gemm g, const Sched& S, const Epi& E) {
;     ...
;             PG8_LDA(At, 1, 1); PG8_STAGE(PG8_SB(1, 0), b3, voffB); PG8_STAGE(PG8_SB(1, 1), b3 + hstepB, voffB); PG8_STAGE(PG8_SA(1, 0), a3, voffA);
;             PG8_WAIT_V(8); PG8_WAIT_L(0); PG8_BAR; PG8_MMA(1, 0, At, B0); PG8_MMA(1, 1, At, B1); PG8_BAR; PG8_SCHED;
;         }
	s_add_i32 s2, s2, s3
	v_lshl_add_u64 v[222:223], v[222:223], 0, s[16:17]
	s_mov_b32 m0, s2
	ds_read_b128 v[190:193], v180 offset:49152
	ds_read_b128 v[194:197], v180 offset:50176
	ds_read_b128 v[198:201], v180 offset:51200
	ds_read_b128 v[202:205], v180 offset:52224
	ds_read_b128 v[206:209], v180 offset:53248
	ds_read_b128 v[210:213], v180 offset:54272
	ds_read_b128 v[214:217], v180 offset:55296
	ds_read_b128 v[218:221], v180 offset:56320
	global_load_lds_dwordx4 v[222:223], off
	s_add_i32 m0, s2, 0x2000
	s_add_u32 s34, s40, 0x40080
	v_lshl_add_u64 v[222:223], v[224:225], 0, s[16:17]
	s_addc_u32 s35, s41, 0
	s_add_i32 s2, s23, s3
	global_load_lds_dwordx4 v[222:223], off
	v_lshl_add_u64 v[222:223], s[34:35], 0, v[140:141]
	s_mov_b32 m0, s2
	s_nop 0
	global_load_lds_dwordx4 v[222:223], off
	v_lshl_add_u64 v[222:223], s[34:35], 0, v[144:145]
	s_add_i32 m0, s2, 0x2000
	s_nop 0
	global_load_lds_dwordx4 v[222:223], off
	v_lshl_add_u64 v[222:223], s[38:39], 0, v[138:139]
	s_mov_b32 m0, s48
	s_nop 0
	global_load_lds_dwordx4 v[222:223], off
	v_lshl_add_u64 v[222:223], s[38:39], 0, v[142:143]
	s_mov_b32 m0, s49
	s_nop 0
	global_load_lds_dwordx4 v[222:223], off
	s_waitcnt vmcnt(8)
	s_waitcnt lgkmcnt(0)
	s_barrier
	s_setprio 1
	s_waitcnt lgkmcnt(0)
	v_mfma_f32_16x16x32_bf16 v[94:97], v[114:117], v[190:193], v[94:97]
	v_mfma_f32_16x16x32_bf16 v[94:97], v[118:121], v[194:197], v[94:97]
	v_mfma_f32_16x16x32_bf16 v[90:93], v[160:163], v[194:197], v[90:93]
	v_mfma_f32_16x16x32_bf16 v[90:93], v[156:159], v[190:193], v[90:93]
	v_mfma_f32_16x16x32_bf16 v[82:85], v[156:159], v[198:201], v[82:85]
	v_mfma_f32_16x16x32_bf16 v[82:85], v[160:163], v[202:205], v[82:85]
	v_mfma_f32_16x16x32_bf16 v[86:89], v[118:121], v[202:205], v[86:89]
	v_mfma_f32_16x16x32_bf16 v[86:89], v[114:117], v[198:201], v[86:89]
	v_mfma_f32_16x16x32_bf16 v[78:81], v[114:117], v[206:209], v[78:81]
	v_mfma_f32_16x16x32_bf16 v[78:81], v[118:121], v[210:213], v[78:81]
	v_mfma_f32_16x16x32_bf16 v[74:77], v[160:163], v[210:213], v[74:77]
	v_mfma_f32_16x16x32_bf16 v[74:77], v[156:159], v[206:209], v[74:77]
	v_mfma_f32_16x16x32_bf16 v[66:69], v[156:159], v[214:217], v[66:69]
	v_mfma_f32_16x16x32_bf16 v[66:69], v[160:163], v[218:221], v[66:69]
	v_mfma_f32_16x16x32_bf16 v[70:73], v[118:121], v[218:221], v[70:73]
	v_mfma_f32_16x16x32_bf16 v[70:73], v[114:117], v[214:217], v[70:73]
	s_setprio 0
	s_setprio 1
	v_mfma_f32_16x16x32_bf16 v[30:33], v[164:167], v[190:193], v[30:33]
	v_mfma_f32_16x16x32_bf16 v[30:33], v[168:171], v[194:197], v[30:33]
	v_mfma_f32_16x16x32_bf16 v[26:29], v[186:189], v[194:197], v[26:29]
	v_mfma_f32_16x16x32_bf16 v[26:29], v[182:185], v[190:193], v[26:29]
	v_mfma_f32_16x16x32_bf16 v[18:21], v[182:185], v[198:201], v[18:21]
	v_mfma_f32_16x16x32_bf16 v[18:21], v[186:189], v[202:205], v[18:21]
	v_mfma_f32_16x16x32_bf16 v[22:25], v[168:171], v[202:205], v[22:25]
	v_mfma_f32_16x16x32_bf16 v[22:25], v[164:167], v[198:201], v[22:25]
	v_mfma_f32_16x16x32_bf16 v[14:17], v[164:167], v[206:209], v[14:17]
	v_mfma_f32_16x16x32_bf16 v[14:17], v[168:171], v[210:213], v[14:17]
	v_mfma_f32_16x16x32_bf16 v[10:13], v[186:189], v[210:213], v[10:13]
	v_mfma_f32_16x16x32_bf16 v[10:13], v[182:185], v[206:209], v[10:13]
	v_mfma_f32_16x16x32_bf16 v[2:5], v[182:185], v[214:217], v[2:5]
	v_mfma_f32_16x16x32_bf16 v[2:5], v[186:189], v[218:221], v[2:5]
	v_mfma_f32_16x16x32_bf16 v[6:9], v[168:171], v[218:221], v[6:9]
	v_mfma_f32_16x16x32_bf16 v[6:9], v[164:167], v[214:217], v[6:9]
	s_setprio 0
	s_barrier
	s_add_i32 s21, s21, 2
	s_add_u32 s4, s4, 0x100
	s_addc_u32 s5, s5, 0
	s_cmp_gt_u32 s21, 13
	s_mov_b64 s[34:35], s[36:37]
	s_cbranch_scc0 .LBB0_778
	s_and_b64 vcc, exec, s[18:19]
	s_cbranch_vccz .LBB0_781
	s_barrier

; #define PG8_STAGE(bufoff, gbase, voff) do { _Pragma("unroll") for (int _i = 0; _i < 2; ++_i) \
;         __builtin_amdgcn_global_load_lds((const unsigned*)((const char*)(gbase) + (voff)[_i]), (PG8_LAS unsigned*)(lds + (bufoff) + ldsw + _i * 8192), 16, 0, 0); } while (0)
; #define PG8_LDA(dst, b, h) do { _Pragma("unroll") for (int m = 0; m < 4; ++m) _Pragma("unroll") for (int k = 0; k < 2; ++k) dst[m][k] = *(const PG8_LAS bf16x8*)(lds + PG8_SA(b, h) + aoff + m * 2048 + k * 1024); } while (0)
; #define PG8_LDB(dst, b, h) do { _Pragma("unroll") for (int n = 0; n < 2; ++n) _Pragma("unroll") for (int k = 0; k < 2; ++k) dst[n][k] = *(const PG8_LAS bf16x8*)(lds + PG8_SB(b, h) + boff + n * 2048 + k * 1024); } while (0)
; #define PG8_BAR __builtin_amdgcn_s_barrier()
; template <class Epi, class Sched, bool ALIGN_EPI>
; __device__ __forceinline__ void gemm_phase(PG8_LAS unsigned char* lds, const Gemm g, const Sched& S, const Epi& E) {
;     ...
;             PG8_LDB(B0, 0, 0); PG8_LDB(B1, 0, 1); PG8_SCHED; PG8_LDA(At, 0, 0); PG8_STAGE(PG8_SA(1, 1), a1 + hstepA, voffA);
;             PG8_WAIT_V(8); PG8_WAIT_L(0); PG8_BAR; PG8_MMA(0, 0, At, B0); PG8_MMA(0, 1, At, B1); PG8_BAR; PG8_SCHED;
;             PG8_LDA(At, 0, 1); PG8_STAGE(PG8_SB(0, 0), b2, voffB); PG8_STAGE(PG8_SB(0, 1), b2 + hstepB, voffB); PG8_STAGE(PG8_SA(0, 0), a2, voffA);
;             PG8_WAIT_V(8); PG8_WAIT_L(0); PG8_BAR; PG8_MMA(1, 0, At, B0); PG8_MMA(1, 1, At, B1); PG8_BAR; PG8_SCHED;
; __global__ void __launch_bounds__(NWAVES * 64, 2) hymba_fwd(Args a) {
;     ...
;         pg8::Gemm g{A3, Wo_t, DM, DM, DM}; pg8::StaticOrder S; S.init(M, DM, G, bx);
;         LAS float* ratl = (LAS float*)(lds + LDSCTL_OFF + 2048); LAS float* rsl = ratl + 256;
;         if (tid_l < 256) { const int row = team_pm * 256 + tid_l;
;             const float sa = __uint_as_float(__hip_atomic_load((const unsigned*)(stat_a + row), __ATOMIC_RELAXED, __HIP_MEMORY_SCOPE_AGENT)), ss = __uint_as_float(__hip_atomic_load((const unsigned*)(stat_s + row), __ATOMIC_RELAXED, __HIP_MEMORY_SCOPE_AGENT));
;             const float ra = 1.0f / sqrtf(sa * (1.0f / 1024.0f) + RMS_EPS), rsi = sqrtf(ss * (1.0f / 1024.0f) + RMS_EPS);
;             ratl[tid_l] = ra * rsi; rsl[tid_l] = 1.0f / rsi; }
;         LDS_WAIT(); __syncthreads();
;         pg8::EpiMix E{MIX, DM, ratl, rsl};
;         pg8::gemm_phase<pg8::EpiMix, pg8::StaticOrder, true>(lds, g, S, E);
.LBB0_839:
	v_add_u32_e32 v3, s55, v155
	ds_read_b128 v[160:163], v3
	ds_read_b128 v[164:167], v3 offset:1024
	ds_read_b128 v[168:171], v3 offset:2048
	ds_read_b128 v[174:177], v3 offset:3072
	v_add_u32_e32 v3, s56, v155
	s_add_u32 s2, s38, s40
	ds_read_b128 v[178:181], v3
	ds_read_b128 v[182:185], v3 offset:1024
	ds_read_b128 v[186:189], v3 offset:2048
	ds_read_b128 v[190:193], v3 offset:3072
	s_addc_u32 s42, s39, s41
	s_add_u32 s2, s2, 0x100
	s_addc_u32 s42, s42, 0
	s_add_u32 s63, s27, s40
	s_addc_u32 s43, s29, s41
	s_cmpk_eq_i32 s40, 0xf00
	s_cselect_b32 s45, s31, s42
	s_cselect_b32 s44, s30, s2
	s_cselect_b32 s43, s35, s43
	s_cselect_b32 s42, s34, s63
	v_lshl_add_u64 v[4:5], v[150:151], 0, s[40:41]
	s_add_i32 m0, s37, 0xc000
	ds_read_b128 v[194:197], v159
	ds_read_b128 v[198:201], v159 offset:1024
	ds_read_b128 v[202:205], v159 offset:2048
	ds_read_b128 v[206:209], v159 offset:3072
	ds_read_b128 v[210:213], v159 offset:4096
	ds_read_b128 v[214:217], v159 offset:5120
	ds_read_b128 v[218:221], v159 offset:6144
	ds_read_b128 v[222:225], v159 offset:7168
	global_load_lds_dwordx4 v[4:5], off
	v_lshl_add_u64 v[4:5], v[152:153], 0, s[40:41]
	s_add_i32 m0, s37, 0xe000
	s_nop 0
	global_load_lds_dwordx4 v[4:5], off
	s_waitcnt vmcnt(8)
	s_waitcnt lgkmcnt(0)
	s_barrier
	s_setprio 1
	s_waitcnt lgkmcnt(0)
	v_mfma_f32_16x16x32_bf16 v[130:133], v[160:163], v[194:197], v[130:133]
	v_mfma_f32_16x16x32_bf16 v[130:133], v[164:167], v[198:201], v[130:133]
	v_mfma_f32_16x16x32_bf16 v[126:129], v[174:177], v[198:201], v[126:129]
	v_mfma_f32_16x16x32_bf16 v[126:129], v[168:171], v[194:197], v[126:129]
	v_mfma_f32_16x16x32_bf16 v[110:113], v[168:171], v[202:205], v[110:113]
	v_mfma_f32_16x16x32_bf16 v[110:113], v[174:177], v[206:209], v[110:113]
	v_mfma_f32_16x16x32_bf16 v[114:117], v[164:167], v[206:209], v[114:117]
	v_mfma_f32_16x16x32_bf16 v[114:117], v[160:163], v[202:205], v[114:117]
	v_mfma_f32_16x16x32_bf16 v[98:101], v[160:163], v[210:213], v[98:101]
	v_mfma_f32_16x16x32_bf16 v[98:101], v[164:167], v[214:217], v[98:101]
	v_mfma_f32_16x16x32_bf16 v[94:97], v[174:177], v[214:217], v[94:97]
	v_mfma_f32_16x16x32_bf16 v[94:97], v[168:171], v[210:213], v[94:97]
	v_mfma_f32_16x16x32_bf16 v[78:81], v[168:171], v[218:221], v[78:81]
	v_mfma_f32_16x16x32_bf16 v[78:81], v[174:177], v[222:225], v[78:81]
	v_mfma_f32_16x16x32_bf16 v[82:85], v[164:167], v[222:225], v[82:85]
	v_mfma_f32_16x16x32_bf16 v[82:85], v[160:163], v[218:221], v[82:85]
	s_setprio 0
	s_setprio 1
	v_mfma_f32_16x16x32_bf16 v[122:125], v[178:181], v[194:197], v[122:125]
	v_mfma_f32_16x16x32_bf16 v[122:125], v[182:185], v[198:201], v[122:125]
	v_mfma_f32_16x16x32_bf16 v[118:121], v[190:193], v[198:201], v[118:121]
	v_mfma_f32_16x16x32_bf16 v[118:121], v[186:189], v[194:197], v[118:121]
	v_mfma_f32_16x16x32_bf16 v[102:105], v[186:189], v[202:205], v[102:105]
	v_mfma_f32_16x16x32_bf16 v[102:105], v[190:193], v[206:209], v[102:105]
	v_mfma_f32_16x16x32_bf16 v[106:109], v[182:185], v[206:209], v[106:109]
	v_mfma_f32_16x16x32_bf16 v[106:109], v[178:181], v[202:205], v[106:109]
	v_mfma_f32_16x16x32_bf16 v[90:93], v[178:181], v[210:213], v[90:93]
	v_mfma_f32_16x16x32_bf16 v[90:93], v[182:185], v[214:217], v[90:93]
	v_mfma_f32_16x16x32_bf16 v[86:89], v[190:193], v[214:217], v[86:89]
	v_mfma_f32_16x16x32_bf16 v[86:89], v[186:189], v[210:213], v[86:89]
	v_mfma_f32_16x16x32_bf16 v[70:73], v[186:189], v[218:221], v[70:73]
	v_mfma_f32_16x16x32_bf16 v[70:73], v[190:193], v[222:225], v[70:73]
	v_mfma_f32_16x16x32_bf16 v[74:77], v[182:185], v[222:225], v[74:77]
	v_mfma_f32_16x16x32_bf16 v[74:77], v[178:181], v[218:221], v[74:77]
	s_setprio 0
	s_barrier
	s_add_i32 s2, s55, s4
	v_lshl_add_u64 v[226:227], s[42:43], 0, v[136:137]
	s_mov_b32 m0, s2
	ds_read_b128 v[194:197], v159 offset:16384
	ds_read_b128 v[198:201], v159 offset:17408
	ds_read_b128 v[202:205], v159 offset:18432
	ds_read_b128 v[206:209], v159 offset:19456
	ds_read_b128 v[210:213], v159 offset:20480
	ds_read_b128 v[214:217], v159 offset:21504
	ds_read_b128 v[218:221], v159 offset:22528
	ds_read_b128 v[222:225], v159 offset:23552
	global_load_lds_dwordx4 v[226:227], off
	s_add_i32 m0, s2, 0x2000
	s_add_u32 s64, s42, 0x80000
	v_lshl_add_u64 v[228:229], s[42:43], 0, v[140:141]
	s_addc_u32 s65, s43, 0
	s_add_i32 s2, s56, s4
	global_load_lds_dwordx4 v[228:229], off
	v_lshl_add_u64 v[4:5], s[64:65], 0, v[136:137]
	s_mov_b32 m0, s2
	v_lshl_add_u64 v[230:231], s[44:45], 0, v[134:135]
	global_load_lds_dwordx4 v[4:5], off
	v_lshl_add_u64 v[4:5], s[64:65], 0, v[140:141]
	s_add_i32 m0, s2, 0x2000
	v_lshl_add_u64 v[232:233], s[44:45], 0, v[138:139]
	global_load_lds_dwordx4 v[4:5], off
	s_mov_b32 m0, s37
	s_nop 0
	global_load_lds_dwordx4 v[230:231], off
	s_mov_b32 m0, s48
	s_nop 0
	global_load_lds_dwordx4 v[232:233], off
	s_waitcnt vmcnt(8)
	s_waitcnt lgkmcnt(0)
	s_barrier
; #define PG8_STAGE(bufoff, gbase, voff) do { _Pragma("unroll") for (int _i = 0; _i < 2; ++_i) \
;         __builtin_amdgcn_global_load_lds((const unsigned*)((const char*)(gbase) + (voff)[_i]), (PG8_LAS unsigned*)(lds + (bufoff) + ldsw + _i * 8192), 16, 0, 0); } while (0)
; #define PG8_LDA(dst, b, h) do { _Pragma("unroll") for (int m = 0; m < 4; ++m) _Pragma("unroll") for (int k = 0; k < 2; ++k) dst[m][k] = *(const PG8_LAS bf16x8*)(lds + PG8_SA(b, h) + aoff + m * 2048 + k * 1024); } while (0)
; #define PG8_LDB(dst, b, h) do { _Pragma("unroll") for (int n = 0; n < 2; ++n) _Pragma("unroll") for (int k = 0; k < 2; ++k) dst[n][k] = *(const PG8_LAS bf16x8*)(lds + PG8_SB(b, h) + boff + n * 2048 + k * 1024); } while (0)
; #define PG8_MMA(ai, bj, At, Bt) do { __builtin_amdgcn_s_setprio(1); _Pragma("unroll") for (int m = 0; m < 4; ++m) _Pragma("unroll") for (int n = 0; n < 2; ++n) _Pragma("unroll") for (int k = 0; k < 2; ++k) \
;         acc[ai][bj][m][n] = __builtin_amdgcn_mfma_f32_16x16x32_bf16(Bt[n][k], At[m][k], acc[ai][bj][m][n], 0, 0, 0); __builtin_amdgcn_s_setprio(0); } while (0)
; #define PG8_WAIT_V(n) asm volatile("s_waitcnt vmcnt(" #n ")" ::: "memory")
; #define PG8_WAIT_L(n) asm volatile("s_waitcnt lgkmcnt(" #n ")" ::: "memory")
; #define PG8_BAR __builtin_amdgcn_s_barrier()
; #define PG8_SCHED __builtin_amdgcn_sched_barrier(0)
; template <class Epi, class Sched, bool ALIGN_EPI>
; __device__ __forceinline__ void gemm_phase(PG8_LAS unsigned char* lds, const Gemm g, const Sched& S, const Epi& E) {
;     ...
;             PG8_WAIT_V(8); PG8_WAIT_L(0); PG8_BAR; PG8_MMA(1, 0, At, B0); PG8_MMA(1, 1, At, B1); PG8_BAR; PG8_SCHED;
;             PG8_LDB(B0, 1, 0); PG8_LDB(B1, 1, 1); PG8_SCHED; PG8_LDA(At, 1, 0); PG8_STAGE(PG8_SA(0, 1), a2 + hstepA, voffA);
;             PG8_WAIT_V(8); PG8_WAIT_L(0); PG8_BAR; PG8_MMA(0, 0, At, B0); PG8_MMA(0, 1, At, B1); PG8_BAR; PG8_SCHED;
	s_setprio 1
	s_waitcnt lgkmcnt(0)
	v_mfma_f32_16x16x32_bf16 v[66:69], v[160:163], v[194:197], v[66:69]
	v_mfma_f32_16x16x32_bf16 v[66:69], v[164:167], v[198:201], v[66:69]
	v_mfma_f32_16x16x32_bf16 v[62:65], v[174:177], v[198:201], v[62:65]
	v_mfma_f32_16x16x32_bf16 v[62:65], v[168:171], v[194:197], v[62:65]
	v_mfma_f32_16x16x32_bf16 v[46:49], v[168:171], v[202:205], v[46:49]
	v_mfma_f32_16x16x32_bf16 v[46:49], v[174:177], v[206:209], v[46:49]
	v_mfma_f32_16x16x32_bf16 v[50:53], v[164:167], v[206:209], v[50:53]
	v_mfma_f32_16x16x32_bf16 v[50:53], v[160:163], v[202:205], v[50:53]
	v_mfma_f32_16x16x32_bf16 v[34:37], v[160:163], v[210:213], v[34:37]
	v_mfma_f32_16x16x32_bf16 v[34:37], v[164:167], v[214:217], v[34:37]
	v_mfma_f32_16x16x32_bf16 v[30:33], v[174:177], v[214:217], v[30:33]
	v_mfma_f32_16x16x32_bf16 v[30:33], v[168:171], v[210:213], v[30:33]
	v_mfma_f32_16x16x32_bf16 v[14:17], v[168:171], v[218:221], v[14:17]
	v_mfma_f32_16x16x32_bf16 v[14:17], v[174:177], v[222:225], v[14:17]
	v_mfma_f32_16x16x32_bf16 v[18:21], v[164:167], v[222:225], v[18:21]
	v_mfma_f32_16x16x32_bf16 v[18:21], v[160:163], v[218:221], v[18:21]
	s_setprio 0
	s_setprio 1
	v_mfma_f32_16x16x32_bf16 v[58:61], v[178:181], v[194:197], v[58:61]
	v_mfma_f32_16x16x32_bf16 v[54:57], v[186:189], v[194:197], v[54:57]
	v_mfma_f32_16x16x32_bf16 v[42:45], v[178:181], v[202:205], v[42:45]
	v_mfma_f32_16x16x32_bf16 v[38:41], v[186:189], v[202:205], v[38:41]
	v_mfma_f32_16x16x32_bf16 v[26:29], v[178:181], v[210:213], v[26:29]
	v_mfma_f32_16x16x32_bf16 v[22:25], v[186:189], v[210:213], v[22:25]
	v_mfma_f32_16x16x32_bf16 v[10:13], v[178:181], v[218:221], v[10:13]
	v_mfma_f32_16x16x32_bf16 v[4:7], v[186:189], v[218:221], v[6:9]
	v_mfma_f32_16x16x32_bf16 v[58:61], v[182:185], v[198:201], v[58:61]
	v_mfma_f32_16x16x32_bf16 v[54:57], v[190:193], v[198:201], v[54:57]
	v_mfma_f32_16x16x32_bf16 v[42:45], v[182:185], v[206:209], v[42:45]
	v_mfma_f32_16x16x32_bf16 v[38:41], v[190:193], v[206:209], v[38:41]
	v_mfma_f32_16x16x32_bf16 v[26:29], v[182:185], v[214:217], v[26:29]
	v_mfma_f32_16x16x32_bf16 v[22:25], v[190:193], v[214:217], v[22:25]
	v_mfma_f32_16x16x32_bf16 v[10:13], v[182:185], v[222:225], v[10:13]
	v_mfma_f32_16x16x32_bf16 v[4:7], v[190:193], v[222:225], v[4:7]
	s_setprio 0
	s_barrier
	s_add_i32 s2, 0, 0x18000
	v_add_u32_e32 v3, s2, v155
	s_add_i32 s63, 0, 0x1c000
	ds_read_b128 v[160:163], v3
	ds_read_b128 v[164:167], v3 offset:1024
	ds_read_b128 v[168:171], v3 offset:2048
	ds_read_b128 v[174:177], v3 offset:3072
	v_add_u32_e32 v3, s63, v155
	ds_read_b128 v[178:181], v3
	ds_read_b128 v[182:185], v3 offset:1024
	ds_read_b128 v[186:189], v3 offset:2048
	ds_read_b128 v[190:193], v3 offset:3072
	s_add_u32 s44, s44, 0x80000
	s_addc_u32 s45, s45, 0
	s_mov_b32 m0, s49
	v_lshl_add_u64 v[8:9], s[44:45], 0, v[134:135]
	ds_read_b128 v[194:197], v159 offset:32768
	ds_read_b128 v[198:201], v159 offset:33792
	ds_read_b128 v[202:205], v159 offset:34816
	ds_read_b128 v[206:209], v159 offset:35840
	ds_read_b128 v[210:213], v159 offset:36864
	ds_read_b128 v[214:217], v159 offset:37888
	ds_read_b128 v[218:221], v159 offset:38912
	ds_read_b128 v[222:225], v159 offset:39936
	global_load_lds_dwordx4 v[8:9], off
	v_lshl_add_u64 v[8:9], s[44:45], 0, v[138:139]
	s_mov_b32 m0, s50
	s_nop 0
	global_load_lds_dwordx4 v[8:9], off
	s_waitcnt vmcnt(8)
	s_waitcnt lgkmcnt(0)
	s_barrier
	s_setprio 1
	s_waitcnt lgkmcnt(0)
	v_mfma_f32_16x16x32_bf16 v[130:133], v[160:163], v[194:197], v[130:133]
	v_mfma_f32_16x16x32_bf16 v[130:133], v[164:167], v[198:201], v[130:133]
	v_mfma_f32_16x16x32_bf16 v[126:129], v[174:177], v[198:201], v[126:129]
	v_mfma_f32_16x16x32_bf16 v[126:129], v[168:171], v[194:197], v[126:129]
	v_mfma_f32_16x16x32_bf16 v[110:113], v[168:171], v[202:205], v[110:113]
	v_mfma_f32_16x16x32_bf16 v[110:113], v[174:177], v[206:209], v[110:113]
	v_mfma_f32_16x16x32_bf16 v[114:117], v[164:167], v[206:209], v[114:117]
	v_mfma_f32_16x16x32_bf16 v[114:117], v[160:163], v[202:205], v[114:117]
	v_mfma_f32_16x16x32_bf16 v[98:101], v[160:163], v[210:213], v[98:101]
	v_mfma_f32_16x16x32_bf16 v[98:101], v[164:167], v[214:217], v[98:101]
	v_mfma_f32_16x16x32_bf16 v[94:97], v[174:177], v[214:217], v[94:97]
	v_mfma_f32_16x16x32_bf16 v[94:97], v[168:171], v[210:213], v[94:97]
	v_mfma_f32_16x16x32_bf16 v[78:81], v[168:171], v[218:221], v[78:81]
	v_mfma_f32_16x16x32_bf16 v[78:81], v[174:177], v[222:225], v[78:81]
	v_mfma_f32_16x16x32_bf16 v[82:85], v[164:167], v[222:225], v[82:85]
	v_mfma_f32_16x16x32_bf16 v[82:85], v[160:163], v[218:221], v[82:85]
	s_setprio 0
	s_setprio 1
	v_mfma_f32_16x16x32_bf16 v[122:125], v[178:181], v[194:197], v[122:125]
	v_mfma_f32_16x16x32_bf16 v[122:125], v[182:185], v[198:201], v[122:125]
	v_mfma_f32_16x16x32_bf16 v[118:121], v[190:193], v[198:201], v[118:121]
	v_mfma_f32_16x16x32_bf16 v[118:121], v[186:189], v[194:197], v[118:121]
	v_mfma_f32_16x16x32_bf16 v[102:105], v[186:189], v[202:205], v[102:105]
	v_mfma_f32_16x16x32_bf16 v[102:105], v[190:193], v[206:209], v[102:105]
	v_mfma_f32_16x16x32_bf16 v[106:109], v[182:185], v[206:209], v[106:109]
	v_mfma_f32_16x16x32_bf16 v[106:109], v[178:181], v[202:205], v[106:109]
	v_mfma_f32_16x16x32_bf16 v[90:93], v[178:181], v[210:213], v[90:93]
	v_mfma_f32_16x16x32_bf16 v[90:93], v[182:185], v[214:217], v[90:93]
	v_mfma_f32_16x16x32_bf16 v[86:89], v[190:193], v[214:217], v[86:89]
	v_mfma_f32_16x16x32_bf16 v[86:89], v[186:189], v[210:213], v[86:89]
	v_mfma_f32_16x16x32_bf16 v[70:73], v[186:189], v[218:221], v[70:73]
	v_mfma_f32_16x16x32_bf16 v[70:73], v[190:193], v[222:225], v[70:73]
	v_mfma_f32_16x16x32_bf16 v[74:77], v[182:185], v[222:225], v[74:77]
	v_mfma_f32_16x16x32_bf16 v[74:77], v[178:181], v[218:221], v[74:77]
	s_setprio 0
	s_barrier
; #define PG8_STAGE(bufoff, gbase, voff) do { _Pragma("unroll") for (int _i = 0; _i < 2; ++_i) \
;         __builtin_amdgcn_global_load_lds((const unsigned*)((const char*)(gbase) + (voff)[_i]), (PG8_LAS unsigned*)(lds + (bufoff) + ldsw + _i * 8192), 16, 0, 0); } while (0)
; #define PG8_LDA(dst, b, h) do { _Pragma("unroll") for (int m = 0; m < 4; ++m) _Pragma("unroll") for (int k = 0; k < 2; ++k) dst[m][k] = *(const PG8_LAS bf16x8*)(lds + PG8_SA(b, h) + aoff + m * 2048 + k * 1024); } while (0)
; #define PG8_MMA(ai, bj, At, Bt) do { __builtin_amdgcn_s_setprio(1); _Pragma("unroll") for (int m = 0; m < 4; ++m) _Pragma("unroll") for (int n = 0; n < 2; ++n) _Pragma("unroll") for (int k = 0; k < 2; ++k) \
;         acc[ai][bj][m][n] = __builtin_amdgcn_mfma_f32_16x16x32_bf16(Bt[n][k], At[m][k], acc[ai][bj][m][n], 0, 0, 0); __builtin_amdgcn_s_setprio(0); } while (0)
; #define PG8_WAIT_V(n) asm volatile("s_waitcnt vmcnt(" #n ")" ::: "memory")
; #define PG8_WAIT_L(n) asm volatile("s_waitcnt lgkmcnt(" #n ")" ::: "memory")
; #define PG8_BAR __builtin_amdgcn_s_barrier()
; #define PG8_SCHED __builtin_amdgcn_sched_barrier(0)
; template <class Epi, class Sched, bool ALIGN_EPI>
; __device__ __forceinline__ void gemm_phase(PG8_LAS unsigned char* lds, const Gemm g, const Sched& S, const Epi& E) {
;     ...
;             PG8_LDA(At, 1, 1); PG8_STAGE(PG8_SB(1, 0), b3, voffB); PG8_STAGE(PG8_SB(1, 1), b3 + hstepB, voffB); PG8_STAGE(PG8_SA(1, 0), a3, voffA);
;             PG8_WAIT_V(8); PG8_WAIT_L(0); PG8_BAR; PG8_MMA(1, 0, At, B0); PG8_MMA(1, 1, At, B1); PG8_BAR; PG8_SCHED;
;         }
	s_add_i32 s2, s2, s4
	v_lshl_add_u64 v[8:9], v[226:227], 0, s[16:17]
	s_mov_b32 m0, s2
	ds_read_b128 v[194:197], v159 offset:49152
	ds_read_b128 v[198:201], v159 offset:50176
	ds_read_b128 v[202:205], v159 offset:51200
	ds_read_b128 v[206:209], v159 offset:52224
	ds_read_b128 v[210:213], v159 offset:53248
	ds_read_b128 v[214:217], v159 offset:54272
	ds_read_b128 v[218:221], v159 offset:55296
	ds_read_b128 v[222:225], v159 offset:56320
	global_load_lds_dwordx4 v[8:9], off
	s_add_i32 m0, s2, 0x2000
	s_add_u32 s42, s42, 0x80080
	v_lshl_add_u64 v[8:9], v[228:229], 0, s[16:17]
	s_addc_u32 s43, s43, 0
	s_add_i32 s2, s63, s4
	global_load_lds_dwordx4 v[8:9], off
	v_lshl_add_u64 v[8:9], s[42:43], 0, v[136:137]
	s_mov_b32 m0, s2
	s_nop 0
	global_load_lds_dwordx4 v[8:9], off
	v_lshl_add_u64 v[8:9], s[42:43], 0, v[140:141]
	s_add_i32 m0, s2, 0x2000
	s_nop 0
	global_load_lds_dwordx4 v[8:9], off
	v_lshl_add_u64 v[8:9], v[230:231], 0, s[16:17]
	s_mov_b32 m0, s52
	s_nop 0
	global_load_lds_dwordx4 v[8:9], off
	v_lshl_add_u64 v[8:9], v[232:233], 0, s[16:17]
	s_mov_b32 m0, s53
	s_nop 0
	global_load_lds_dwordx4 v[8:9], off
	s_waitcnt vmcnt(8)
	s_waitcnt lgkmcnt(0)
	s_barrier
	s_setprio 1
	s_waitcnt lgkmcnt(0)
	v_mfma_f32_16x16x32_bf16 v[66:69], v[160:163], v[194:197], v[66:69]
	v_mfma_f32_16x16x32_bf16 v[66:69], v[164:167], v[198:201], v[66:69]
	v_mfma_f32_16x16x32_bf16 v[62:65], v[174:177], v[198:201], v[62:65]
	v_mfma_f32_16x16x32_bf16 v[62:65], v[168:171], v[194:197], v[62:65]
	v_mfma_f32_16x16x32_bf16 v[46:49], v[168:171], v[202:205], v[46:49]
	v_mfma_f32_16x16x32_bf16 v[46:49], v[174:177], v[206:209], v[46:49]
	v_mfma_f32_16x16x32_bf16 v[50:53], v[164:167], v[206:209], v[50:53]
	v_mfma_f32_16x16x32_bf16 v[50:53], v[160:163], v[202:205], v[50:53]
	v_mfma_f32_16x16x32_bf16 v[34:37], v[160:163], v[210:213], v[34:37]
	v_mfma_f32_16x16x32_bf16 v[34:37], v[164:167], v[214:217], v[34:37]
	v_mfma_f32_16x16x32_bf16 v[30:33], v[174:177], v[214:217], v[30:33]
	v_mfma_f32_16x16x32_bf16 v[30:33], v[168:171], v[210:213], v[30:33]
	v_mfma_f32_16x16x32_bf16 v[14:17], v[168:171], v[218:221], v[14:17]
	v_mfma_f32_16x16x32_bf16 v[14:17], v[174:177], v[222:225], v[14:17]
	v_mfma_f32_16x16x32_bf16 v[18:21], v[164:167], v[222:225], v[18:21]
	v_mfma_f32_16x16x32_bf16 v[18:21], v[160:163], v[218:221], v[18:21]
	s_setprio 0
	s_setprio 1
	v_mfma_f32_16x16x32_bf16 v[58:61], v[178:181], v[194:197], v[58:61]
	v_mfma_f32_16x16x32_bf16 v[54:57], v[186:189], v[194:197], v[54:57]
	v_mfma_f32_16x16x32_bf16 v[42:45], v[178:181], v[202:205], v[42:45]
	v_mfma_f32_16x16x32_bf16 v[38:41], v[186:189], v[202:205], v[38:41]
	v_mfma_f32_16x16x32_bf16 v[26:29], v[178:181], v[210:213], v[26:29]
	v_mfma_f32_16x16x32_bf16 v[22:25], v[186:189], v[210:213], v[22:25]
	v_mfma_f32_16x16x32_bf16 v[8:11], v[178:181], v[218:221], v[10:13]
	v_mfma_f32_16x16x32_bf16 v[4:7], v[186:189], v[218:221], v[4:7]
	v_mfma_f32_16x16x32_bf16 v[58:61], v[182:185], v[198:201], v[58:61]
	v_mfma_f32_16x16x32_bf16 v[54:57], v[190:193], v[198:201], v[54:57]
	v_mfma_f32_16x16x32_bf16 v[42:45], v[182:185], v[206:209], v[42:45]
	v_mfma_f32_16x16x32_bf16 v[38:41], v[190:193], v[206:209], v[38:41]
	v_mfma_f32_16x16x32_bf16 v[26:29], v[182:185], v[214:217], v[26:29]
	v_mfma_f32_16x16x32_bf16 v[22:25], v[190:193], v[214:217], v[22:25]
	v_mfma_f32_16x16x32_bf16 v[10:13], v[182:185], v[222:225], v[8:11]
	v_mfma_f32_16x16x32_bf16 v[6:9], v[190:193], v[222:225], v[4:7]
	s_setprio 0
	s_barrier
	s_add_i32 s62, s62, 2
	s_add_u32 s40, s40, 0x100
	s_addc_u32 s41, s41, 0
	s_cmp_gt_u32 s62, 29
	s_cbranch_scc1 .LBB0_842

; #define PG8_STAGE(bufoff, gbase, voff) do { _Pragma("unroll") for (int _i = 0; _i < 2; ++_i) \
;         __builtin_amdgcn_global_load_lds((const unsigned*)((const char*)(gbase) + (voff)[_i]), (PG8_LAS unsigned*)(lds + (bufoff) + ldsw + _i * 8192), 16, 0, 0); } while (0)
; #define PG8_LDA(dst, b, h) do { _Pragma("unroll") for (int m = 0; m < 4; ++m) _Pragma("unroll") for (int k = 0; k < 2; ++k) dst[m][k] = *(const PG8_LAS bf16x8*)(lds + PG8_SA(b, h) + aoff + m * 2048 + k * 1024); } while (0)
; #define PG8_LDB(dst, b, h) do { _Pragma("unroll") for (int n = 0; n < 2; ++n) _Pragma("unroll") for (int k = 0; k < 2; ++k) dst[n][k] = *(const PG8_LAS bf16x8*)(lds + PG8_SB(b, h) + boff + n * 2048 + k * 1024); } while (0)
; #define PG8_MMA(ai, bj, At, Bt) do { __builtin_amdgcn_s_setprio(1); _Pragma("unroll") for (int m = 0; m < 4; ++m) _Pragma("unroll") for (int n = 0; n < 2; ++n) _Pragma("unroll") for (int k = 0; k < 2; ++k) \
;         acc[ai][bj][m][n] = __builtin_amdgcn_mfma_f32_16x16x32_bf16(Bt[n][k], At[m][k], acc[ai][bj][m][n], 0, 0, 0); __builtin_amdgcn_s_setprio(0); } while (0)
; #define PG8_WAIT_V(n) asm volatile("s_waitcnt vmcnt(" #n ")" ::: "memory")
; #define PG8_WAIT_L(n) asm volatile("s_waitcnt lgkmcnt(" #n ")" ::: "memory")
; #define PG8_BAR __builtin_amdgcn_s_barrier()
; #define PG8_SCHED __builtin_amdgcn_sched_barrier(0)
; template <class Epi, class Sched, bool ALIGN_EPI>
; __device__ __forceinline__ void gemm_phase(PG8_LAS unsigned char* lds, const Gemm g, const Sched& S, const Epi& E) {
;     ...
;             PG8_LDB(B0, 0, 0); PG8_LDB(B1, 0, 1); PG8_SCHED; PG8_LDA(At, 0, 0); PG8_STAGE(PG8_SA(1, 1), a1 + hstepA, voffA);
;             PG8_WAIT_V(8); PG8_WAIT_L(0); PG8_BAR; PG8_MMA(0, 0, At, B0); PG8_MMA(0, 1, At, B1); PG8_BAR; PG8_SCHED;
;             PG8_LDA(At, 0, 1); PG8_STAGE(PG8_SB(0, 0), b2, voffB); PG8_STAGE(PG8_SB(0, 1), b2 + hstepB, voffB); PG8_STAGE(PG8_SA(0, 0), a2, voffA);
;             PG8_WAIT_V(8); PG8_WAIT_L(0); PG8_BAR; PG8_MMA(1, 0, At, B0); PG8_MMA(1, 1, At, B1); PG8_BAR; PG8_SCHED;
; __global__ void __launch_bounds__(NWAVES * 64, 2) hymba_fwd(Args a) {
;     ...
;         pg8::Gemm g{R1, Wgu_t, DM, DM, DM}; pg8::StaticOrder S; S.init(M, 2 * D_FF, G, bx);
;         pg8::EpiSwiGLU E{HID, D_FF, (const float*)(ws + WS_RH)};
;         pg8::gemm_phase<pg8::EpiSwiGLU, pg8::StaticOrder, true>(lds, g, S, E);
.LBB0_901:
	ds_read_b128 v[156:159], v153
	ds_read_b128 v[160:163], v153 offset:1024
	ds_read_b128 v[164:167], v153 offset:2048
	ds_read_b128 v[168:171], v153 offset:3072
	ds_read_b128 v[174:177], v154
	ds_read_b128 v[178:181], v154 offset:1024
	ds_read_b128 v[182:185], v154 offset:2048
	ds_read_b128 v[186:189], v154 offset:3072
	s_add_u32 s2, s28, 0xfff80080
	s_addc_u32 s30, s29, -1
	s_cmp_eq_u32 s49, 28
	s_cselect_b32 s35, s23, s30
	s_cselect_b32 s34, s22, s2
	s_cselect_b32 s31, s25, s21
	s_cselect_b32 s30, s24, s19
	v_lshl_add_u64 v[222:223], s[28:29], 0, v[138:139]
	s_add_i32 m0, s27, 0xc000
	ds_read_b128 v[190:193], v155
	ds_read_b128 v[194:197], v155 offset:1024
	ds_read_b128 v[198:201], v155 offset:2048
	ds_read_b128 v[202:205], v155 offset:3072
	ds_read_b128 v[206:209], v155 offset:4096
	ds_read_b128 v[210:213], v155 offset:5120
	ds_read_b128 v[214:217], v155 offset:6144
	ds_read_b128 v[218:221], v155 offset:7168
	global_load_lds_dwordx4 v[222:223], off
	v_lshl_add_u64 v[222:223], s[28:29], 0, v[140:141]
	s_add_i32 m0, s27, 0xe000
	s_nop 0
	global_load_lds_dwordx4 v[222:223], off
	s_waitcnt vmcnt(8)
	s_waitcnt lgkmcnt(0)
	s_barrier
	s_setprio 1
	s_waitcnt lgkmcnt(0)
	v_mfma_f32_16x16x32_bf16 v[126:129], v[156:159], v[190:193], v[126:129]
	v_mfma_f32_16x16x32_bf16 v[126:129], v[160:163], v[194:197], v[126:129]
	v_mfma_f32_16x16x32_bf16 v[122:125], v[168:171], v[194:197], v[122:125]
	v_mfma_f32_16x16x32_bf16 v[122:125], v[164:167], v[190:193], v[122:125]
	v_mfma_f32_16x16x32_bf16 v[106:109], v[164:167], v[198:201], v[106:109]
	v_mfma_f32_16x16x32_bf16 v[106:109], v[168:171], v[202:205], v[106:109]
	v_mfma_f32_16x16x32_bf16 v[110:113], v[160:163], v[202:205], v[110:113]
	v_mfma_f32_16x16x32_bf16 v[110:113], v[156:159], v[198:201], v[110:113]
	v_mfma_f32_16x16x32_bf16 v[94:97], v[156:159], v[206:209], v[94:97]
	v_mfma_f32_16x16x32_bf16 v[94:97], v[160:163], v[210:213], v[94:97]
	v_mfma_f32_16x16x32_bf16 v[90:93], v[168:171], v[210:213], v[90:93]
	v_mfma_f32_16x16x32_bf16 v[90:93], v[164:167], v[206:209], v[90:93]
	v_mfma_f32_16x16x32_bf16 v[74:77], v[164:167], v[214:217], v[74:77]
	v_mfma_f32_16x16x32_bf16 v[74:77], v[168:171], v[218:221], v[74:77]
	v_mfma_f32_16x16x32_bf16 v[78:81], v[160:163], v[218:221], v[78:81]
	v_mfma_f32_16x16x32_bf16 v[78:81], v[156:159], v[214:217], v[78:81]
	s_setprio 0
	s_setprio 1
	v_mfma_f32_16x16x32_bf16 v[118:121], v[174:177], v[190:193], v[118:121]
	v_mfma_f32_16x16x32_bf16 v[118:121], v[178:181], v[194:197], v[118:121]
	v_mfma_f32_16x16x32_bf16 v[114:117], v[186:189], v[194:197], v[114:117]
	v_mfma_f32_16x16x32_bf16 v[114:117], v[182:185], v[190:193], v[114:117]
	v_mfma_f32_16x16x32_bf16 v[98:101], v[182:185], v[198:201], v[98:101]
	v_mfma_f32_16x16x32_bf16 v[98:101], v[186:189], v[202:205], v[98:101]
	v_mfma_f32_16x16x32_bf16 v[102:105], v[178:181], v[202:205], v[102:105]
	v_mfma_f32_16x16x32_bf16 v[102:105], v[174:177], v[198:201], v[102:105]
	v_mfma_f32_16x16x32_bf16 v[86:89], v[174:177], v[206:209], v[86:89]
	v_mfma_f32_16x16x32_bf16 v[86:89], v[178:181], v[210:213], v[86:89]
	v_mfma_f32_16x16x32_bf16 v[82:85], v[186:189], v[210:213], v[82:85]
	v_mfma_f32_16x16x32_bf16 v[82:85], v[182:185], v[206:209], v[82:85]
	v_mfma_f32_16x16x32_bf16 v[66:69], v[182:185], v[214:217], v[66:69]
	v_mfma_f32_16x16x32_bf16 v[66:69], v[186:189], v[218:221], v[66:69]
	v_mfma_f32_16x16x32_bf16 v[70:73], v[178:181], v[218:221], v[70:73]
	v_mfma_f32_16x16x32_bf16 v[70:73], v[174:177], v[214:217], v[70:73]
	s_setprio 0
	s_barrier
	s_add_i32 s2, s5, s3
	v_lshl_add_u64 v[222:223], s[30:31], 0, v[134:135]
	s_mov_b32 m0, s2
	ds_read_b128 v[190:193], v155 offset:16384
	ds_read_b128 v[194:197], v155 offset:17408
	ds_read_b128 v[198:201], v155 offset:18432
	ds_read_b128 v[202:205], v155 offset:19456
	ds_read_b128 v[206:209], v155 offset:20480
	ds_read_b128 v[210:213], v155 offset:21504
	ds_read_b128 v[214:217], v155 offset:22528
	ds_read_b128 v[218:221], v155 offset:23552
	global_load_lds_dwordx4 v[222:223], off
	s_add_i32 m0, s2, 0x2000
	s_add_u32 s50, s30, 0x80000
	v_lshl_add_u64 v[224:225], s[30:31], 0, v[130:131]
	s_addc_u32 s51, s31, 0
	s_add_i32 s2, s45, s3
	global_load_lds_dwordx4 v[224:225], off
	v_lshl_add_u64 v[226:227], s[50:51], 0, v[134:135]
	s_mov_b32 m0, s2
	v_lshl_add_u64 v[228:229], s[34:35], 0, v[132:133]
	global_load_lds_dwordx4 v[226:227], off
	v_lshl_add_u64 v[226:227], s[50:51], 0, v[130:131]
	s_add_i32 m0, s2, 0x2000
	s_nop 0
	global_load_lds_dwordx4 v[226:227], off
	v_lshl_add_u64 v[226:227], s[34:35], 0, v[136:137]
	s_mov_b32 m0, s27
	s_nop 0
	global_load_lds_dwordx4 v[226:227], off
	s_mov_b32 m0, s39
	s_nop 0
	global_load_lds_dwordx4 v[228:229], off
	s_waitcnt vmcnt(8)
	s_waitcnt lgkmcnt(0)
	s_barrier
; #define PG8_STAGE(bufoff, gbase, voff) do { _Pragma("unroll") for (int _i = 0; _i < 2; ++_i) \
;         __builtin_amdgcn_global_load_lds((const unsigned*)((const char*)(gbase) + (voff)[_i]), (PG8_LAS unsigned*)(lds + (bufoff) + ldsw + _i * 8192), 16, 0, 0); } while (0)
; #define PG8_LDA(dst, b, h) do { _Pragma("unroll") for (int m = 0; m < 4; ++m) _Pragma("unroll") for (int k = 0; k < 2; ++k) dst[m][k] = *(const PG8_LAS bf16x8*)(lds + PG8_SA(b, h) + aoff + m * 2048 + k * 1024); } while (0)
; #define PG8_LDB(dst, b, h) do { _Pragma("unroll") for (int n = 0; n < 2; ++n) _Pragma("unroll") for (int k = 0; k < 2; ++k) dst[n][k] = *(const PG8_LAS bf16x8*)(lds + PG8_SB(b, h) + boff + n * 2048 + k * 1024); } while (0)
; #define PG8_MMA(ai, bj, At, Bt) do { __builtin_amdgcn_s_setprio(1); _Pragma("unroll") for (int m = 0; m < 4; ++m) _Pragma("unroll") for (int n = 0; n < 2; ++n) _Pragma("unroll") for (int k = 0; k < 2; ++k) \
;         acc[ai][bj][m][n] = __builtin_amdgcn_mfma_f32_16x16x32_bf16(Bt[n][k], At[m][k], acc[ai][bj][m][n], 0, 0, 0); __builtin_amdgcn_s_setprio(0); } while (0)
; #define PG8_WAIT_V(n) asm volatile("s_waitcnt vmcnt(" #n ")" ::: "memory")
; #define PG8_WAIT_L(n) asm volatile("s_waitcnt lgkmcnt(" #n ")" ::: "memory")
; #define PG8_BAR __builtin_amdgcn_s_barrier()
; #define PG8_SCHED __builtin_amdgcn_sched_barrier(0)
; template <class Epi, class Sched, bool ALIGN_EPI>
; __device__ __forceinline__ void gemm_phase(PG8_LAS unsigned char* lds, const Gemm g, const Sched& S, const Epi& E) {
;     ...
;             PG8_WAIT_V(8); PG8_WAIT_L(0); PG8_BAR; PG8_MMA(1, 0, At, B0); PG8_MMA(1, 1, At, B1); PG8_BAR; PG8_SCHED;
;             PG8_LDB(B0, 1, 0); PG8_LDB(B1, 1, 1); PG8_SCHED; PG8_LDA(At, 1, 0); PG8_STAGE(PG8_SA(0, 1), a2 + hstepA, voffA);
;             PG8_WAIT_V(8); PG8_WAIT_L(0); PG8_BAR; PG8_MMA(0, 0, At, B0); PG8_MMA(0, 1, At, B1); PG8_BAR; PG8_SCHED;
	s_setprio 1
	s_waitcnt lgkmcnt(0)
	v_mfma_f32_16x16x32_bf16 v[62:65], v[156:159], v[190:193], v[62:65]
	v_mfma_f32_16x16x32_bf16 v[62:65], v[160:163], v[194:197], v[62:65]
	v_mfma_f32_16x16x32_bf16 v[58:61], v[168:171], v[194:197], v[58:61]
	v_mfma_f32_16x16x32_bf16 v[58:61], v[164:167], v[190:193], v[58:61]
	v_mfma_f32_16x16x32_bf16 v[42:45], v[164:167], v[198:201], v[42:45]
	v_mfma_f32_16x16x32_bf16 v[42:45], v[168:171], v[202:205], v[42:45]
	v_mfma_f32_16x16x32_bf16 v[46:49], v[160:163], v[202:205], v[46:49]
	v_mfma_f32_16x16x32_bf16 v[46:49], v[156:159], v[198:201], v[46:49]
	v_mfma_f32_16x16x32_bf16 v[30:33], v[156:159], v[206:209], v[30:33]
	v_mfma_f32_16x16x32_bf16 v[30:33], v[160:163], v[210:213], v[30:33]
	v_mfma_f32_16x16x32_bf16 v[26:29], v[168:171], v[210:213], v[26:29]
	v_mfma_f32_16x16x32_bf16 v[26:29], v[164:167], v[206:209], v[26:29]
	v_mfma_f32_16x16x32_bf16 v[10:13], v[164:167], v[214:217], v[10:13]
	v_mfma_f32_16x16x32_bf16 v[10:13], v[168:171], v[218:221], v[10:13]
	v_mfma_f32_16x16x32_bf16 v[14:17], v[160:163], v[218:221], v[14:17]
	v_mfma_f32_16x16x32_bf16 v[14:17], v[156:159], v[214:217], v[14:17]
	s_setprio 0
	s_setprio 1
	v_mfma_f32_16x16x32_bf16 v[54:57], v[174:177], v[190:193], v[54:57]
	v_mfma_f32_16x16x32_bf16 v[54:57], v[178:181], v[194:197], v[54:57]
	v_mfma_f32_16x16x32_bf16 v[50:53], v[186:189], v[194:197], v[50:53]
	v_mfma_f32_16x16x32_bf16 v[50:53], v[182:185], v[190:193], v[50:53]
	v_mfma_f32_16x16x32_bf16 v[34:37], v[182:185], v[198:201], v[34:37]
	v_mfma_f32_16x16x32_bf16 v[34:37], v[186:189], v[202:205], v[34:37]
	v_mfma_f32_16x16x32_bf16 v[38:41], v[178:181], v[202:205], v[38:41]
	v_mfma_f32_16x16x32_bf16 v[38:41], v[174:177], v[198:201], v[38:41]
	v_mfma_f32_16x16x32_bf16 v[22:25], v[174:177], v[206:209], v[22:25]
	v_mfma_f32_16x16x32_bf16 v[22:25], v[178:181], v[210:213], v[22:25]
	v_mfma_f32_16x16x32_bf16 v[18:21], v[186:189], v[210:213], v[18:21]
	v_mfma_f32_16x16x32_bf16 v[18:21], v[182:185], v[206:209], v[18:21]
	v_mfma_f32_16x16x32_bf16 v[2:5], v[182:185], v[214:217], v[2:5]
	v_mfma_f32_16x16x32_bf16 v[2:5], v[186:189], v[218:221], v[2:5]
	v_mfma_f32_16x16x32_bf16 v[6:9], v[178:181], v[218:221], v[6:9]
	v_mfma_f32_16x16x32_bf16 v[6:9], v[174:177], v[214:217], v[6:9]
	s_setprio 0
	s_barrier
	s_add_i32 s2, 0, 0x18000
	s_add_i32 s50, 0, 0x1c000
	v_add_u32_e32 v168, s2, v146
	v_add_u32_e32 v173, s50, v146
	ds_read_b128 v[156:159], v168
	ds_read_b128 v[160:163], v168 offset:1024
	ds_read_b128 v[164:167], v168 offset:2048
	ds_read_b128 v[168:171], v168 offset:3072
	ds_read_b128 v[174:177], v173
	ds_read_b128 v[178:181], v173 offset:1024
	ds_read_b128 v[182:185], v173 offset:2048
	ds_read_b128 v[186:189], v173 offset:3072
	s_add_u32 s34, s34, 0x80000
	s_addc_u32 s35, s35, 0
	s_mov_b32 m0, s40
	v_lshl_add_u64 v[230:231], s[34:35], 0, v[136:137]
	ds_read_b128 v[190:193], v155 offset:32768
	ds_read_b128 v[194:197], v155 offset:33792
	ds_read_b128 v[198:201], v155 offset:34816
	ds_read_b128 v[202:205], v155 offset:35840
	ds_read_b128 v[206:209], v155 offset:36864
	ds_read_b128 v[210:213], v155 offset:37888
	ds_read_b128 v[214:217], v155 offset:38912
	ds_read_b128 v[218:221], v155 offset:39936
	global_load_lds_dwordx4 v[230:231], off
	v_lshl_add_u64 v[230:231], s[34:35], 0, v[132:133]
	s_mov_b32 m0, s41
	s_nop 0
	global_load_lds_dwordx4 v[230:231], off
	s_waitcnt vmcnt(8)
	s_waitcnt lgkmcnt(0)
	s_barrier
	s_setprio 1
	s_waitcnt lgkmcnt(0)
	v_mfma_f32_16x16x32_bf16 v[126:129], v[156:159], v[190:193], v[126:129]
	v_mfma_f32_16x16x32_bf16 v[126:129], v[160:163], v[194:197], v[126:129]
	v_mfma_f32_16x16x32_bf16 v[122:125], v[168:171], v[194:197], v[122:125]
	v_mfma_f32_16x16x32_bf16 v[122:125], v[164:167], v[190:193], v[122:125]
	v_mfma_f32_16x16x32_bf16 v[106:109], v[164:167], v[198:201], v[106:109]
	v_mfma_f32_16x16x32_bf16 v[106:109], v[168:171], v[202:205], v[106:109]
	v_mfma_f32_16x16x32_bf16 v[110:113], v[160:163], v[202:205], v[110:113]
	v_mfma_f32_16x16x32_bf16 v[110:113], v[156:159], v[198:201], v[110:113]
	v_mfma_f32_16x16x32_bf16 v[94:97], v[156:159], v[206:209], v[94:97]
	v_mfma_f32_16x16x32_bf16 v[94:97], v[160:163], v[210:213], v[94:97]
	v_mfma_f32_16x16x32_bf16 v[90:93], v[168:171], v[210:213], v[90:93]
	v_mfma_f32_16x16x32_bf16 v[90:93], v[164:167], v[206:209], v[90:93]
	v_mfma_f32_16x16x32_bf16 v[74:77], v[164:167], v[214:217], v[74:77]
	v_mfma_f32_16x16x32_bf16 v[74:77], v[168:171], v[218:221], v[74:77]
	v_mfma_f32_16x16x32_bf16 v[78:81], v[160:163], v[218:221], v[78:81]
	v_mfma_f32_16x16x32_bf16 v[78:81], v[156:159], v[214:217], v[78:81]
	s_setprio 0
	s_setprio 1
	v_mfma_f32_16x16x32_bf16 v[118:121], v[174:177], v[190:193], v[118:121]
	v_mfma_f32_16x16x32_bf16 v[118:121], v[178:181], v[194:197], v[118:121]
	v_mfma_f32_16x16x32_bf16 v[114:117], v[186:189], v[194:197], v[114:117]
	v_mfma_f32_16x16x32_bf16 v[114:117], v[182:185], v[190:193], v[114:117]
	v_mfma_f32_16x16x32_bf16 v[98:101], v[182:185], v[198:201], v[98:101]
	v_mfma_f32_16x16x32_bf16 v[98:101], v[186:189], v[202:205], v[98:101]
	v_mfma_f32_16x16x32_bf16 v[102:105], v[178:181], v[202:205], v[102:105]
	v_mfma_f32_16x16x32_bf16 v[102:105], v[174:177], v[198:201], v[102:105]
	v_mfma_f32_16x16x32_bf16 v[86:89], v[174:177], v[206:209], v[86:89]
	v_mfma_f32_16x16x32_bf16 v[86:89], v[178:181], v[210:213], v[86:89]
	v_mfma_f32_16x16x32_bf16 v[82:85], v[186:189], v[210:213], v[82:85]
	v_mfma_f32_16x16x32_bf16 v[82:85], v[182:185], v[206:209], v[82:85]
	v_mfma_f32_16x16x32_bf16 v[66:69], v[182:185], v[214:217], v[66:69]
	v_mfma_f32_16x16x32_bf16 v[66:69], v[186:189], v[218:221], v[66:69]
	v_mfma_f32_16x16x32_bf16 v[70:73], v[178:181], v[218:221], v[70:73]
	v_mfma_f32_16x16x32_bf16 v[70:73], v[174:177], v[214:217], v[70:73]
	s_setprio 0
	s_barrier
; #define PG8_STAGE(bufoff, gbase, voff) do { _Pragma("unroll") for (int _i = 0; _i < 2; ++_i) \
;         __builtin_amdgcn_global_load_lds((const unsigned*)((const char*)(gbase) + (voff)[_i]), (PG8_LAS unsigned*)(lds + (bufoff) + ldsw + _i * 8192), 16, 0, 0); } while (0)
; #define PG8_LDA(dst, b, h) do { _Pragma("unroll") for (int m = 0; m < 4; ++m) _Pragma("unroll") for (int k = 0; k < 2; ++k) dst[m][k] = *(const PG8_LAS bf16x8*)(lds + PG8_SA(b, h) + aoff + m * 2048 + k * 1024); } while (0)
; #define PG8_MMA(ai, bj, At, Bt) do { __builtin_amdgcn_s_setprio(1); _Pragma("unroll") for (int m = 0; m < 4; ++m) _Pragma("unroll") for (int n = 0; n < 2; ++n) _Pragma("unroll") for (int k = 0; k < 2; ++k) \
;         acc[ai][bj][m][n] = __builtin_amdgcn_mfma_f32_16x16x32_bf16(Bt[n][k], At[m][k], acc[ai][bj][m][n], 0, 0, 0); __builtin_amdgcn_s_setprio(0); } while (0)
; #define PG8_WAIT_V(n) asm volatile("s_waitcnt vmcnt(" #n ")" ::: "memory")
; #define PG8_WAIT_L(n) asm volatile("s_waitcnt lgkmcnt(" #n ")" ::: "memory")
; #define PG8_BAR __builtin_amdgcn_s_barrier()
; #define PG8_SCHED __builtin_amdgcn_sched_barrier(0)
; template <class Epi, class Sched, bool ALIGN_EPI>
; __device__ __forceinline__ void gemm_phase(PG8_LAS unsigned char* lds, const Gemm g, const Sched& S, const Epi& E) {
;     ...
;             PG8_LDA(At, 1, 1); PG8_STAGE(PG8_SB(1, 0), b3, voffB); PG8_STAGE(PG8_SB(1, 1), b3 + hstepB, voffB); PG8_STAGE(PG8_SA(1, 0), a3, voffA);
;             PG8_WAIT_V(8); PG8_WAIT_L(0); PG8_BAR; PG8_MMA(1, 0, At, B0); PG8_MMA(1, 1, At, B1); PG8_BAR; PG8_SCHED;
;         }
	s_add_i32 s2, s2, s3
	v_lshl_add_u64 v[222:223], v[222:223], 0, s[14:15]
	s_mov_b32 m0, s2
	ds_read_b128 v[190:193], v155 offset:49152
	ds_read_b128 v[194:197], v155 offset:50176
	ds_read_b128 v[198:201], v155 offset:51200
	ds_read_b128 v[202:205], v155 offset:52224
	ds_read_b128 v[206:209], v155 offset:53248
	ds_read_b128 v[210:213], v155 offset:54272
	ds_read_b128 v[214:217], v155 offset:55296
	ds_read_b128 v[218:221], v155 offset:56320
	global_load_lds_dwordx4 v[222:223], off
	s_add_i32 m0, s2, 0x2000
	s_add_u32 s30, s30, 0x80080
	v_lshl_add_u64 v[222:223], v[224:225], 0, s[14:15]
	s_addc_u32 s31, s31, 0
	s_add_i32 s2, s50, s3
	global_load_lds_dwordx4 v[222:223], off
	v_lshl_add_u64 v[222:223], s[30:31], 0, v[134:135]
	s_mov_b32 m0, s2
	s_nop 0
	global_load_lds_dwordx4 v[222:223], off
	v_lshl_add_u64 v[222:223], s[30:31], 0, v[130:131]
	s_add_i32 m0, s2, 0x2000
	s_nop 0
	global_load_lds_dwordx4 v[222:223], off
	v_lshl_add_u64 v[222:223], v[226:227], 0, s[14:15]
	s_mov_b32 m0, s43
	s_nop 0
	global_load_lds_dwordx4 v[222:223], off
	v_lshl_add_u64 v[222:223], v[228:229], 0, s[14:15]
	s_mov_b32 m0, s44
	s_nop 0
	global_load_lds_dwordx4 v[222:223], off
	s_waitcnt vmcnt(8)
	s_waitcnt lgkmcnt(0)
	s_barrier
	s_setprio 1
	s_waitcnt lgkmcnt(0)
	v_mfma_f32_16x16x32_bf16 v[62:65], v[156:159], v[190:193], v[62:65]
	v_mfma_f32_16x16x32_bf16 v[62:65], v[160:163], v[194:197], v[62:65]
	v_mfma_f32_16x16x32_bf16 v[58:61], v[168:171], v[194:197], v[58:61]
	v_mfma_f32_16x16x32_bf16 v[58:61], v[164:167], v[190:193], v[58:61]
	v_mfma_f32_16x16x32_bf16 v[42:45], v[164:167], v[198:201], v[42:45]
	v_mfma_f32_16x16x32_bf16 v[42:45], v[168:171], v[202:205], v[42:45]
	v_mfma_f32_16x16x32_bf16 v[46:49], v[160:163], v[202:205], v[46:49]
	v_mfma_f32_16x16x32_bf16 v[46:49], v[156:159], v[198:201], v[46:49]
	v_mfma_f32_16x16x32_bf16 v[30:33], v[156:159], v[206:209], v[30:33]
	v_mfma_f32_16x16x32_bf16 v[30:33], v[160:163], v[210:213], v[30:33]
	v_mfma_f32_16x16x32_bf16 v[26:29], v[168:171], v[210:213], v[26:29]
	v_mfma_f32_16x16x32_bf16 v[26:29], v[164:167], v[206:209], v[26:29]
	v_mfma_f32_16x16x32_bf16 v[10:13], v[164:167], v[214:217], v[10:13]
	v_mfma_f32_16x16x32_bf16 v[10:13], v[168:171], v[218:221], v[10:13]
	v_mfma_f32_16x16x32_bf16 v[14:17], v[160:163], v[218:221], v[14:17]
	v_mfma_f32_16x16x32_bf16 v[14:17], v[156:159], v[214:217], v[14:17]
	s_setprio 0
	s_setprio 1
	v_mfma_f32_16x16x32_bf16 v[54:57], v[174:177], v[190:193], v[54:57]
	v_mfma_f32_16x16x32_bf16 v[54:57], v[178:181], v[194:197], v[54:57]
	v_mfma_f32_16x16x32_bf16 v[50:53], v[186:189], v[194:197], v[50:53]
	v_mfma_f32_16x16x32_bf16 v[50:53], v[182:185], v[190:193], v[50:53]
	v_mfma_f32_16x16x32_bf16 v[34:37], v[182:185], v[198:201], v[34:37]
	v_mfma_f32_16x16x32_bf16 v[34:37], v[186:189], v[202:205], v[34:37]
	v_mfma_f32_16x16x32_bf16 v[38:41], v[178:181], v[202:205], v[38:41]
	v_mfma_f32_16x16x32_bf16 v[38:41], v[174:177], v[198:201], v[38:41]
	v_mfma_f32_16x16x32_bf16 v[22:25], v[174:177], v[206:209], v[22:25]
	v_mfma_f32_16x16x32_bf16 v[22:25], v[178:181], v[210:213], v[22:25]
	v_mfma_f32_16x16x32_bf16 v[18:21], v[186:189], v[210:213], v[18:21]
	v_mfma_f32_16x16x32_bf16 v[18:21], v[182:185], v[206:209], v[18:21]
	v_mfma_f32_16x16x32_bf16 v[2:5], v[182:185], v[214:217], v[2:5]
	v_mfma_f32_16x16x32_bf16 v[2:5], v[186:189], v[218:221], v[2:5]
	v_mfma_f32_16x16x32_bf16 v[6:9], v[178:181], v[218:221], v[6:9]
	v_mfma_f32_16x16x32_bf16 v[6:9], v[174:177], v[214:217], v[6:9]
	s_setprio 0
	s_barrier
	s_add_i32 s49, s49, 2
	s_add_u32 s28, s28, 0x100
	s_addc_u32 s29, s29, 0
	s_add_u32 s19, s19, 0x100
	s_addc_u32 s21, s21, 0
	s_cmp_gt_u32 s49, 29
	s_cbranch_scc0 .LBB0_901
	s_and_b64 vcc, exec, s[16:17]
	s_cbranch_vccz .LBB0_904
	s_barrier

; #define PG8_STAGE(bufoff, gbase, voff) do { _Pragma("unroll") for (int _i = 0; _i < 2; ++_i) \
;         __builtin_amdgcn_global_load_lds((const unsigned*)((const char*)(gbase) + (voff)[_i]), (PG8_LAS unsigned*)(lds + (bufoff) + ldsw + _i * 8192), 16, 0, 0); } while (0)
; #define PG8_LDA(dst, b, h) do { _Pragma("unroll") for (int m = 0; m < 4; ++m) _Pragma("unroll") for (int k = 0; k < 2; ++k) dst[m][k] = *(const PG8_LAS bf16x8*)(lds + PG8_SA(b, h) + aoff + m * 2048 + k * 1024); } while (0)
; #define PG8_LDB(dst, b, h) do { _Pragma("unroll") for (int n = 0; n < 2; ++n) _Pragma("unroll") for (int k = 0; k < 2; ++k) dst[n][k] = *(const PG8_LAS bf16x8*)(lds + PG8_SB(b, h) + boff + n * 2048 + k * 1024); } while (0)
; #define PG8_MMA(ai, bj, At, Bt) do { __builtin_amdgcn_s_setprio(1); _Pragma("unroll") for (int m = 0; m < 4; ++m) _Pragma("unroll") for (int n = 0; n < 2; ++n) _Pragma("unroll") for (int k = 0; k < 2; ++k) \
;         acc[ai][bj][m][n] = __builtin_amdgcn_mfma_f32_16x16x32_bf16(Bt[n][k], At[m][k], acc[ai][bj][m][n], 0, 0, 0); __builtin_amdgcn_s_setprio(0); } while (0)
; #define PG8_WAIT_V(n) asm volatile("s_waitcnt vmcnt(" #n ")" ::: "memory")
; #define PG8_WAIT_L(n) asm volatile("s_waitcnt lgkmcnt(" #n ")" ::: "memory")
; #define PG8_BAR __builtin_amdgcn_s_barrier()
; #define PG8_SCHED __builtin_amdgcn_sched_barrier(0)
; template <class Epi, class Sched, bool ALIGN_EPI>
; __device__ __forceinline__ void gemm_phase(PG8_LAS unsigned char* lds, const Gemm g, const Sched& S, const Epi& E) {
;     ...
;             PG8_LDB(B0, 0, 0); PG8_LDB(B1, 0, 1); PG8_SCHED; PG8_LDA(At, 0, 0); PG8_STAGE(PG8_SA(1, 1), a1 + hstepA, voffA);
;             PG8_WAIT_V(8); PG8_WAIT_L(0); PG8_BAR; PG8_MMA(0, 0, At, B0); PG8_MMA(0, 1, At, B1); PG8_BAR; PG8_SCHED;
;             PG8_LDA(At, 0, 1); PG8_STAGE(PG8_SB(0, 0), b2, voffB); PG8_STAGE(PG8_SB(0, 1), b2 + hstepB, voffB); PG8_STAGE(PG8_SA(0, 0), a2, voffA);
;             PG8_WAIT_V(8); PG8_WAIT_L(0); PG8_BAR; PG8_MMA(1, 0, At, B0); PG8_MMA(1, 1, At, B1); PG8_BAR; PG8_SCHED;
; __global__ void __launch_bounds__(NWAVES * 64, 2) hymba_fwd(Args a) {
;     ...
;     {
;         PHASE_IDS();
;         pg8::Gemm g{HID, Wd_t, D_FF, D_FF, D_FF}; pg8::StaticOrder S; S.init(M, DM, G, bx);
;         pg8::EpiBf16P E{MIX, DM};
;         pg8::gemm_phase<pg8::EpiBf16P, pg8::StaticOrder, true>(lds, g, S, E);
;     }
.LBB0_948:
	ds_read_b128 v[158:161], v155
	ds_read_b128 v[162:165], v155 offset:1024
	ds_read_b128 v[166:169], v155 offset:2048
	ds_read_b128 v[174:177], v155 offset:3072
	ds_read_b128 v[178:181], v156
	ds_read_b128 v[182:185], v156 offset:1024
	ds_read_b128 v[186:189], v156 offset:2048
	ds_read_b128 v[190:193], v156 offset:3072
	s_add_u32 s28, s26, 0x100
	s_addc_u32 s29, s27, 0
	s_cmpk_eq_i32 s59, 0x54
	s_cselect_b32 s35, s7, s29
	s_cselect_b32 s34, s6, s28
	s_cselect_b32 s31, s25, s58
	s_cselect_b32 s30, s24, s57
	v_lshl_add_u64 v[146:147], s[26:27], 0, v[138:139]
	s_add_i32 m0, s37, 0xc000
	ds_read_b128 v[194:197], v157
	ds_read_b128 v[198:201], v157 offset:1024
	ds_read_b128 v[202:205], v157 offset:2048
	ds_read_b128 v[206:209], v157 offset:3072
	ds_read_b128 v[210:213], v157 offset:4096
	ds_read_b128 v[214:217], v157 offset:5120
	ds_read_b128 v[218:221], v157 offset:6144
	ds_read_b128 v[222:225], v157 offset:7168
	global_load_lds_dwordx4 v[146:147], off
	v_lshl_add_u64 v[146:147], s[26:27], 0, v[140:141]
	s_add_i32 m0, s37, 0xe000
	s_nop 0
	global_load_lds_dwordx4 v[146:147], off
	s_waitcnt vmcnt(8)
	s_waitcnt lgkmcnt(0)
	s_barrier
	s_setprio 1
	s_waitcnt lgkmcnt(0)
	v_mfma_f32_16x16x32_bf16 v[126:129], v[158:161], v[194:197], v[126:129]
	v_mfma_f32_16x16x32_bf16 v[126:129], v[162:165], v[198:201], v[126:129]
	v_mfma_f32_16x16x32_bf16 v[122:125], v[174:177], v[198:201], v[122:125]
	v_mfma_f32_16x16x32_bf16 v[122:125], v[166:169], v[194:197], v[122:125]
	v_mfma_f32_16x16x32_bf16 v[110:113], v[166:169], v[202:205], v[110:113]
	v_mfma_f32_16x16x32_bf16 v[110:113], v[174:177], v[206:209], v[110:113]
	v_mfma_f32_16x16x32_bf16 v[118:121], v[162:165], v[206:209], v[118:121]
	v_mfma_f32_16x16x32_bf16 v[118:121], v[158:161], v[202:205], v[118:121]
	v_mfma_f32_16x16x32_bf16 v[102:105], v[158:161], v[210:213], v[102:105]
	v_mfma_f32_16x16x32_bf16 v[102:105], v[162:165], v[214:217], v[102:105]
	v_mfma_f32_16x16x32_bf16 v[94:97], v[174:177], v[214:217], v[94:97]
	v_mfma_f32_16x16x32_bf16 v[94:97], v[166:169], v[210:213], v[94:97]
	v_mfma_f32_16x16x32_bf16 v[78:81], v[166:169], v[218:221], v[78:81]
	v_mfma_f32_16x16x32_bf16 v[78:81], v[174:177], v[222:225], v[78:81]
	v_mfma_f32_16x16x32_bf16 v[86:89], v[162:165], v[222:225], v[86:89]
	v_mfma_f32_16x16x32_bf16 v[86:89], v[158:161], v[218:221], v[86:89]
	s_setprio 0
	s_setprio 1
	v_mfma_f32_16x16x32_bf16 v[114:117], v[178:181], v[194:197], v[114:117]
	v_mfma_f32_16x16x32_bf16 v[114:117], v[182:185], v[198:201], v[114:117]
	v_mfma_f32_16x16x32_bf16 v[106:109], v[190:193], v[198:201], v[106:109]
	v_mfma_f32_16x16x32_bf16 v[106:109], v[186:189], v[194:197], v[106:109]
	v_mfma_f32_16x16x32_bf16 v[90:93], v[186:189], v[202:205], v[90:93]
	v_mfma_f32_16x16x32_bf16 v[90:93], v[190:193], v[206:209], v[90:93]
	v_mfma_f32_16x16x32_bf16 v[98:101], v[182:185], v[206:209], v[98:101]
	v_mfma_f32_16x16x32_bf16 v[98:101], v[178:181], v[202:205], v[98:101]
	v_mfma_f32_16x16x32_bf16 v[82:85], v[178:181], v[210:213], v[82:85]
	v_mfma_f32_16x16x32_bf16 v[82:85], v[182:185], v[214:217], v[82:85]
	v_mfma_f32_16x16x32_bf16 v[74:77], v[190:193], v[214:217], v[74:77]
	v_mfma_f32_16x16x32_bf16 v[74:77], v[186:189], v[210:213], v[74:77]
	v_mfma_f32_16x16x32_bf16 v[66:69], v[186:189], v[218:221], v[66:69]
	v_mfma_f32_16x16x32_bf16 v[66:69], v[190:193], v[222:225], v[66:69]
	v_mfma_f32_16x16x32_bf16 v[70:73], v[182:185], v[222:225], v[70:73]
	v_mfma_f32_16x16x32_bf16 v[70:73], v[178:181], v[218:221], v[70:73]
	s_setprio 0
	s_barrier
	s_add_i32 s2, s47, s36
	v_lshl_add_u64 v[146:147], s[30:31], 0, v[132:133]
	s_mov_b32 m0, s2
	ds_read_b128 v[194:197], v157 offset:16384
	ds_read_b128 v[198:201], v157 offset:17408
	ds_read_b128 v[202:205], v157 offset:18432
	ds_read_b128 v[206:209], v157 offset:19456
	ds_read_b128 v[210:213], v157 offset:20480
	ds_read_b128 v[214:217], v157 offset:21504
	ds_read_b128 v[218:221], v157 offset:22528
	ds_read_b128 v[222:225], v157 offset:23552
	global_load_lds_dwordx4 v[146:147], off
	s_add_i32 m0, s2, 0x2000
	s_add_u32 s26, s30, 0x160000
	v_lshl_add_u64 v[170:171], s[30:31], 0, v[136:137]
	s_addc_u32 s27, s31, 0
	s_add_i32 s2, s48, s36
	global_load_lds_dwordx4 v[170:171], off
	v_lshl_add_u64 v[226:227], s[26:27], 0, v[132:133]
	s_mov_b32 m0, s2
	v_lshl_add_u64 v[228:229], s[34:35], 0, v[134:135]
	global_load_lds_dwordx4 v[226:227], off
	v_lshl_add_u64 v[226:227], s[26:27], 0, v[136:137]
	s_add_i32 m0, s2, 0x2000
	s_nop 0
	global_load_lds_dwordx4 v[226:227], off
	v_lshl_add_u64 v[226:227], s[34:35], 0, v[130:131]
	s_mov_b32 m0, s37
	s_nop 0
	global_load_lds_dwordx4 v[226:227], off
	s_mov_b32 m0, s39
	s_nop 0
	global_load_lds_dwordx4 v[228:229], off
	s_waitcnt vmcnt(8)
	s_waitcnt lgkmcnt(0)
	s_barrier
; #define PG8_STAGE(bufoff, gbase, voff) do { _Pragma("unroll") for (int _i = 0; _i < 2; ++_i) \
;         __builtin_amdgcn_global_load_lds((const unsigned*)((const char*)(gbase) + (voff)[_i]), (PG8_LAS unsigned*)(lds + (bufoff) + ldsw + _i * 8192), 16, 0, 0); } while (0)
; #define PG8_LDA(dst, b, h) do { _Pragma("unroll") for (int m = 0; m < 4; ++m) _Pragma("unroll") for (int k = 0; k < 2; ++k) dst[m][k] = *(const PG8_LAS bf16x8*)(lds + PG8_SA(b, h) + aoff + m * 2048 + k * 1024); } while (0)
; #define PG8_LDB(dst, b, h) do { _Pragma("unroll") for (int n = 0; n < 2; ++n) _Pragma("unroll") for (int k = 0; k < 2; ++k) dst[n][k] = *(const PG8_LAS bf16x8*)(lds + PG8_SB(b, h) + boff + n * 2048 + k * 1024); } while (0)
; #define PG8_MMA(ai, bj, At, Bt) do { __builtin_amdgcn_s_setprio(1); _Pragma("unroll") for (int m = 0; m < 4; ++m) _Pragma("unroll") for (int n = 0; n < 2; ++n) _Pragma("unroll") for (int k = 0; k < 2; ++k) \
;         acc[ai][bj][m][n] = __builtin_amdgcn_mfma_f32_16x16x32_bf16(Bt[n][k], At[m][k], acc[ai][bj][m][n], 0, 0, 0); __builtin_amdgcn_s_setprio(0); } while (0)
; #define PG8_WAIT_V(n) asm volatile("s_waitcnt vmcnt(" #n ")" ::: "memory")
; #define PG8_WAIT_L(n) asm volatile("s_waitcnt lgkmcnt(" #n ")" ::: "memory")
; #define PG8_BAR __builtin_amdgcn_s_barrier()
; #define PG8_SCHED __builtin_amdgcn_sched_barrier(0)
; template <class Epi, class Sched, bool ALIGN_EPI>
; __device__ __forceinline__ void gemm_phase(PG8_LAS unsigned char* lds, const Gemm g, const Sched& S, const Epi& E) {
;     ...
;             PG8_WAIT_V(8); PG8_WAIT_L(0); PG8_BAR; PG8_MMA(1, 0, At, B0); PG8_MMA(1, 1, At, B1); PG8_BAR; PG8_SCHED;
;             PG8_LDB(B0, 1, 0); PG8_LDB(B1, 1, 1); PG8_SCHED; PG8_LDA(At, 1, 0); PG8_STAGE(PG8_SA(0, 1), a2 + hstepA, voffA);
;             PG8_WAIT_V(8); PG8_WAIT_L(0); PG8_BAR; PG8_MMA(0, 0, At, B0); PG8_MMA(0, 1, At, B1); PG8_BAR; PG8_SCHED;
	s_setprio 1
	s_waitcnt lgkmcnt(0)
	v_mfma_f32_16x16x32_bf16 v[62:65], v[158:161], v[194:197], v[62:65]
	v_mfma_f32_16x16x32_bf16 v[62:65], v[162:165], v[198:201], v[62:65]
	v_mfma_f32_16x16x32_bf16 v[58:61], v[174:177], v[198:201], v[58:61]
	v_mfma_f32_16x16x32_bf16 v[58:61], v[166:169], v[194:197], v[58:61]
	v_mfma_f32_16x16x32_bf16 v[46:49], v[166:169], v[202:205], v[46:49]
	v_mfma_f32_16x16x32_bf16 v[46:49], v[174:177], v[206:209], v[46:49]
	v_mfma_f32_16x16x32_bf16 v[54:57], v[162:165], v[206:209], v[54:57]
	v_mfma_f32_16x16x32_bf16 v[54:57], v[158:161], v[202:205], v[54:57]
	v_mfma_f32_16x16x32_bf16 v[38:41], v[158:161], v[210:213], v[38:41]
	v_mfma_f32_16x16x32_bf16 v[38:41], v[162:165], v[214:217], v[38:41]
	v_mfma_f32_16x16x32_bf16 v[30:33], v[174:177], v[214:217], v[30:33]
	v_mfma_f32_16x16x32_bf16 v[30:33], v[166:169], v[210:213], v[30:33]
	v_mfma_f32_16x16x32_bf16 v[14:17], v[166:169], v[218:221], v[14:17]
	v_mfma_f32_16x16x32_bf16 v[14:17], v[174:177], v[222:225], v[14:17]
	v_mfma_f32_16x16x32_bf16 v[22:25], v[162:165], v[222:225], v[22:25]
	v_mfma_f32_16x16x32_bf16 v[22:25], v[158:161], v[218:221], v[22:25]
	s_setprio 0
	s_setprio 1
	v_mfma_f32_16x16x32_bf16 v[50:53], v[178:181], v[194:197], v[50:53]
	v_mfma_f32_16x16x32_bf16 v[50:53], v[182:185], v[198:201], v[50:53]
	v_mfma_f32_16x16x32_bf16 v[42:45], v[190:193], v[198:201], v[42:45]
	v_mfma_f32_16x16x32_bf16 v[42:45], v[186:189], v[194:197], v[42:45]
	v_mfma_f32_16x16x32_bf16 v[26:29], v[186:189], v[202:205], v[26:29]
	v_mfma_f32_16x16x32_bf16 v[26:29], v[190:193], v[206:209], v[26:29]
	v_mfma_f32_16x16x32_bf16 v[34:37], v[182:185], v[206:209], v[34:37]
	v_mfma_f32_16x16x32_bf16 v[34:37], v[178:181], v[202:205], v[34:37]
	v_mfma_f32_16x16x32_bf16 v[18:21], v[178:181], v[210:213], v[18:21]
	v_mfma_f32_16x16x32_bf16 v[18:21], v[182:185], v[214:217], v[18:21]
	v_mfma_f32_16x16x32_bf16 v[10:13], v[190:193], v[214:217], v[10:13]
	v_mfma_f32_16x16x32_bf16 v[10:13], v[186:189], v[210:213], v[10:13]
	v_mfma_f32_16x16x32_bf16 v[2:5], v[186:189], v[218:221], v[2:5]
	v_mfma_f32_16x16x32_bf16 v[2:5], v[190:193], v[222:225], v[2:5]
	v_mfma_f32_16x16x32_bf16 v[6:9], v[182:185], v[222:225], v[6:9]
	v_mfma_f32_16x16x32_bf16 v[6:9], v[178:181], v[218:221], v[6:9]
	s_setprio 0
	s_barrier
	s_add_i32 s2, 0, 0x18000
	v_add_u32_e32 v173, s2, v153
	s_add_i32 s60, 0, 0x1c000
	ds_read_b128 v[158:161], v173
	ds_read_b128 v[162:165], v173 offset:1024
	ds_read_b128 v[166:169], v173 offset:2048
	ds_read_b128 v[174:177], v173 offset:3072
	v_add_u32_e32 v173, s60, v153
	ds_read_b128 v[178:181], v173
	ds_read_b128 v[182:185], v173 offset:1024
	ds_read_b128 v[186:189], v173 offset:2048
	ds_read_b128 v[190:193], v173 offset:3072
	s_add_u32 s26, s34, 0x160000
	s_addc_u32 s27, s35, 0
	s_mov_b32 m0, s40
	v_lshl_add_u64 v[230:231], s[26:27], 0, v[130:131]
	ds_read_b128 v[194:197], v157 offset:32768
	ds_read_b128 v[198:201], v157 offset:33792
	ds_read_b128 v[202:205], v157 offset:34816
	ds_read_b128 v[206:209], v157 offset:35840
	ds_read_b128 v[210:213], v157 offset:36864
	ds_read_b128 v[214:217], v157 offset:37888
	ds_read_b128 v[218:221], v157 offset:38912
	ds_read_b128 v[222:225], v157 offset:39936
	global_load_lds_dwordx4 v[230:231], off
	v_lshl_add_u64 v[230:231], s[26:27], 0, v[134:135]
	s_mov_b32 m0, s41
	s_nop 0
	global_load_lds_dwordx4 v[230:231], off
	s_waitcnt vmcnt(8)
	s_waitcnt lgkmcnt(0)
	s_barrier
	s_setprio 1
	s_waitcnt lgkmcnt(0)
	v_mfma_f32_16x16x32_bf16 v[126:129], v[158:161], v[194:197], v[126:129]
	v_mfma_f32_16x16x32_bf16 v[126:129], v[162:165], v[198:201], v[126:129]
	v_mfma_f32_16x16x32_bf16 v[122:125], v[174:177], v[198:201], v[122:125]
	v_mfma_f32_16x16x32_bf16 v[122:125], v[166:169], v[194:197], v[122:125]
	v_mfma_f32_16x16x32_bf16 v[110:113], v[166:169], v[202:205], v[110:113]
	v_mfma_f32_16x16x32_bf16 v[110:113], v[174:177], v[206:209], v[110:113]
	v_mfma_f32_16x16x32_bf16 v[118:121], v[162:165], v[206:209], v[118:121]
	v_mfma_f32_16x16x32_bf16 v[118:121], v[158:161], v[202:205], v[118:121]
	v_mfma_f32_16x16x32_bf16 v[102:105], v[158:161], v[210:213], v[102:105]
	v_mfma_f32_16x16x32_bf16 v[102:105], v[162:165], v[214:217], v[102:105]
	v_mfma_f32_16x16x32_bf16 v[94:97], v[174:177], v[214:217], v[94:97]
	v_mfma_f32_16x16x32_bf16 v[94:97], v[166:169], v[210:213], v[94:97]
	v_mfma_f32_16x16x32_bf16 v[78:81], v[166:169], v[218:221], v[78:81]
	v_mfma_f32_16x16x32_bf16 v[78:81], v[174:177], v[222:225], v[78:81]
	v_mfma_f32_16x16x32_bf16 v[86:89], v[162:165], v[222:225], v[86:89]
	v_mfma_f32_16x16x32_bf16 v[86:89], v[158:161], v[218:221], v[86:89]
	s_setprio 0
	s_setprio 1
	v_mfma_f32_16x16x32_bf16 v[114:117], v[178:181], v[194:197], v[114:117]
	v_mfma_f32_16x16x32_bf16 v[114:117], v[182:185], v[198:201], v[114:117]
	v_mfma_f32_16x16x32_bf16 v[106:109], v[190:193], v[198:201], v[106:109]
	v_mfma_f32_16x16x32_bf16 v[106:109], v[186:189], v[194:197], v[106:109]
	v_mfma_f32_16x16x32_bf16 v[90:93], v[186:189], v[202:205], v[90:93]
	v_mfma_f32_16x16x32_bf16 v[90:93], v[190:193], v[206:209], v[90:93]
	v_mfma_f32_16x16x32_bf16 v[98:101], v[182:185], v[206:209], v[98:101]
	v_mfma_f32_16x16x32_bf16 v[98:101], v[178:181], v[202:205], v[98:101]
	v_mfma_f32_16x16x32_bf16 v[82:85], v[178:181], v[210:213], v[82:85]
	v_mfma_f32_16x16x32_bf16 v[82:85], v[182:185], v[214:217], v[82:85]
	v_mfma_f32_16x16x32_bf16 v[74:77], v[190:193], v[214:217], v[74:77]
	v_mfma_f32_16x16x32_bf16 v[74:77], v[186:189], v[210:213], v[74:77]
	v_mfma_f32_16x16x32_bf16 v[66:69], v[186:189], v[218:221], v[66:69]
	v_mfma_f32_16x16x32_bf16 v[66:69], v[190:193], v[222:225], v[66:69]
	v_mfma_f32_16x16x32_bf16 v[70:73], v[182:185], v[222:225], v[70:73]
	v_mfma_f32_16x16x32_bf16 v[70:73], v[178:181], v[218:221], v[70:73]
	s_setprio 0
	s_barrier
; #define PG8_STAGE(bufoff, gbase, voff) do { _Pragma("unroll") for (int _i = 0; _i < 2; ++_i) \
;         __builtin_amdgcn_global_load_lds((const unsigned*)((const char*)(gbase) + (voff)[_i]), (PG8_LAS unsigned*)(lds + (bufoff) + ldsw + _i * 8192), 16, 0, 0); } while (0)
; #define PG8_LDA(dst, b, h) do { _Pragma("unroll") for (int m = 0; m < 4; ++m) _Pragma("unroll") for (int k = 0; k < 2; ++k) dst[m][k] = *(const PG8_LAS bf16x8*)(lds + PG8_SA(b, h) + aoff + m * 2048 + k * 1024); } while (0)
; #define PG8_MMA(ai, bj, At, Bt) do { __builtin_amdgcn_s_setprio(1); _Pragma("unroll") for (int m = 0; m < 4; ++m) _Pragma("unroll") for (int n = 0; n < 2; ++n) _Pragma("unroll") for (int k = 0; k < 2; ++k) \
;         acc[ai][bj][m][n] = __builtin_amdgcn_mfma_f32_16x16x32_bf16(Bt[n][k], At[m][k], acc[ai][bj][m][n], 0, 0, 0); __builtin_amdgcn_s_setprio(0); } while (0)
; #define PG8_WAIT_V(n) asm volatile("s_waitcnt vmcnt(" #n ")" ::: "memory")
; #define PG8_WAIT_L(n) asm volatile("s_waitcnt lgkmcnt(" #n ")" ::: "memory")
; #define PG8_BAR __builtin_amdgcn_s_barrier()
; #define PG8_SCHED __builtin_amdgcn_sched_barrier(0)
; template <class Epi, class Sched, bool ALIGN_EPI>
; __device__ __forceinline__ void gemm_phase(PG8_LAS unsigned char* lds, const Gemm g, const Sched& S, const Epi& E) {
;     ...
;             PG8_LDA(At, 1, 1); PG8_STAGE(PG8_SB(1, 0), b3, voffB); PG8_STAGE(PG8_SB(1, 1), b3 + hstepB, voffB); PG8_STAGE(PG8_SA(1, 0), a3, voffA);
;             PG8_WAIT_V(8); PG8_WAIT_L(0); PG8_BAR; PG8_MMA(1, 0, At, B0); PG8_MMA(1, 1, At, B1); PG8_BAR; PG8_SCHED;
;         }
	s_add_i32 s2, s2, s36
	v_lshl_add_u64 v[146:147], v[146:147], 0, s[12:13]
	s_mov_b32 m0, s2
	ds_read_b128 v[194:197], v157 offset:49152
	ds_read_b128 v[198:201], v157 offset:50176
	ds_read_b128 v[202:205], v157 offset:51200
	ds_read_b128 v[206:209], v157 offset:52224
	ds_read_b128 v[210:213], v157 offset:53248
	ds_read_b128 v[214:217], v157 offset:54272
	ds_read_b128 v[218:221], v157 offset:55296
	ds_read_b128 v[222:225], v157 offset:56320
	global_load_lds_dwordx4 v[146:147], off
	s_add_i32 m0, s2, 0x2000
	s_add_u32 s26, s30, 0x160080
	v_lshl_add_u64 v[146:147], v[170:171], 0, s[12:13]
	s_addc_u32 s27, s31, 0
	s_add_i32 s2, s60, s36
	global_load_lds_dwordx4 v[146:147], off
	v_lshl_add_u64 v[146:147], s[26:27], 0, v[132:133]
	s_mov_b32 m0, s2
	s_nop 0
	global_load_lds_dwordx4 v[146:147], off
	v_lshl_add_u64 v[146:147], s[26:27], 0, v[136:137]
	s_add_i32 m0, s2, 0x2000
	s_nop 0
	global_load_lds_dwordx4 v[146:147], off
	v_lshl_add_u64 v[146:147], v[226:227], 0, s[12:13]
	s_mov_b32 m0, s43
	s_nop 0
	global_load_lds_dwordx4 v[146:147], off
	v_lshl_add_u64 v[146:147], v[228:229], 0, s[12:13]
	s_mov_b32 m0, s44
	s_nop 0
	global_load_lds_dwordx4 v[146:147], off
	s_waitcnt vmcnt(8)
	s_waitcnt lgkmcnt(0)
	s_barrier
	s_setprio 1
	s_waitcnt lgkmcnt(0)
	v_mfma_f32_16x16x32_bf16 v[62:65], v[158:161], v[194:197], v[62:65]
	v_mfma_f32_16x16x32_bf16 v[62:65], v[162:165], v[198:201], v[62:65]
	v_mfma_f32_16x16x32_bf16 v[58:61], v[174:177], v[198:201], v[58:61]
	v_mfma_f32_16x16x32_bf16 v[58:61], v[166:169], v[194:197], v[58:61]
	v_mfma_f32_16x16x32_bf16 v[46:49], v[166:169], v[202:205], v[46:49]
	v_mfma_f32_16x16x32_bf16 v[46:49], v[174:177], v[206:209], v[46:49]
	v_mfma_f32_16x16x32_bf16 v[54:57], v[162:165], v[206:209], v[54:57]
	v_mfma_f32_16x16x32_bf16 v[54:57], v[158:161], v[202:205], v[54:57]
	v_mfma_f32_16x16x32_bf16 v[38:41], v[158:161], v[210:213], v[38:41]
	v_mfma_f32_16x16x32_bf16 v[38:41], v[162:165], v[214:217], v[38:41]
	v_mfma_f32_16x16x32_bf16 v[30:33], v[174:177], v[214:217], v[30:33]
	v_mfma_f32_16x16x32_bf16 v[30:33], v[166:169], v[210:213], v[30:33]
	v_mfma_f32_16x16x32_bf16 v[14:17], v[166:169], v[218:221], v[14:17]
	v_mfma_f32_16x16x32_bf16 v[14:17], v[174:177], v[222:225], v[14:17]
	v_mfma_f32_16x16x32_bf16 v[22:25], v[162:165], v[222:225], v[22:25]
	v_mfma_f32_16x16x32_bf16 v[22:25], v[158:161], v[218:221], v[22:25]
	s_setprio 0
	s_setprio 1
	v_mfma_f32_16x16x32_bf16 v[50:53], v[178:181], v[194:197], v[50:53]
	v_mfma_f32_16x16x32_bf16 v[50:53], v[182:185], v[198:201], v[50:53]
	v_mfma_f32_16x16x32_bf16 v[42:45], v[190:193], v[198:201], v[42:45]
	v_mfma_f32_16x16x32_bf16 v[42:45], v[186:189], v[194:197], v[42:45]
	v_mfma_f32_16x16x32_bf16 v[26:29], v[186:189], v[202:205], v[26:29]
	v_mfma_f32_16x16x32_bf16 v[26:29], v[190:193], v[206:209], v[26:29]
	v_mfma_f32_16x16x32_bf16 v[34:37], v[182:185], v[206:209], v[34:37]
	v_mfma_f32_16x16x32_bf16 v[34:37], v[178:181], v[202:205], v[34:37]
	v_mfma_f32_16x16x32_bf16 v[18:21], v[178:181], v[210:213], v[18:21]
	v_mfma_f32_16x16x32_bf16 v[18:21], v[182:185], v[214:217], v[18:21]
	v_mfma_f32_16x16x32_bf16 v[10:13], v[190:193], v[214:217], v[10:13]
	v_mfma_f32_16x16x32_bf16 v[10:13], v[186:189], v[210:213], v[10:13]
	v_mfma_f32_16x16x32_bf16 v[2:5], v[186:189], v[218:221], v[2:5]
	v_mfma_f32_16x16x32_bf16 v[2:5], v[190:193], v[222:225], v[2:5]
	v_mfma_f32_16x16x32_bf16 v[6:9], v[182:185], v[222:225], v[6:9]
	v_mfma_f32_16x16x32_bf16 v[6:9], v[178:181], v[218:221], v[6:9]
	s_setprio 0
	s_barrier
	s_add_i32 s59, s59, 2
	s_add_u32 s57, s57, 0x100
	s_addc_u32 s58, s58, 0
	s_cmpk_gt_u32 s59, 0x55
	s_mov_b64 s[26:27], s[28:29]
	s_cbranch_scc0 .LBB0_948
	s_and_b64 vcc, exec, s[14:15]
	s_cbranch_vccz .LBB0_951
	s_barrier
